# rwkv_pre 32x32 forward-substitution: row t+1 of L prefetched from LDS during step t into dead VGPR pools (all copies), counted lgkmcnt
# speedup vs baseline: 1.0052x; 1.0035x over previous
; #define LAS __attribute__((address_space(3)))
; __device__ __forceinline__ unsigned f2bf(float f) { return (unsigned)__builtin_bit_cast(unsigned short, (__bf16)f); }
; __device__ __forceinline__ void rwkv_pre(LAS unsigned char* lds, const MixBufs& B, bf16_t* rq, int L, int u, int unext, RwRaw& R) {
;     ...
;     if (w < 2) {
;         const int ob = w * 32, j = lane & 31;
;         float T[32];
;         int zv = 0; asm volatile("" : "+v"(zv));
;         const LAS float* Lfz = Lf + zv + ob * 68 + ob;
; #pragma unroll
;         for (int t = 0; t < 32; ++t) {
;             float a0 = (t == j) ? 1.f : 0.f, a1 = 0.f;
; #pragma unroll
;             for (int s4 = 0; s4 < (t + 3) / 4; ++s4) {
;                 const f32x4 l = *(const LAS f32x4*)(Lfz + t * 68 + s4 * 4);
; #pragma unroll
;                 for (int e2 = 0; e2 < 4; ++e2) { const int s_ = s4 * 4 + e2; if (s_ < t) { if (e2 & 1) a1 += l[e2] * T[s_]; else a0 += l[e2] * T[s_]; } }
;             }
;             T[t] = a0 + a1;
;             if (lane < 32) {
;                 Tm[(ob + t) * RL + ob + j] = (bf16_t)f2bf(T[t]);
;                 if (w == 0) T11T[j * 40 + t] = (bf16_t)f2bf(T[t]);
;             }
;         }
.LBB0_483:
	s_or_b64 exec, exec, s[0:1]
	ds_read_b128 v[70:73], v37 offset:544
	v_cmp_eq_u32_e64 s[0:1], 2, v38
	s_waitcnt lgkmcnt(0)
	ds_read_b128 v[174:177], v37 offset:816
	v_fma_f32 v41, v36, v71, 0
	v_cndmask_b32_e64 v40, 0, 1.0, s[0:1]
	v_fmac_f32_e32 v40, v39, v70
	v_add_f32_e32 v41, v41, v40
	s_and_saveexec_b64 s[0:1], s[42:43]
	s_cbranch_execz .LBB0_486
	s_movk_i32 s4, 0x1200
	v_cvt_pk_bf16_f32 v40, v41, s0
	v_mad_u64_u32 v[70:71], s[6:7], v45, s4, v[0:1]
	ds_write_b16 v70, v40 offset:288
	s_and_b64 exec, exec, vcc
	s_add_i32 s5, 0, 0x18c00
	v_add_u32_e32 v50, s5, v35
	ds_write_b16 v50, v40 offset:4
.LBB0_486:
	s_or_b64 exec, exec, s[0:1]
	v_cmp_eq_u32_e64 s[0:1], 3, v38
	s_waitcnt lgkmcnt(1)
	ds_read_b128 v[132:135], v37 offset:1088
	v_fma_f32 v50, v36, v175, 0
	v_cndmask_b32_e64 v40, 0, 1.0, s[0:1]
	v_fmac_f32_e32 v40, v39, v174
	v_fmac_f32_e32 v40, v41, v176
	v_add_f32_e32 v40, v50, v40
	s_and_saveexec_b64 s[0:1], s[42:43]
	s_cbranch_execz .LBB0_489
	s_movk_i32 s4, 0x1200
	v_cvt_pk_bf16_f32 v50, v40, s0
	v_mad_u64_u32 v[70:71], s[6:7], v45, s4, v[0:1]
	ds_write_b16 v70, v50 offset:432
	s_and_b64 exec, exec, vcc
	s_add_i32 s5, 0, 0x18c00
	v_add_u32_e32 v69, s5, v35
	ds_write_b16 v69, v50 offset:6
.LBB0_489:
	s_or_b64 exec, exec, s[0:1]
	v_cmp_eq_u32_e64 s[0:1], 4, v38
	s_waitcnt lgkmcnt(1)
	ds_read_b128 v[174:177], v37 offset:1360
	ds_read_b128 v[178:181], v37 offset:1376
	v_fma_f32 v69, v36, v133, 0
	v_cndmask_b32_e64 v50, 0, 1.0, s[0:1]
	v_fmac_f32_e32 v50, v39, v132
	v_fmac_f32_e32 v50, v41, v134
	v_fmac_f32_e32 v69, v40, v135
	v_add_f32_e32 v69, v69, v50
	s_and_saveexec_b64 s[0:1], s[42:43]
	s_cbranch_execz .LBB0_492
	s_movk_i32 s4, 0x1200
	v_cvt_pk_bf16_f32 v50, v69, s0
	v_mad_u64_u32 v[70:71], s[6:7], v45, s4, v[0:1]
	ds_write_b16 v70, v50 offset:576
	s_and_b64 exec, exec, vcc
	s_add_i32 s5, 0, 0x18c00
	v_add_u32_e32 v70, s5, v35
	ds_write_b16 v70, v50 offset:8
.LBB0_492:
	s_or_b64 exec, exec, s[0:1]
	v_cmp_eq_u32_e64 s[0:1], 5, v38
	s_nop 1
	v_cndmask_b32_e64 v50, 0, 1.0, s[0:1]
	s_waitcnt lgkmcnt(1)
	ds_read_b128 v[132:135], v37 offset:1632
	ds_read_b128 v[136:139], v37 offset:1648
	v_fmac_f32_e32 v50, v39, v174
	v_fma_f32 v70, v36, v175, 0
	v_fmac_f32_e32 v50, v41, v176
	v_fmac_f32_e32 v70, v40, v177
	v_fmac_f32_e32 v50, v69, v178
	v_add_f32_e32 v50, v70, v50
	s_and_saveexec_b64 s[0:1], s[42:43]
	s_cbranch_execz .LBB0_495
	s_movk_i32 s4, 0x1200
	v_cvt_pk_bf16_f32 v70, v50, s0
	v_mad_u64_u32 v[72:73], s[6:7], v45, s4, v[0:1]
	ds_write_b16 v72, v70 offset:720
	s_and_b64 exec, exec, vcc
	s_add_i32 s5, 0, 0x18c00
	v_add_u32_e32 v71, s5, v35
	ds_write_b16 v71, v70 offset:10
.LBB0_495:
	s_or_b64 exec, exec, s[0:1]
	v_cmp_eq_u32_e64 s[0:1], 6, v38
	s_waitcnt lgkmcnt(1)
	ds_read_b128 v[174:177], v37 offset:1904
	ds_read_b128 v[178:181], v37 offset:1920
	s_nop 0
	v_cndmask_b32_e64 v76, 0, 1.0, s[0:1]
	v_fmac_f32_e32 v76, v39, v132
	v_fma_f32 v70, v36, v133, 0
	v_fmac_f32_e32 v76, v41, v134
	v_fmac_f32_e32 v70, v40, v135
	v_fmac_f32_e32 v76, v69, v136
	v_fmac_f32_e32 v70, v50, v137
	v_add_f32_e32 v70, v70, v76
	s_and_saveexec_b64 s[0:1], s[42:43]
	s_cbranch_execz .LBB0_498
	s_movk_i32 s4, 0x1200
	v_cvt_pk_bf16_f32 v71, v70, s0
	v_mad_u64_u32 v[72:73], s[6:7], v45, s4, v[0:1]
	ds_write_b16 v72, v71 offset:864
	s_and_b64 exec, exec, vcc
	s_add_i32 s5, 0, 0x18c00
	v_add_u32_e32 v72, s5, v35
	ds_write_b16 v72, v71 offset:12
.LBB0_498:
	s_or_b64 exec, exec, s[0:1]
	v_cmp_eq_u32_e64 s[0:1], 7, v38
	s_nop 1
	v_cndmask_b32_e64 v71, 0, 1.0, s[0:1]
	s_waitcnt lgkmcnt(1)
	ds_read_b128 v[132:135], v37 offset:2176
	ds_read_b128 v[136:139], v37 offset:2192
	v_fmac_f32_e32 v71, v39, v174
	v_fma_f32 v72, v36, v175, 0
	v_fmac_f32_e32 v71, v41, v176
	v_fmac_f32_e32 v72, v40, v177
	v_fmac_f32_e32 v71, v69, v178
	v_fmac_f32_e32 v72, v50, v179
	v_fmac_f32_e32 v71, v70, v180
	v_add_f32_e32 v71, v72, v71
	s_and_saveexec_b64 s[0:1], s[42:43]
	s_cbranch_execz .LBB0_501
	s_movk_i32 s4, 0x1200
	v_cvt_pk_bf16_f32 v72, v71, s0
	v_mad_u64_u32 v[74:75], s[6:7], v45, s4, v[0:1]
	ds_write_b16 v74, v72 offset:1008
	s_and_b64 exec, exec, vcc
	s_add_i32 s5, 0, 0x18c00
	v_add_u32_e32 v73, s5, v35
	ds_write_b16 v73, v72 offset:14
.LBB0_501:
	s_or_b64 exec, exec, s[0:1]
	v_cmp_eq_u32_e64 s[0:1], 8, v38
	s_nop 1
	v_cndmask_b32_e64 v80, 0, 1.0, s[0:1]
	s_waitcnt lgkmcnt(1)
	ds_read_b128 v[174:177], v37 offset:2448
	ds_read_b128 v[178:181], v37 offset:2464
	ds_read_b128 v[182:185], v37 offset:2480
	v_fmac_f32_e32 v80, v39, v132
	v_fma_f32 v72, v36, v133, 0
	v_fmac_f32_e32 v80, v41, v134
	v_fmac_f32_e32 v72, v40, v135
	v_fmac_f32_e32 v80, v69, v136
	v_fmac_f32_e32 v72, v50, v137
	v_fmac_f32_e32 v80, v70, v138
	v_fmac_f32_e32 v72, v71, v139
	v_add_f32_e32 v72, v72, v80
	s_and_saveexec_b64 s[0:1], s[42:43]
	s_cbranch_execz .LBB0_504
	s_movk_i32 s4, 0x1200
	v_cvt_pk_bf16_f32 v73, v72, s0
	v_mad_u64_u32 v[74:75], s[6:7], v45, s4, v[0:1]
	ds_write_b16 v74, v73 offset:1152
	s_and_b64 exec, exec, vcc
	s_add_i32 s5, 0, 0x18c00
	v_add_u32_e32 v74, s5, v35
	ds_write_b16 v74, v73 offset:16
.LBB0_504:
	s_or_b64 exec, exec, s[0:1]
	v_cmp_eq_u32_e64 s[0:1], 9, v38
	s_nop 1
	v_cndmask_b32_e64 v73, 0, 1.0, s[0:1]
	s_waitcnt lgkmcnt(1)
	ds_read_b128 v[132:135], v37 offset:2720
	ds_read_b128 v[136:139], v37 offset:2736
	ds_read_b128 v[140:143], v37 offset:2752
	v_fmac_f32_e32 v73, v39, v174
	v_fma_f32 v74, v36, v175, 0
	v_fmac_f32_e32 v73, v41, v176
	v_fmac_f32_e32 v74, v40, v177
	v_fmac_f32_e32 v73, v69, v178
	v_fmac_f32_e32 v74, v50, v179
	v_fmac_f32_e32 v73, v70, v180
	v_fmac_f32_e32 v74, v71, v181
	v_fmac_f32_e32 v73, v72, v182
	v_add_f32_e32 v73, v74, v73
	s_and_saveexec_b64 s[0:1], s[42:43]
	s_cbranch_execz .LBB0_507
	s_movk_i32 s4, 0x1200
	v_cvt_pk_bf16_f32 v74, v73, s0
	v_mad_u64_u32 v[76:77], s[6:7], v45, s4, v[0:1]
	ds_write_b16 v76, v74 offset:1296
	s_and_b64 exec, exec, vcc
	s_add_i32 s5, 0, 0x18c00
	v_add_u32_e32 v75, s5, v35
	ds_write_b16 v75, v74 offset:18
; #define LAS __attribute__((address_space(3)))
; __device__ __forceinline__ unsigned f2bf(float f) { return (unsigned)__builtin_bit_cast(unsigned short, (__bf16)f); }
; __device__ __forceinline__ void rwkv_pre(LAS unsigned char* lds, const MixBufs& B, bf16_t* rq, int L, int u, int unext, RwRaw& R) {
;     ...
;     if (w < 2) {
;         const int ob = w * 32, j = lane & 31;
;         float T[32];
;         int zv = 0; asm volatile("" : "+v"(zv));
;         const LAS float* Lfz = Lf + zv + ob * 68 + ob;
; #pragma unroll
;         for (int t = 0; t < 32; ++t) {
;             float a0 = (t == j) ? 1.f : 0.f, a1 = 0.f;
; #pragma unroll
;             for (int s4 = 0; s4 < (t + 3) / 4; ++s4) {
;                 const f32x4 l = *(const LAS f32x4*)(Lfz + t * 68 + s4 * 4);
; #pragma unroll
;                 for (int e2 = 0; e2 < 4; ++e2) { const int s_ = s4 * 4 + e2; if (s_ < t) { if (e2 & 1) a1 += l[e2] * T[s_]; else a0 += l[e2] * T[s_]; } }
;             }
;             T[t] = a0 + a1;
;             if (lane < 32) {
;                 Tm[(ob + t) * RL + ob + j] = (bf16_t)f2bf(T[t]);
;                 if (w == 0) T11T[j * 40 + t] = (bf16_t)f2bf(T[t]);
;             }
;         }
.LBB0_507:
	s_or_b64 exec, exec, s[0:1]
	v_cmp_eq_u32_e64 s[0:1], 10, v38
	s_waitcnt lgkmcnt(1)
	ds_read_b128 v[174:177], v37 offset:2992
	ds_read_b128 v[178:181], v37 offset:3008
	ds_read_b128 v[182:185], v37 offset:3024
	s_nop 0
	v_cndmask_b32_e64 v84, 0, 1.0, s[0:1]
	v_fmac_f32_e32 v84, v39, v132
	v_fma_f32 v74, v36, v133, 0
	v_fmac_f32_e32 v84, v41, v134
	v_fmac_f32_e32 v74, v40, v135
	v_fmac_f32_e32 v84, v69, v136
	v_fmac_f32_e32 v74, v50, v137
	v_fmac_f32_e32 v84, v70, v138
	v_fmac_f32_e32 v74, v71, v139
	v_fmac_f32_e32 v84, v72, v140
	v_fmac_f32_e32 v74, v73, v141
	v_add_f32_e32 v74, v74, v84
	s_and_saveexec_b64 s[0:1], s[42:43]
	s_cbranch_execz .LBB0_510
	s_movk_i32 s4, 0x1200
	v_cvt_pk_bf16_f32 v75, v74, s0
	v_mad_u64_u32 v[76:77], s[6:7], v45, s4, v[0:1]
	ds_write_b16 v76, v75 offset:1440
	s_and_b64 exec, exec, vcc
	s_add_i32 s5, 0, 0x18c00
	v_add_u32_e32 v76, s5, v35
	ds_write_b16 v76, v75 offset:20
.LBB0_510:
	s_or_b64 exec, exec, s[0:1]
	v_cmp_eq_u32_e64 s[0:1], 11, v38
	s_nop 1
	v_cndmask_b32_e64 v75, 0, 1.0, s[0:1]
	s_waitcnt lgkmcnt(1)
	ds_read_b128 v[132:135], v37 offset:3264
	ds_read_b128 v[136:139], v37 offset:3280
	ds_read_b128 v[140:143], v37 offset:3296
	v_fmac_f32_e32 v75, v39, v174
	v_fma_f32 v76, v36, v175, 0
	v_fmac_f32_e32 v75, v41, v176
	v_fmac_f32_e32 v76, v40, v177
	v_fmac_f32_e32 v75, v69, v178
	v_fmac_f32_e32 v76, v50, v179
	v_fmac_f32_e32 v75, v70, v180
	v_fmac_f32_e32 v76, v71, v181
	v_fmac_f32_e32 v75, v72, v182
	v_fmac_f32_e32 v76, v73, v183
	v_fmac_f32_e32 v75, v74, v184
	v_add_f32_e32 v75, v76, v75
	s_and_saveexec_b64 s[0:1], s[42:43]
	s_cbranch_execz .LBB0_513
	s_movk_i32 s4, 0x1200
	v_cvt_pk_bf16_f32 v76, v75, s0
	v_mad_u64_u32 v[78:79], s[6:7], v45, s4, v[0:1]
	ds_write_b16 v78, v76 offset:1584
	s_and_b64 exec, exec, vcc
	s_add_i32 s5, 0, 0x18c00
	v_add_u32_e32 v77, s5, v35
	ds_write_b16 v77, v76 offset:22
.LBB0_513:
	s_or_b64 exec, exec, s[0:1]
	v_cmp_eq_u32_e64 s[0:1], 12, v38
	v_cndmask_b32_e64 v88, 0, 1.0, s[0:1]
	s_waitcnt lgkmcnt(1)
	ds_read_b128 v[174:177], v37 offset:3536
	ds_read_b128 v[178:181], v37 offset:3552
	ds_read_b128 v[182:185], v37 offset:3568
	ds_read_b128 v[186:189], v37 offset:3584
	v_fmac_f32_e32 v88, v39, v132
	v_fma_f32 v76, v36, v133, 0
	v_fmac_f32_e32 v88, v41, v134
	v_fmac_f32_e32 v76, v40, v135
	v_fmac_f32_e32 v88, v69, v136
	v_fmac_f32_e32 v76, v50, v137
	v_fmac_f32_e32 v88, v70, v138
	v_fmac_f32_e32 v76, v71, v139
	v_fmac_f32_e32 v88, v72, v140
	v_fmac_f32_e32 v76, v73, v141
	v_fmac_f32_e32 v88, v74, v142
	v_fmac_f32_e32 v76, v75, v143
	v_add_f32_e32 v76, v76, v88
	s_and_saveexec_b64 s[0:1], s[42:43]
	s_cbranch_execz .LBB0_516
	s_movk_i32 s4, 0x1200
	v_cvt_pk_bf16_f32 v77, v76, s0
	v_mad_u64_u32 v[78:79], s[6:7], v45, s4, v[0:1]
	ds_write_b16 v78, v77 offset:1728
	s_and_b64 exec, exec, vcc
	s_add_i32 s5, 0, 0x18c00
	v_add_u32_e32 v78, s5, v35
	ds_write_b16 v78, v77 offset:24
.LBB0_516:
	s_or_b64 exec, exec, s[0:1]
	v_cmp_eq_u32_e64 s[0:1], 13, v38
	v_cndmask_b32_e64 v77, 0, 1.0, s[0:1]
	s_waitcnt lgkmcnt(1)
	ds_read_b128 v[132:135], v37 offset:3808
	ds_read_b128 v[136:139], v37 offset:3824
	ds_read_b128 v[140:143], v37 offset:3840
	ds_read_b128 v[144:147], v37 offset:3856
	v_fmac_f32_e32 v77, v39, v174
	v_fma_f32 v78, v36, v175, 0
	v_fmac_f32_e32 v77, v41, v176
	v_fmac_f32_e32 v78, v40, v177
	v_fmac_f32_e32 v77, v69, v178
	v_fmac_f32_e32 v78, v50, v179
	v_fmac_f32_e32 v77, v70, v180
	v_fmac_f32_e32 v78, v71, v181
	v_fmac_f32_e32 v77, v72, v182
	v_fmac_f32_e32 v78, v73, v183
	v_fmac_f32_e32 v77, v74, v184
	v_fmac_f32_e32 v78, v75, v185
	v_fmac_f32_e32 v77, v76, v186
	v_add_f32_e32 v77, v78, v77
	s_and_saveexec_b64 s[0:1], s[42:43]
	s_cbranch_execz .LBB0_519
	s_movk_i32 s4, 0x1200
	v_cvt_pk_bf16_f32 v78, v77, s0
	v_mad_u64_u32 v[80:81], s[6:7], v45, s4, v[0:1]
	ds_write_b16 v80, v78 offset:1872
	s_and_b64 exec, exec, vcc
	s_add_i32 s5, 0, 0x18c00
	v_add_u32_e32 v79, s5, v35
	ds_write_b16 v79, v78 offset:26
.LBB0_519:
	s_or_b64 exec, exec, s[0:1]
	v_cmp_eq_u32_e64 s[0:1], 14, v38
	v_cndmask_b32_e64 v94, 0, 1.0, s[0:1]
	s_waitcnt lgkmcnt(1)
	ds_read_b128 v[174:177], v37 offset:4080
	ds_read_b128 v[178:181], v37 offset:4096
	ds_read_b128 v[182:185], v37 offset:4112
	ds_read_b128 v[186:189], v37 offset:4128
	v_fmac_f32_e32 v94, v39, v132
	v_fma_f32 v78, v36, v133, 0
	v_fmac_f32_e32 v94, v41, v134
	v_fmac_f32_e32 v78, v40, v135
	v_fmac_f32_e32 v94, v69, v136
	v_fmac_f32_e32 v78, v50, v137
	v_fmac_f32_e32 v94, v70, v138
	v_fmac_f32_e32 v78, v71, v139
	v_fmac_f32_e32 v94, v72, v140
	v_fmac_f32_e32 v78, v73, v141
	v_fmac_f32_e32 v94, v74, v142
	v_fmac_f32_e32 v78, v75, v143
	v_fmac_f32_e32 v94, v76, v144
	v_fmac_f32_e32 v78, v77, v145
	v_add_f32_e32 v78, v78, v94
	s_and_saveexec_b64 s[0:1], s[42:43]
	s_cbranch_execz .LBB0_522
	s_movk_i32 s4, 0x1200
	v_cvt_pk_bf16_f32 v79, v78, s0
	v_mad_u64_u32 v[80:81], s[6:7], v45, s4, v[0:1]
	ds_write_b16 v80, v79 offset:2016
	s_and_b64 exec, exec, vcc
	s_add_i32 s5, 0, 0x18c00
	v_add_u32_e32 v80, s5, v35
	ds_write_b16 v80, v79 offset:28
.LBB0_522:
	s_or_b64 exec, exec, s[0:1]
	v_cmp_eq_u32_e64 s[0:1], 15, v38
	v_cndmask_b32_e64 v79, 0, 1.0, s[0:1]
	s_waitcnt lgkmcnt(1)
	ds_read_b128 v[132:135], v37 offset:4352
	ds_read_b128 v[136:139], v37 offset:4368
	ds_read_b128 v[140:143], v37 offset:4384
	ds_read_b128 v[144:147], v37 offset:4400
	v_fmac_f32_e32 v79, v39, v174
	v_fma_f32 v80, v36, v175, 0
	v_fmac_f32_e32 v79, v41, v176
	v_fmac_f32_e32 v80, v40, v177
	v_fmac_f32_e32 v79, v69, v178
	v_fmac_f32_e32 v80, v50, v179
	v_fmac_f32_e32 v79, v70, v180
	v_fmac_f32_e32 v80, v71, v181
	v_fmac_f32_e32 v79, v72, v182
	v_fmac_f32_e32 v80, v73, v183
	v_fmac_f32_e32 v79, v74, v184
	v_fmac_f32_e32 v80, v75, v185
	v_fmac_f32_e32 v79, v76, v186
	v_fmac_f32_e32 v80, v77, v187
	v_fmac_f32_e32 v79, v78, v188
	v_add_f32_e32 v79, v80, v79
	s_and_saveexec_b64 s[0:1], s[42:43]
	s_cbranch_execz .LBB0_525
	s_movk_i32 s4, 0x1200
	v_cvt_pk_bf16_f32 v80, v79, s0
	v_mad_u64_u32 v[82:83], s[6:7], v45, s4, v[0:1]
	ds_write_b16 v82, v80 offset:2160
	s_and_b64 exec, exec, vcc
	s_add_i32 s5, 0, 0x18c00
	v_add_u32_e32 v81, s5, v35
	ds_write_b16 v81, v80 offset:30
; #define LAS __attribute__((address_space(3)))
; __device__ __forceinline__ unsigned f2bf(float f) { return (unsigned)__builtin_bit_cast(unsigned short, (__bf16)f); }
; __device__ __forceinline__ void rwkv_pre(LAS unsigned char* lds, const MixBufs& B, bf16_t* rq, int L, int u, int unext, RwRaw& R) {
;     ...
;     if (w < 2) {
;         const int ob = w * 32, j = lane & 31;
;         float T[32];
;         int zv = 0; asm volatile("" : "+v"(zv));
;         const LAS float* Lfz = Lf + zv + ob * 68 + ob;
; #pragma unroll
;         for (int t = 0; t < 32; ++t) {
;             float a0 = (t == j) ? 1.f : 0.f, a1 = 0.f;
; #pragma unroll
;             for (int s4 = 0; s4 < (t + 3) / 4; ++s4) {
;                 const f32x4 l = *(const LAS f32x4*)(Lfz + t * 68 + s4 * 4);
; #pragma unroll
;                 for (int e2 = 0; e2 < 4; ++e2) { const int s_ = s4 * 4 + e2; if (s_ < t) { if (e2 & 1) a1 += l[e2] * T[s_]; else a0 += l[e2] * T[s_]; } }
;             }
;             T[t] = a0 + a1;
;             if (lane < 32) {
;                 Tm[(ob + t) * RL + ob + j] = (bf16_t)f2bf(T[t]);
;                 if (w == 0) T11T[j * 40 + t] = (bf16_t)f2bf(T[t]);
;             }
;         }
.LBB0_525:
	s_or_b64 exec, exec, s[0:1]
	v_cmp_eq_u32_e64 s[0:1], 16, v38
	v_cndmask_b32_e64 v96, 0, 1.0, s[0:1]
	s_waitcnt lgkmcnt(1)
	ds_read_b128 v[174:177], v37 offset:4624
	ds_read_b128 v[178:181], v37 offset:4640
	ds_read_b128 v[182:185], v37 offset:4656
	ds_read_b128 v[186:189], v37 offset:4672
	ds_read_b128 v[190:193], v37 offset:4688
	v_fmac_f32_e32 v96, v39, v132
	v_fma_f32 v80, v36, v133, 0
	v_fmac_f32_e32 v96, v41, v134
	v_fmac_f32_e32 v80, v40, v135
	v_fmac_f32_e32 v96, v69, v136
	v_fmac_f32_e32 v80, v50, v137
	v_fmac_f32_e32 v96, v70, v138
	v_fmac_f32_e32 v80, v71, v139
	v_fmac_f32_e32 v96, v72, v140
	v_fmac_f32_e32 v80, v73, v141
	v_fmac_f32_e32 v96, v74, v142
	v_fmac_f32_e32 v80, v75, v143
	v_fmac_f32_e32 v96, v76, v144
	v_fmac_f32_e32 v80, v77, v145
	v_fmac_f32_e32 v96, v78, v146
	v_fmac_f32_e32 v80, v79, v147
	v_add_f32_e32 v80, v80, v96
	s_and_saveexec_b64 s[0:1], s[42:43]
	s_cbranch_execz .LBB0_528
	s_movk_i32 s4, 0x1200
	v_cvt_pk_bf16_f32 v81, v80, s0
	v_mad_u64_u32 v[82:83], s[6:7], v45, s4, v[0:1]
	ds_write_b16 v82, v81 offset:2304
	s_and_b64 exec, exec, vcc
	s_add_i32 s5, 0, 0x18c00
	v_add_u32_e32 v82, s5, v35
	ds_write_b16 v82, v81 offset:32
.LBB0_528:
	s_or_b64 exec, exec, s[0:1]
	v_cmp_eq_u32_e64 s[0:1], 17, v38
	v_cndmask_b32_e64 v81, 0, 1.0, s[0:1]
	s_waitcnt lgkmcnt(1)
	ds_read_b128 v[132:135], v37 offset:4896
	ds_read_b128 v[136:139], v37 offset:4912
	ds_read_b128 v[140:143], v37 offset:4928
	ds_read_b128 v[144:147], v37 offset:4944
	ds_read_b128 v[148:151], v37 offset:4960
	v_fmac_f32_e32 v81, v39, v174
	v_fma_f32 v98, v36, v175, 0
	v_fmac_f32_e32 v81, v41, v176
	v_fmac_f32_e32 v98, v40, v177
	v_fmac_f32_e32 v81, v69, v178
	v_fmac_f32_e32 v98, v50, v179
	v_fmac_f32_e32 v81, v70, v180
	v_fmac_f32_e32 v98, v71, v181
	v_fmac_f32_e32 v81, v72, v182
	v_fmac_f32_e32 v98, v73, v183
	v_fmac_f32_e32 v81, v74, v184
	v_fmac_f32_e32 v98, v75, v185
	v_fmac_f32_e32 v81, v76, v186
	v_fmac_f32_e32 v98, v77, v187
	v_fmac_f32_e32 v81, v78, v188
	v_fmac_f32_e32 v98, v79, v189
	v_fmac_f32_e32 v81, v80, v190
	v_add_f32_e32 v81, v98, v81
	s_and_saveexec_b64 s[0:1], s[42:43]
	s_cbranch_execz .LBB0_531
	s_movk_i32 s4, 0x1200
	v_cvt_pk_bf16_f32 v82, v81, s0
	v_mad_u64_u32 v[84:85], s[6:7], v45, s4, v[0:1]
	ds_write_b16 v84, v82 offset:2448
	s_and_b64 exec, exec, vcc
	s_add_i32 s5, 0, 0x18c00
	v_add_u32_e32 v83, s5, v35
	ds_write_b16 v83, v82 offset:34
.LBB0_531:
	s_or_b64 exec, exec, s[0:1]
	v_cmp_eq_u32_e64 s[0:1], 18, v38
	v_cndmask_b32_e64 v98, 0, 1.0, s[0:1]
	s_waitcnt lgkmcnt(1)
	ds_read_b128 v[174:177], v37 offset:5168
	ds_read_b128 v[178:181], v37 offset:5184
	ds_read_b128 v[182:185], v37 offset:5200
	ds_read_b128 v[186:189], v37 offset:5216
	ds_read_b128 v[190:193], v37 offset:5232
	v_fmac_f32_e32 v98, v39, v132
	v_fma_f32 v99, v36, v133, 0
	v_fmac_f32_e32 v98, v41, v134
	v_fmac_f32_e32 v99, v40, v135
	v_fmac_f32_e32 v98, v69, v136
	v_fmac_f32_e32 v99, v50, v137
	v_fmac_f32_e32 v98, v70, v138
	v_fmac_f32_e32 v99, v71, v139
	v_fmac_f32_e32 v98, v72, v140
	v_fmac_f32_e32 v99, v73, v141
	v_fmac_f32_e32 v98, v74, v142
	v_fmac_f32_e32 v99, v75, v143
	v_fmac_f32_e32 v98, v76, v144
	v_fmac_f32_e32 v99, v77, v145
	v_fmac_f32_e32 v98, v78, v146
	v_fmac_f32_e32 v99, v79, v147
	v_fmac_f32_e32 v98, v80, v148
	v_fmac_f32_e32 v99, v81, v149
	v_add_f32_e32 v82, v99, v98
	s_and_saveexec_b64 s[0:1], s[42:43]
	s_cbranch_execz .LBB0_534
	s_movk_i32 s4, 0x1200
	v_cvt_pk_bf16_f32 v83, v82, s0
	v_mad_u64_u32 v[84:85], s[6:7], v45, s4, v[0:1]
	ds_write_b16 v84, v83 offset:2592
	s_and_b64 exec, exec, vcc
	s_add_i32 s5, 0, 0x18c00
	v_add_u32_e32 v84, s5, v35
	ds_write_b16 v84, v83 offset:36
.LBB0_534:
	s_or_b64 exec, exec, s[0:1]
	v_cmp_eq_u32_e64 s[0:1], 19, v38
	v_cndmask_b32_e64 v83, 0, 1.0, s[0:1]
	s_waitcnt lgkmcnt(1)
	ds_read_b128 v[132:135], v37 offset:5440
	ds_read_b128 v[136:139], v37 offset:5456
	ds_read_b128 v[140:143], v37 offset:5472
	ds_read_b128 v[144:147], v37 offset:5488
	ds_read_b128 v[148:151], v37 offset:5504
	v_fmac_f32_e32 v83, v39, v174
	v_fma_f32 v100, v36, v175, 0
	v_fmac_f32_e32 v83, v41, v176
	v_fmac_f32_e32 v100, v40, v177
	v_fmac_f32_e32 v83, v69, v178
	v_fmac_f32_e32 v100, v50, v179
	v_fmac_f32_e32 v83, v70, v180
	v_fmac_f32_e32 v100, v71, v181
	v_fmac_f32_e32 v83, v72, v182
	v_fmac_f32_e32 v100, v73, v183
	v_fmac_f32_e32 v83, v74, v184
	v_fmac_f32_e32 v100, v75, v185
	v_fmac_f32_e32 v83, v76, v186
	v_fmac_f32_e32 v100, v77, v187
	v_fmac_f32_e32 v83, v78, v188
	v_fmac_f32_e32 v100, v79, v189
	v_fmac_f32_e32 v83, v80, v190
	v_fmac_f32_e32 v100, v81, v191
	v_fmac_f32_e32 v83, v82, v192
	v_add_f32_e32 v83, v100, v83
	s_and_saveexec_b64 s[0:1], s[42:43]
	s_cbranch_execz .LBB0_537
	s_movk_i32 s4, 0x1200
	v_cvt_pk_bf16_f32 v84, v83, s0
	v_mad_u64_u32 v[86:87], s[6:7], v45, s4, v[0:1]
	ds_write_b16 v86, v84 offset:2736
	s_and_b64 exec, exec, vcc
	s_add_i32 s5, 0, 0x18c00
	v_add_u32_e32 v85, s5, v35
	ds_write_b16 v85, v84 offset:38
.LBB0_537:
	s_or_b64 exec, exec, s[0:1]
	v_cmp_eq_u32_e64 s[0:1], 20, v38
	v_cndmask_b32_e64 v100, 0, 1.0, s[0:1]
	s_waitcnt lgkmcnt(1)
	ds_read_b128 v[174:177], v37 offset:5712
	ds_read_b128 v[178:181], v37 offset:5728
	ds_read_b128 v[182:185], v37 offset:5744
	ds_read_b128 v[186:189], v37 offset:5760
	ds_read_b128 v[190:193], v37 offset:5776
	ds_read_b128 v[194:197], v37 offset:5792
	v_fmac_f32_e32 v100, v39, v132
	v_fma_f32 v101, v36, v133, 0
	v_fmac_f32_e32 v100, v41, v134
	v_fmac_f32_e32 v101, v40, v135
	v_fmac_f32_e32 v100, v69, v136
	v_fmac_f32_e32 v101, v50, v137
	v_fmac_f32_e32 v100, v70, v138
	v_fmac_f32_e32 v101, v71, v139
	v_fmac_f32_e32 v100, v72, v140
	v_fmac_f32_e32 v101, v73, v141
	v_fmac_f32_e32 v100, v74, v142
	v_fmac_f32_e32 v101, v75, v143
	v_fmac_f32_e32 v100, v76, v144
	v_fmac_f32_e32 v101, v77, v145
	v_fmac_f32_e32 v100, v78, v146
	v_fmac_f32_e32 v101, v79, v147
	v_fmac_f32_e32 v100, v80, v148
	v_fmac_f32_e32 v101, v81, v149
	v_fmac_f32_e32 v100, v82, v150
	v_fmac_f32_e32 v101, v83, v151
	v_add_f32_e32 v84, v101, v100
	s_and_saveexec_b64 s[0:1], s[42:43]
	s_cbranch_execz .LBB0_540
	s_movk_i32 s4, 0x1200
	v_cvt_pk_bf16_f32 v85, v84, s0
	v_mad_u64_u32 v[86:87], s[6:7], v45, s4, v[0:1]
	ds_write_b16 v86, v85 offset:2880
	s_and_b64 exec, exec, vcc
	s_add_i32 s5, 0, 0x18c00
	v_add_u32_e32 v86, s5, v35
	ds_write_b16 v86, v85 offset:40
; #define LAS __attribute__((address_space(3)))
; __device__ __forceinline__ unsigned f2bf(float f) { return (unsigned)__builtin_bit_cast(unsigned short, (__bf16)f); }
; __device__ __forceinline__ void rwkv_pre(LAS unsigned char* lds, const MixBufs& B, bf16_t* rq, int L, int u, int unext, RwRaw& R) {
;     ...
;     if (w < 2) {
;         const int ob = w * 32, j = lane & 31;
;         float T[32];
;         int zv = 0; asm volatile("" : "+v"(zv));
;         const LAS float* Lfz = Lf + zv + ob * 68 + ob;
; #pragma unroll
;         for (int t = 0; t < 32; ++t) {
;             float a0 = (t == j) ? 1.f : 0.f, a1 = 0.f;
; #pragma unroll
;             for (int s4 = 0; s4 < (t + 3) / 4; ++s4) {
;                 const f32x4 l = *(const LAS f32x4*)(Lfz + t * 68 + s4 * 4);
; #pragma unroll
;                 for (int e2 = 0; e2 < 4; ++e2) { const int s_ = s4 * 4 + e2; if (s_ < t) { if (e2 & 1) a1 += l[e2] * T[s_]; else a0 += l[e2] * T[s_]; } }
;             }
;             T[t] = a0 + a1;
;             if (lane < 32) {
;                 Tm[(ob + t) * RL + ob + j] = (bf16_t)f2bf(T[t]);
;                 if (w == 0) T11T[j * 40 + t] = (bf16_t)f2bf(T[t]);
;             }
;         }
.LBB0_540:
	s_or_b64 exec, exec, s[0:1]
	v_cmp_eq_u32_e64 s[0:1], 21, v38
	v_cndmask_b32_e64 v85, 0, 1.0, s[0:1]
	s_waitcnt lgkmcnt(1)
	ds_read_b128 v[132:135], v37 offset:5984
	ds_read_b128 v[136:139], v37 offset:6000
	ds_read_b128 v[140:143], v37 offset:6016
	ds_read_b128 v[144:147], v37 offset:6032
	ds_read_b128 v[148:151], v37 offset:6048
	ds_read_b128 v[166:169], v37 offset:6064
	v_fmac_f32_e32 v85, v39, v174
	v_fma_f32 v102, v36, v175, 0
	v_fmac_f32_e32 v85, v41, v176
	v_fmac_f32_e32 v102, v40, v177
	v_fmac_f32_e32 v85, v69, v178
	v_fmac_f32_e32 v102, v50, v179
	v_fmac_f32_e32 v85, v70, v180
	v_fmac_f32_e32 v102, v71, v181
	v_fmac_f32_e32 v85, v72, v182
	v_fmac_f32_e32 v102, v73, v183
	v_fmac_f32_e32 v85, v74, v184
	v_fmac_f32_e32 v102, v75, v185
	v_fmac_f32_e32 v85, v76, v186
	v_fmac_f32_e32 v102, v77, v187
	v_fmac_f32_e32 v85, v78, v188
	v_fmac_f32_e32 v102, v79, v189
	v_fmac_f32_e32 v85, v80, v190
	v_fmac_f32_e32 v102, v81, v191
	v_fmac_f32_e32 v85, v82, v192
	v_fmac_f32_e32 v102, v83, v193
	v_fmac_f32_e32 v85, v84, v194
	v_add_f32_e32 v85, v102, v85
	s_and_saveexec_b64 s[0:1], s[42:43]
	s_cbranch_execz .LBB0_543
	s_movk_i32 s4, 0x1200
	v_cvt_pk_bf16_f32 v86, v85, s0
	v_mad_u64_u32 v[88:89], s[6:7], v45, s4, v[0:1]
	ds_write_b16 v88, v86 offset:3024
	s_and_b64 exec, exec, vcc
	s_add_i32 s5, 0, 0x18c00
	v_add_u32_e32 v87, s5, v35
	ds_write_b16 v87, v86 offset:42
.LBB0_543:
	s_or_b64 exec, exec, s[0:1]
	v_cmp_eq_u32_e64 s[0:1], 22, v38
	v_cndmask_b32_e64 v102, 0, 1.0, s[0:1]
	s_waitcnt lgkmcnt(1)
	ds_read_b128 v[174:177], v37 offset:6256
	ds_read_b128 v[178:181], v37 offset:6272
	ds_read_b128 v[182:185], v37 offset:6288
	ds_read_b128 v[186:189], v37 offset:6304
	ds_read_b128 v[190:193], v37 offset:6320
	ds_read_b128 v[194:197], v37 offset:6336
	v_fmac_f32_e32 v102, v39, v132
	v_fma_f32 v103, v36, v133, 0
	v_fmac_f32_e32 v102, v41, v134
	v_fmac_f32_e32 v103, v40, v135
	v_fmac_f32_e32 v102, v69, v136
	v_fmac_f32_e32 v103, v50, v137
	v_fmac_f32_e32 v102, v70, v138
	v_fmac_f32_e32 v103, v71, v139
	v_fmac_f32_e32 v102, v72, v140
	v_fmac_f32_e32 v103, v73, v141
	v_fmac_f32_e32 v102, v74, v142
	v_fmac_f32_e32 v103, v75, v143
	v_fmac_f32_e32 v102, v76, v144
	v_fmac_f32_e32 v103, v77, v145
	v_fmac_f32_e32 v102, v78, v146
	v_fmac_f32_e32 v103, v79, v147
	v_fmac_f32_e32 v102, v80, v148
	v_fmac_f32_e32 v103, v81, v149
	v_fmac_f32_e32 v102, v82, v150
	v_fmac_f32_e32 v103, v83, v151
	v_fmac_f32_e32 v102, v84, v166
	v_fmac_f32_e32 v103, v85, v167
	v_add_f32_e32 v86, v103, v102
	s_and_saveexec_b64 s[0:1], s[42:43]
	s_cbranch_execz .LBB0_546
	s_movk_i32 s4, 0x1200
	v_cvt_pk_bf16_f32 v87, v86, s0
	v_mad_u64_u32 v[88:89], s[6:7], v45, s4, v[0:1]
	ds_write_b16 v88, v87 offset:3168
	s_and_b64 exec, exec, vcc
	s_add_i32 s5, 0, 0x18c00
	v_add_u32_e32 v88, s5, v35
	ds_write_b16 v88, v87 offset:44
.LBB0_546:
	s_or_b64 exec, exec, s[0:1]
	v_cmp_eq_u32_e64 s[0:1], 23, v38
	v_cndmask_b32_e64 v87, 0, 1.0, s[0:1]
	s_waitcnt lgkmcnt(1)
	ds_read_b128 v[132:135], v37 offset:6528
	ds_read_b128 v[136:139], v37 offset:6544
	ds_read_b128 v[140:143], v37 offset:6560
	ds_read_b128 v[144:147], v37 offset:6576
	ds_read_b128 v[148:151], v37 offset:6592
	ds_read_b128 v[166:169], v37 offset:6608
	v_fmac_f32_e32 v87, v39, v174
	v_fma_f32 v104, v36, v175, 0
	v_fmac_f32_e32 v87, v41, v176
	v_fmac_f32_e32 v104, v40, v177
	v_fmac_f32_e32 v87, v69, v178
	v_fmac_f32_e32 v104, v50, v179
	v_fmac_f32_e32 v87, v70, v180
	v_fmac_f32_e32 v104, v71, v181
	v_fmac_f32_e32 v87, v72, v182
	v_fmac_f32_e32 v104, v73, v183
	v_fmac_f32_e32 v87, v74, v184
	v_fmac_f32_e32 v104, v75, v185
	v_fmac_f32_e32 v87, v76, v186
	v_fmac_f32_e32 v104, v77, v187
	v_fmac_f32_e32 v87, v78, v188
	v_fmac_f32_e32 v104, v79, v189
	v_fmac_f32_e32 v87, v80, v190
	v_fmac_f32_e32 v104, v81, v191
	v_fmac_f32_e32 v87, v82, v192
	v_fmac_f32_e32 v104, v83, v193
	v_fmac_f32_e32 v87, v84, v194
	v_fmac_f32_e32 v104, v85, v195
	v_fmac_f32_e32 v87, v86, v196
	v_add_f32_e32 v87, v104, v87
	s_and_saveexec_b64 s[0:1], s[42:43]
	s_cbranch_execz .LBB0_549
	s_movk_i32 s4, 0x1200
	v_cvt_pk_bf16_f32 v88, v87, s0
	v_mad_u64_u32 v[90:91], s[6:7], v45, s4, v[0:1]
	ds_write_b16 v90, v88 offset:3312
	s_and_b64 exec, exec, vcc
	s_add_i32 s5, 0, 0x18c00
	v_add_u32_e32 v89, s5, v35
	ds_write_b16 v89, v88 offset:46
.LBB0_549:
	s_or_b64 exec, exec, s[0:1]
	v_cmp_eq_u32_e64 s[0:1], 24, v38
	v_cndmask_b32_e64 v104, 0, 1.0, s[0:1]
	s_waitcnt lgkmcnt(1)
	ds_read_b128 v[174:177], v37 offset:6800
	ds_read_b128 v[178:181], v37 offset:6816
	ds_read_b128 v[182:185], v37 offset:6832
	ds_read_b128 v[186:189], v37 offset:6848
	ds_read_b128 v[190:193], v37 offset:6864
	ds_read_b128 v[194:197], v37 offset:6880
	ds_read_b128 v[198:201], v37 offset:6896
	v_fmac_f32_e32 v104, v39, v132
	v_fma_f32 v105, v36, v133, 0
	v_fmac_f32_e32 v104, v41, v134
	v_fmac_f32_e32 v105, v40, v135
	v_fmac_f32_e32 v104, v69, v136
	v_fmac_f32_e32 v105, v50, v137
	v_fmac_f32_e32 v104, v70, v138
	v_fmac_f32_e32 v105, v71, v139
	v_fmac_f32_e32 v104, v72, v140
	v_fmac_f32_e32 v105, v73, v141
	v_fmac_f32_e32 v104, v74, v142
	v_fmac_f32_e32 v105, v75, v143
	v_fmac_f32_e32 v104, v76, v144
	v_fmac_f32_e32 v105, v77, v145
	v_fmac_f32_e32 v104, v78, v146
	v_fmac_f32_e32 v105, v79, v147
	v_fmac_f32_e32 v104, v80, v148
	v_fmac_f32_e32 v105, v81, v149
	v_fmac_f32_e32 v104, v82, v150
	v_fmac_f32_e32 v105, v83, v151
	v_fmac_f32_e32 v104, v84, v166
	v_fmac_f32_e32 v105, v85, v167
	v_fmac_f32_e32 v104, v86, v168
	v_fmac_f32_e32 v105, v87, v169
	v_add_f32_e32 v88, v105, v104
	s_and_saveexec_b64 s[0:1], s[42:43]
	s_cbranch_execz .LBB0_552
	s_movk_i32 s4, 0x1200
	v_cvt_pk_bf16_f32 v89, v88, s0
	v_mad_u64_u32 v[90:91], s[6:7], v45, s4, v[0:1]
	ds_write_b16 v90, v89 offset:3456
	s_and_b64 exec, exec, vcc
	s_add_i32 s5, 0, 0x18c00
	v_add_u32_e32 v90, s5, v35
	ds_write_b16 v90, v89 offset:48
; #define LAS __attribute__((address_space(3)))
; __device__ __forceinline__ unsigned f2bf(float f) { return (unsigned)__builtin_bit_cast(unsigned short, (__bf16)f); }
; __device__ __forceinline__ void rwkv_pre(LAS unsigned char* lds, const MixBufs& B, bf16_t* rq, int L, int u, int unext, RwRaw& R) {
;     ...
;     if (w < 2) {
;         const int ob = w * 32, j = lane & 31;
;         float T[32];
;         int zv = 0; asm volatile("" : "+v"(zv));
;         const LAS float* Lfz = Lf + zv + ob * 68 + ob;
; #pragma unroll
;         for (int t = 0; t < 32; ++t) {
;             float a0 = (t == j) ? 1.f : 0.f, a1 = 0.f;
; #pragma unroll
;             for (int s4 = 0; s4 < (t + 3) / 4; ++s4) {
;                 const f32x4 l = *(const LAS f32x4*)(Lfz + t * 68 + s4 * 4);
; #pragma unroll
;                 for (int e2 = 0; e2 < 4; ++e2) { const int s_ = s4 * 4 + e2; if (s_ < t) { if (e2 & 1) a1 += l[e2] * T[s_]; else a0 += l[e2] * T[s_]; } }
;             }
;             T[t] = a0 + a1;
;             if (lane < 32) {
;                 Tm[(ob + t) * RL + ob + j] = (bf16_t)f2bf(T[t]);
;                 if (w == 0) T11T[j * 40 + t] = (bf16_t)f2bf(T[t]);
;             }
;         }
.LBB0_552:
	s_or_b64 exec, exec, s[0:1]
	v_cmp_eq_u32_e64 s[0:1], 25, v38
	v_cndmask_b32_e64 v89, 0, 1.0, s[0:1]
	s_waitcnt lgkmcnt(1)
	ds_read_b128 v[132:135], v37 offset:7072
	ds_read_b128 v[136:139], v37 offset:7088
	ds_read_b128 v[140:143], v37 offset:7104
	ds_read_b128 v[144:147], v37 offset:7120
	ds_read_b128 v[148:151], v37 offset:7136
	ds_read_b128 v[166:169], v37 offset:7152
	ds_read_b128 v[170:173], v37 offset:7168
	v_fmac_f32_e32 v89, v39, v174
	v_fma_f32 v106, v36, v175, 0
	v_fmac_f32_e32 v89, v41, v176
	v_fmac_f32_e32 v106, v40, v177
	v_fmac_f32_e32 v89, v69, v178
	v_fmac_f32_e32 v106, v50, v179
	v_fmac_f32_e32 v89, v70, v180
	v_fmac_f32_e32 v106, v71, v181
	v_fmac_f32_e32 v89, v72, v182
	v_fmac_f32_e32 v106, v73, v183
	v_fmac_f32_e32 v89, v74, v184
	v_fmac_f32_e32 v106, v75, v185
	v_fmac_f32_e32 v89, v76, v186
	v_fmac_f32_e32 v106, v77, v187
	v_fmac_f32_e32 v89, v78, v188
	v_fmac_f32_e32 v106, v79, v189
	v_fmac_f32_e32 v89, v80, v190
	v_fmac_f32_e32 v106, v81, v191
	v_fmac_f32_e32 v89, v82, v192
	v_fmac_f32_e32 v106, v83, v193
	v_fmac_f32_e32 v89, v84, v194
	v_fmac_f32_e32 v106, v85, v195
	v_fmac_f32_e32 v89, v86, v196
	v_fmac_f32_e32 v106, v87, v197
	v_fmac_f32_e32 v89, v88, v198
	v_add_f32_e32 v89, v106, v89
	s_and_saveexec_b64 s[0:1], s[42:43]
	s_cbranch_execz .LBB0_555
	s_movk_i32 s4, 0x1200
	v_cvt_pk_bf16_f32 v90, v89, s0
	v_mad_u64_u32 v[92:93], s[6:7], v45, s4, v[0:1]
	ds_write_b16 v92, v90 offset:3600
	s_and_b64 exec, exec, vcc
	s_add_i32 s5, 0, 0x18c00
	v_add_u32_e32 v91, s5, v35
	ds_write_b16 v91, v90 offset:50
.LBB0_555:
	s_or_b64 exec, exec, s[0:1]
	v_cmp_eq_u32_e64 s[0:1], 26, v38
	v_cndmask_b32_e64 v106, 0, 1.0, s[0:1]
	s_waitcnt lgkmcnt(1)
	ds_read_b128 v[174:177], v37 offset:7344
	ds_read_b128 v[178:181], v37 offset:7360
	ds_read_b128 v[182:185], v37 offset:7376
	ds_read_b128 v[186:189], v37 offset:7392
	ds_read_b128 v[190:193], v37 offset:7408
	ds_read_b128 v[194:197], v37 offset:7424
	ds_read_b128 v[198:201], v37 offset:7440
	v_fmac_f32_e32 v106, v39, v132
	v_fma_f32 v107, v36, v133, 0
	v_fmac_f32_e32 v106, v41, v134
	v_fmac_f32_e32 v107, v40, v135
	v_fmac_f32_e32 v106, v69, v136
	v_fmac_f32_e32 v107, v50, v137
	v_fmac_f32_e32 v106, v70, v138
	v_fmac_f32_e32 v107, v71, v139
	v_fmac_f32_e32 v106, v72, v140
	v_fmac_f32_e32 v107, v73, v141
	v_fmac_f32_e32 v106, v74, v142
	v_fmac_f32_e32 v107, v75, v143
	v_fmac_f32_e32 v106, v76, v144
	v_fmac_f32_e32 v107, v77, v145
	v_fmac_f32_e32 v106, v78, v146
	v_fmac_f32_e32 v107, v79, v147
	v_fmac_f32_e32 v106, v80, v148
	v_fmac_f32_e32 v107, v81, v149
	v_fmac_f32_e32 v106, v82, v150
	v_fmac_f32_e32 v107, v83, v151
	v_fmac_f32_e32 v106, v84, v166
	v_fmac_f32_e32 v107, v85, v167
	v_fmac_f32_e32 v106, v86, v168
	v_fmac_f32_e32 v107, v87, v169
	v_fmac_f32_e32 v106, v88, v170
	v_fmac_f32_e32 v107, v89, v171
	v_add_f32_e32 v90, v107, v106
	s_and_saveexec_b64 s[0:1], s[42:43]
	s_cbranch_execz .LBB0_558
	s_movk_i32 s4, 0x1200
	v_cvt_pk_bf16_f32 v91, v90, s0
	v_mad_u64_u32 v[92:93], s[6:7], v45, s4, v[0:1]
	ds_write_b16 v92, v91 offset:3744
	s_and_b64 exec, exec, vcc
	s_add_i32 s5, 0, 0x18c00
	v_add_u32_e32 v92, s5, v35
	ds_write_b16 v92, v91 offset:52
.LBB0_558:
	s_or_b64 exec, exec, s[0:1]
	v_cmp_eq_u32_e64 s[0:1], 27, v38
	v_cndmask_b32_e64 v91, 0, 1.0, s[0:1]
	s_waitcnt lgkmcnt(1)
	ds_read_b128 v[132:135], v37 offset:7616
	ds_read_b128 v[136:139], v37 offset:7632
	ds_read_b128 v[140:143], v37 offset:7648
	ds_read_b128 v[144:147], v37 offset:7664
	ds_read_b128 v[148:151], v37 offset:7680
	ds_read_b128 v[166:169], v37 offset:7696
	ds_read_b128 v[170:173], v37 offset:7712
	v_fmac_f32_e32 v91, v39, v174
	v_fma_f32 v108, v36, v175, 0
	v_fmac_f32_e32 v91, v41, v176
	v_fmac_f32_e32 v108, v40, v177
	v_fmac_f32_e32 v91, v69, v178
	v_fmac_f32_e32 v108, v50, v179
	v_fmac_f32_e32 v91, v70, v180
	v_fmac_f32_e32 v108, v71, v181
	v_fmac_f32_e32 v91, v72, v182
	v_fmac_f32_e32 v108, v73, v183
	v_fmac_f32_e32 v91, v74, v184
	v_fmac_f32_e32 v108, v75, v185
	v_fmac_f32_e32 v91, v76, v186
	v_fmac_f32_e32 v108, v77, v187
	v_fmac_f32_e32 v91, v78, v188
	v_fmac_f32_e32 v108, v79, v189
	v_fmac_f32_e32 v91, v80, v190
	v_fmac_f32_e32 v108, v81, v191
	v_fmac_f32_e32 v91, v82, v192
	v_fmac_f32_e32 v108, v83, v193
	v_fmac_f32_e32 v91, v84, v194
	v_fmac_f32_e32 v108, v85, v195
	v_fmac_f32_e32 v91, v86, v196
	v_fmac_f32_e32 v108, v87, v197
	v_fmac_f32_e32 v91, v88, v198
	v_fmac_f32_e32 v108, v89, v199
	v_fmac_f32_e32 v91, v90, v200
	v_add_f32_e32 v91, v108, v91
	s_and_saveexec_b64 s[0:1], s[42:43]
	s_cbranch_execz .LBB0_561
	s_movk_i32 s4, 0x1200
	v_cvt_pk_bf16_f32 v92, v91, s0
	v_mad_u64_u32 v[94:95], s[6:7], v45, s4, v[0:1]
	ds_write_b16 v94, v92 offset:3888
	s_and_b64 exec, exec, vcc
	s_add_i32 s5, 0, 0x18c00
	v_add_u32_e32 v93, s5, v35
	ds_write_b16 v93, v92 offset:54
.LBB0_561:
	s_or_b64 exec, exec, s[0:1]
	v_cmp_eq_u32_e64 s[0:1], 28, v38
	v_cndmask_b32_e64 v108, 0, 1.0, s[0:1]
	s_waitcnt lgkmcnt(1)
	v_fmac_f32_e32 v108, v39, v132
	v_fma_f32 v109, v36, v133, 0
	v_fmac_f32_e32 v108, v41, v134
	v_fmac_f32_e32 v109, v40, v135
	v_fmac_f32_e32 v108, v69, v136
	v_fmac_f32_e32 v109, v50, v137
	v_fmac_f32_e32 v108, v70, v138
	v_fmac_f32_e32 v109, v71, v139
	v_fmac_f32_e32 v108, v72, v140
	v_fmac_f32_e32 v109, v73, v141
	v_fmac_f32_e32 v108, v74, v142
	v_fmac_f32_e32 v109, v75, v143
	v_fmac_f32_e32 v108, v76, v144
	v_fmac_f32_e32 v109, v77, v145
	v_fmac_f32_e32 v108, v78, v146
	v_fmac_f32_e32 v109, v79, v147
	v_fmac_f32_e32 v108, v80, v148
	v_fmac_f32_e32 v109, v81, v149
	v_fmac_f32_e32 v108, v82, v150
	v_fmac_f32_e32 v109, v83, v151
	v_fmac_f32_e32 v108, v84, v166
	v_fmac_f32_e32 v109, v85, v167
	v_fmac_f32_e32 v108, v86, v168
	v_fmac_f32_e32 v109, v87, v169
	v_fmac_f32_e32 v108, v88, v170
	v_fmac_f32_e32 v109, v89, v171
	v_fmac_f32_e32 v108, v90, v172
	v_fmac_f32_e32 v109, v91, v173
	v_add_f32_e32 v92, v109, v108
	s_and_saveexec_b64 s[0:1], s[42:43]
	s_cbranch_execz .LBB0_564
	s_movk_i32 s4, 0x1200
	v_cvt_pk_bf16_f32 v93, v92, s0
	v_mad_u64_u32 v[94:95], s[6:7], v45, s4, v[0:1]
	ds_write_b16 v94, v93 offset:4032
	s_and_b64 exec, exec, vcc
	s_add_i32 s5, 0, 0x18c00
	v_add_u32_e32 v94, s5, v35
	ds_write_b16 v94, v93 offset:56

; #define LAS __attribute__((address_space(3)))
; __device__ __forceinline__ unsigned f2bf(float f) { return (unsigned)__builtin_bit_cast(unsigned short, (__bf16)f); }
; __device__ __forceinline__ void rwkv_pre(LAS unsigned char* lds, const MixBufs& B, bf16_t* rq, int L, int u, int unext, RwRaw& R) {
;     ...
;     if (w < 2) {
;         const int ob = w * 32, j = lane & 31;
;         float T[32];
;         int zv = 0; asm volatile("" : "+v"(zv));
;         const LAS float* Lfz = Lf + zv + ob * 68 + ob;
; #pragma unroll
;         for (int t = 0; t < 32; ++t) {
;             float a0 = (t == j) ? 1.f : 0.f, a1 = 0.f;
; #pragma unroll
;             for (int s4 = 0; s4 < (t + 3) / 4; ++s4) {
;                 const f32x4 l = *(const LAS f32x4*)(Lfz + t * 68 + s4 * 4);
; #pragma unroll
;                 for (int e2 = 0; e2 < 4; ++e2) { const int s_ = s4 * 4 + e2; if (s_ < t) { if (e2 & 1) a1 += l[e2] * T[s_]; else a0 += l[e2] * T[s_]; } }
;             }
;             T[t] = a0 + a1;
;             if (lane < 32) {
;                 Tm[(ob + t) * RL + ob + j] = (bf16_t)f2bf(T[t]);
;                 if (w == 0) T11T[j * 40 + t] = (bf16_t)f2bf(T[t]);
;             }
;         }
.LBB0_630:
	s_or_b64 exec, exec, s[0:1]
	ds_read_b128 v[12:15], v8 offset:544
	v_cmp_eq_u32_e64 s[0:1], 2, v9
	s_waitcnt lgkmcnt(0)
	ds_read_b128 v[174:177], v8 offset:816
	s_nop 0
	v_cndmask_b32_e64 v14, 0, 1.0, s[0:1]
	v_fmac_f32_e32 v14, v10, v12
	v_fma_f32 v12, v7, v13, 0
	v_add_f32_e32 v13, v12, v14
	s_and_saveexec_b64 s[0:1], s[46:47]
	s_cbranch_execz .LBB0_633
	s_movk_i32 s4, 0x1200
	v_cvt_pk_bf16_f32 v12, v13, s0
	v_mad_u64_u32 v[14:15], s[6:7], v26, s4, v[0:1]
	ds_write_b16 v14, v12 offset:288
	s_and_b64 exec, exec, vcc
	v_add_u32_e32 v14, s56, v11
	ds_write_b16 v14, v12 offset:4
.LBB0_633:
	s_or_b64 exec, exec, s[0:1]
	v_cmp_eq_u32_e64 s[0:1], 3, v9
	s_nop 1
	v_cndmask_b32_e64 v12, 0, 1.0, s[0:1]
	s_waitcnt lgkmcnt(1)
	ds_read_b128 v[132:135], v8 offset:1088
	v_fmac_f32_e32 v12, v10, v174
	v_fma_f32 v14, v7, v175, 0
	v_fmac_f32_e32 v12, v13, v176
	v_add_f32_e32 v12, v14, v12
	s_and_saveexec_b64 s[0:1], s[46:47]
	s_cbranch_execz .LBB0_636
	s_movk_i32 s4, 0x1200
	v_cvt_pk_bf16_f32 v14, v12, s0
	v_mad_u64_u32 v[16:17], s[6:7], v26, s4, v[0:1]
	ds_write_b16 v16, v14 offset:432
	s_and_b64 exec, exec, vcc
	v_add_u32_e32 v15, s56, v11
	ds_write_b16 v15, v14 offset:6
.LBB0_636:
	s_or_b64 exec, exec, s[0:1]
	v_cmp_eq_u32_e64 s[0:1], 4, v9
	s_nop 1
	v_cndmask_b32_e64 v31, 0, 1.0, s[0:1]
	s_waitcnt lgkmcnt(1)
	ds_read_b128 v[174:177], v8 offset:1360
	ds_read_b128 v[178:181], v8 offset:1376
	v_fmac_f32_e32 v31, v10, v132
	v_fma_f32 v14, v7, v133, 0
	v_fmac_f32_e32 v31, v13, v134
	v_fmac_f32_e32 v14, v12, v135
	v_add_f32_e32 v15, v14, v31
	s_and_saveexec_b64 s[0:1], s[46:47]
	s_cbranch_execz .LBB0_639
	s_movk_i32 s4, 0x1200
	v_cvt_pk_bf16_f32 v14, v15, s0
	v_mad_u64_u32 v[16:17], s[6:7], v26, s4, v[0:1]
	ds_write_b16 v16, v14 offset:576
	s_and_b64 exec, exec, vcc
	v_add_u32_e32 v16, s56, v11
	ds_write_b16 v16, v14 offset:8
.LBB0_639:
	s_or_b64 exec, exec, s[0:1]
	v_cmp_eq_u32_e64 s[0:1], 5, v9
	s_waitcnt lgkmcnt(1)
	ds_read_b128 v[132:135], v8 offset:1632
	ds_read_b128 v[136:139], v8 offset:1648
	v_fma_f32 v16, v7, v175, 0
	v_cndmask_b32_e64 v14, 0, 1.0, s[0:1]
	v_fmac_f32_e32 v14, v10, v174
	v_fmac_f32_e32 v14, v13, v176
	v_fmac_f32_e32 v16, v12, v177
	v_fmac_f32_e32 v14, v15, v178
	v_add_f32_e32 v14, v16, v14
	s_and_saveexec_b64 s[0:1], s[46:47]
	s_cbranch_execz .LBB0_642
	s_movk_i32 s4, 0x1200
	v_cvt_pk_bf16_f32 v16, v14, s0
	v_mad_u64_u32 v[32:33], s[6:7], v26, s4, v[0:1]
	ds_write_b16 v32, v16 offset:720
	s_and_b64 exec, exec, vcc
	v_add_u32_e32 v17, s56, v11
	ds_write_b16 v17, v16 offset:10
.LBB0_642:
	s_or_b64 exec, exec, s[0:1]
	v_cmp_eq_u32_e64 s[0:1], 6, v9
	s_waitcnt lgkmcnt(1)
	ds_read_b128 v[174:177], v8 offset:1904
	ds_read_b128 v[178:181], v8 offset:1920
	v_fma_f32 v17, v7, v133, 0
	v_cndmask_b32_e64 v16, 0, 1.0, s[0:1]
	v_fmac_f32_e32 v16, v10, v132
	v_fmac_f32_e32 v16, v13, v134
	v_fmac_f32_e32 v17, v12, v135
	v_fmac_f32_e32 v16, v15, v136
	v_fmac_f32_e32 v17, v14, v137
	v_add_f32_e32 v17, v17, v16
	s_and_saveexec_b64 s[0:1], s[46:47]
	s_cbranch_execz .LBB0_645
	s_movk_i32 s4, 0x1200
	v_cvt_pk_bf16_f32 v16, v17, s0
	v_mad_u64_u32 v[32:33], s[6:7], v26, s4, v[0:1]
	ds_write_b16 v32, v16 offset:864
	s_and_b64 exec, exec, vcc
	v_add_u32_e32 v31, s56, v11
	ds_write_b16 v31, v16 offset:12
.LBB0_645:
	s_or_b64 exec, exec, s[0:1]
	v_cmp_eq_u32_e64 s[0:1], 7, v9
	s_waitcnt lgkmcnt(1)
	ds_read_b128 v[132:135], v8 offset:2176
	ds_read_b128 v[136:139], v8 offset:2192
	v_fma_f32 v31, v7, v175, 0
	v_cndmask_b32_e64 v16, 0, 1.0, s[0:1]
	v_fmac_f32_e32 v16, v10, v174
	v_fmac_f32_e32 v16, v13, v176
	v_fmac_f32_e32 v31, v12, v177
	v_fmac_f32_e32 v16, v15, v178
	v_fmac_f32_e32 v31, v14, v179
	v_fmac_f32_e32 v16, v17, v180
	v_add_f32_e32 v16, v31, v16
	s_and_saveexec_b64 s[0:1], s[46:47]
	s_cbranch_execz .LBB0_648
	s_movk_i32 s4, 0x1200
	v_cvt_pk_bf16_f32 v31, v16, s0
	v_mad_u64_u32 v[32:33], s[6:7], v26, s4, v[0:1]
	ds_write_b16 v32, v31 offset:1008
	s_and_b64 exec, exec, vcc
	v_add_u32_e32 v32, s56, v11
	ds_write_b16 v32, v31 offset:14
.LBB0_648:
	s_or_b64 exec, exec, s[0:1]
	v_cmp_eq_u32_e64 s[0:1], 8, v9
	s_nop 1
	v_cndmask_b32_e64 v31, 0, 1.0, s[0:1]
	s_waitcnt lgkmcnt(1)
	ds_read_b128 v[174:177], v8 offset:2448
	ds_read_b128 v[178:181], v8 offset:2464
	ds_read_b128 v[182:185], v8 offset:2480
	v_fmac_f32_e32 v31, v10, v132
	v_fma_f32 v32, v7, v133, 0
	v_fmac_f32_e32 v31, v13, v134
	v_fmac_f32_e32 v32, v12, v135
	v_fmac_f32_e32 v31, v15, v136
	v_fmac_f32_e32 v32, v14, v137
	v_fmac_f32_e32 v31, v17, v138
	v_fmac_f32_e32 v32, v16, v139
	v_add_f32_e32 v31, v32, v31
	s_and_saveexec_b64 s[0:1], s[46:47]
	s_cbranch_execz .LBB0_651
	s_movk_i32 s4, 0x1200
	v_cvt_pk_bf16_f32 v32, v31, s0
	v_mad_u64_u32 v[34:35], s[6:7], v26, s4, v[0:1]
	ds_write_b16 v34, v32 offset:1152
	s_and_b64 exec, exec, vcc
	v_add_u32_e32 v33, s56, v11
	ds_write_b16 v33, v32 offset:16
.LBB0_651:
	s_or_b64 exec, exec, s[0:1]
	v_cmp_eq_u32_e64 s[0:1], 9, v9
	s_nop 1
	v_cndmask_b32_e64 v40, 0, 1.0, s[0:1]
	s_waitcnt lgkmcnt(1)
	ds_read_b128 v[132:135], v8 offset:2720
	ds_read_b128 v[136:139], v8 offset:2736
	ds_read_b128 v[140:143], v8 offset:2752
	v_fmac_f32_e32 v40, v10, v174
	v_fma_f32 v32, v7, v175, 0
	v_fmac_f32_e32 v40, v13, v176
	v_fmac_f32_e32 v32, v12, v177
	v_fmac_f32_e32 v40, v15, v178
	v_fmac_f32_e32 v32, v14, v179
	v_fmac_f32_e32 v40, v17, v180
	v_fmac_f32_e32 v32, v16, v181
	v_fmac_f32_e32 v40, v31, v182
	v_add_f32_e32 v32, v32, v40
	s_and_saveexec_b64 s[0:1], s[46:47]
	s_cbranch_execz .LBB0_654
	s_movk_i32 s4, 0x1200
	v_cvt_pk_bf16_f32 v33, v32, s0
	v_mad_u64_u32 v[34:35], s[6:7], v26, s4, v[0:1]
	ds_write_b16 v34, v33 offset:1296
	s_and_b64 exec, exec, vcc
	v_add_u32_e32 v34, s56, v11
	ds_write_b16 v34, v33 offset:18
; #define LAS __attribute__((address_space(3)))
; __device__ __forceinline__ unsigned f2bf(float f) { return (unsigned)__builtin_bit_cast(unsigned short, (__bf16)f); }
; __device__ __forceinline__ void rwkv_pre(LAS unsigned char* lds, const MixBufs& B, bf16_t* rq, int L, int u, int unext, RwRaw& R) {
;     ...
;     if (w < 2) {
;         const int ob = w * 32, j = lane & 31;
;         float T[32];
;         int zv = 0; asm volatile("" : "+v"(zv));
;         const LAS float* Lfz = Lf + zv + ob * 68 + ob;
; #pragma unroll
;         for (int t = 0; t < 32; ++t) {
;             float a0 = (t == j) ? 1.f : 0.f, a1 = 0.f;
; #pragma unroll
;             for (int s4 = 0; s4 < (t + 3) / 4; ++s4) {
;                 const f32x4 l = *(const LAS f32x4*)(Lfz + t * 68 + s4 * 4);
; #pragma unroll
;                 for (int e2 = 0; e2 < 4; ++e2) { const int s_ = s4 * 4 + e2; if (s_ < t) { if (e2 & 1) a1 += l[e2] * T[s_]; else a0 += l[e2] * T[s_]; } }
;             }
;             T[t] = a0 + a1;
;             if (lane < 32) {
;                 Tm[(ob + t) * RL + ob + j] = (bf16_t)f2bf(T[t]);
;                 if (w == 0) T11T[j * 40 + t] = (bf16_t)f2bf(T[t]);
;             }
;         }
.LBB0_654:
	s_or_b64 exec, exec, s[0:1]
	v_cmp_eq_u32_e64 s[0:1], 10, v9
	s_nop 1
	v_cndmask_b32_e64 v33, 0, 1.0, s[0:1]
	s_waitcnt lgkmcnt(1)
	ds_read_b128 v[174:177], v8 offset:2992
	ds_read_b128 v[178:181], v8 offset:3008
	ds_read_b128 v[182:185], v8 offset:3024
	v_fmac_f32_e32 v33, v10, v132
	v_fma_f32 v34, v7, v133, 0
	v_fmac_f32_e32 v33, v13, v134
	v_fmac_f32_e32 v34, v12, v135
	v_fmac_f32_e32 v33, v15, v136
	v_fmac_f32_e32 v34, v14, v137
	v_fmac_f32_e32 v33, v17, v138
	v_fmac_f32_e32 v34, v16, v139
	v_fmac_f32_e32 v33, v31, v140
	v_fmac_f32_e32 v34, v32, v141
	v_add_f32_e32 v33, v34, v33
	s_and_saveexec_b64 s[0:1], s[46:47]
	s_cbranch_execz .LBB0_657
	s_movk_i32 s4, 0x1200
	v_cvt_pk_bf16_f32 v34, v33, s0
	v_mad_u64_u32 v[36:37], s[6:7], v26, s4, v[0:1]
	ds_write_b16 v36, v34 offset:1440
	s_and_b64 exec, exec, vcc
	v_add_u32_e32 v35, s56, v11
	ds_write_b16 v35, v34 offset:20
.LBB0_657:
	s_or_b64 exec, exec, s[0:1]
	v_cmp_eq_u32_e64 s[0:1], 11, v9
	s_waitcnt lgkmcnt(1)
	ds_read_b128 v[132:135], v8 offset:3264
	ds_read_b128 v[136:139], v8 offset:3280
	ds_read_b128 v[140:143], v8 offset:3296
	s_nop 0
	v_cndmask_b32_e64 v53, 0, 1.0, s[0:1]
	v_fmac_f32_e32 v53, v10, v174
	v_fma_f32 v34, v7, v175, 0
	v_fmac_f32_e32 v53, v13, v176
	v_fmac_f32_e32 v34, v12, v177
	v_fmac_f32_e32 v53, v15, v178
	v_fmac_f32_e32 v34, v14, v179
	v_fmac_f32_e32 v53, v17, v180
	v_fmac_f32_e32 v34, v16, v181
	v_fmac_f32_e32 v53, v31, v182
	v_fmac_f32_e32 v34, v32, v183
	v_fmac_f32_e32 v53, v33, v184
	v_add_f32_e32 v34, v34, v53
	s_and_saveexec_b64 s[0:1], s[46:47]
	s_cbranch_execz .LBB0_660
	s_movk_i32 s4, 0x1200
	v_cvt_pk_bf16_f32 v35, v34, s0
	v_mad_u64_u32 v[36:37], s[6:7], v26, s4, v[0:1]
	ds_write_b16 v36, v35 offset:1584
	s_and_b64 exec, exec, vcc
	v_add_u32_e32 v36, s56, v11
	ds_write_b16 v36, v35 offset:22
.LBB0_660:
	s_or_b64 exec, exec, s[0:1]
	v_cmp_eq_u32_e64 s[0:1], 12, v9
	v_cndmask_b32_e64 v35, 0, 1.0, s[0:1]
	s_waitcnt lgkmcnt(1)
	ds_read_b128 v[174:177], v8 offset:3536
	ds_read_b128 v[178:181], v8 offset:3552
	ds_read_b128 v[182:185], v8 offset:3568
	ds_read_b128 v[186:189], v8 offset:3584
	v_fmac_f32_e32 v35, v10, v132
	v_fma_f32 v36, v7, v133, 0
	v_fmac_f32_e32 v35, v13, v134
	v_fmac_f32_e32 v36, v12, v135
	v_fmac_f32_e32 v35, v15, v136
	v_fmac_f32_e32 v36, v14, v137
	v_fmac_f32_e32 v35, v17, v138
	v_fmac_f32_e32 v36, v16, v139
	v_fmac_f32_e32 v35, v31, v140
	v_fmac_f32_e32 v36, v32, v141
	v_fmac_f32_e32 v35, v33, v142
	v_fmac_f32_e32 v36, v34, v143
	v_add_f32_e32 v35, v36, v35
	s_and_saveexec_b64 s[0:1], s[46:47]
	s_cbranch_execz .LBB0_663
	s_movk_i32 s4, 0x1200
	v_cvt_pk_bf16_f32 v36, v35, s0
	v_mad_u64_u32 v[38:39], s[6:7], v26, s4, v[0:1]
	ds_write_b16 v38, v36 offset:1728
	s_and_b64 exec, exec, vcc
	v_add_u32_e32 v37, s56, v11
	ds_write_b16 v37, v36 offset:24
.LBB0_663:
	s_or_b64 exec, exec, s[0:1]
	v_cmp_eq_u32_e64 s[0:1], 13, v9
	v_cndmask_b32_e64 v40, 0, 1.0, s[0:1]
	s_waitcnt lgkmcnt(1)
	ds_read_b128 v[132:135], v8 offset:3808
	ds_read_b128 v[136:139], v8 offset:3824
	ds_read_b128 v[140:143], v8 offset:3840
	ds_read_b128 v[144:147], v8 offset:3856
	v_fmac_f32_e32 v40, v10, v174
	v_fma_f32 v36, v7, v175, 0
	v_fmac_f32_e32 v40, v13, v176
	v_fmac_f32_e32 v36, v12, v177
	v_fmac_f32_e32 v40, v15, v178
	v_fmac_f32_e32 v36, v14, v179
	v_fmac_f32_e32 v40, v17, v180
	v_fmac_f32_e32 v36, v16, v181
	v_fmac_f32_e32 v40, v31, v182
	v_fmac_f32_e32 v36, v32, v183
	v_fmac_f32_e32 v40, v33, v184
	v_fmac_f32_e32 v36, v34, v185
	v_fmac_f32_e32 v40, v35, v186
	v_add_f32_e32 v36, v36, v40
	s_and_saveexec_b64 s[0:1], s[46:47]
	s_cbranch_execz .LBB0_666
	s_movk_i32 s4, 0x1200
	v_cvt_pk_bf16_f32 v37, v36, s0
	v_mad_u64_u32 v[38:39], s[6:7], v26, s4, v[0:1]
	ds_write_b16 v38, v37 offset:1872
	s_and_b64 exec, exec, vcc
	v_add_u32_e32 v38, s56, v11
	ds_write_b16 v38, v37 offset:26
.LBB0_666:
	s_or_b64 exec, exec, s[0:1]
	v_cmp_eq_u32_e64 s[0:1], 14, v9
	v_cndmask_b32_e64 v37, 0, 1.0, s[0:1]
	s_waitcnt lgkmcnt(1)
	ds_read_b128 v[174:177], v8 offset:4080
	ds_read_b128 v[178:181], v8 offset:4096
	ds_read_b128 v[182:185], v8 offset:4112
	ds_read_b128 v[186:189], v8 offset:4128
	v_fmac_f32_e32 v37, v10, v132
	v_fma_f32 v38, v7, v133, 0
	v_fmac_f32_e32 v37, v13, v134
	v_fmac_f32_e32 v38, v12, v135
	v_fmac_f32_e32 v37, v15, v136
	v_fmac_f32_e32 v38, v14, v137
	v_fmac_f32_e32 v37, v17, v138
	v_fmac_f32_e32 v38, v16, v139
	v_fmac_f32_e32 v37, v31, v140
	v_fmac_f32_e32 v38, v32, v141
	v_fmac_f32_e32 v37, v33, v142
	v_fmac_f32_e32 v38, v34, v143
	v_fmac_f32_e32 v37, v35, v144
	v_fmac_f32_e32 v38, v36, v145
	v_add_f32_e32 v37, v38, v37
	s_and_saveexec_b64 s[0:1], s[46:47]
	s_cbranch_execz .LBB0_669
	s_movk_i32 s4, 0x1200
	v_cvt_pk_bf16_f32 v38, v37, s0
	v_mad_u64_u32 v[40:41], s[6:7], v26, s4, v[0:1]
	ds_write_b16 v40, v38 offset:2016
	s_and_b64 exec, exec, vcc
	v_add_u32_e32 v39, s56, v11
	ds_write_b16 v39, v38 offset:28
.LBB0_669:
	s_or_b64 exec, exec, s[0:1]
	v_cmp_eq_u32_e64 s[0:1], 15, v9
	v_cndmask_b32_e64 v54, 0, 1.0, s[0:1]
	s_waitcnt lgkmcnt(1)
	ds_read_b128 v[132:135], v8 offset:4352
	ds_read_b128 v[136:139], v8 offset:4368
	ds_read_b128 v[140:143], v8 offset:4384
	ds_read_b128 v[144:147], v8 offset:4400
	v_fmac_f32_e32 v54, v10, v174
	v_fma_f32 v38, v7, v175, 0
	v_fmac_f32_e32 v54, v13, v176
	v_fmac_f32_e32 v38, v12, v177
	v_fmac_f32_e32 v54, v15, v178
	v_fmac_f32_e32 v38, v14, v179
	v_fmac_f32_e32 v54, v17, v180
	v_fmac_f32_e32 v38, v16, v181
	v_fmac_f32_e32 v54, v31, v182
	v_fmac_f32_e32 v38, v32, v183
	v_fmac_f32_e32 v54, v33, v184
	v_fmac_f32_e32 v38, v34, v185
	v_fmac_f32_e32 v54, v35, v186
	v_fmac_f32_e32 v38, v36, v187
	v_fmac_f32_e32 v54, v37, v188
	v_add_f32_e32 v38, v38, v54
	s_and_saveexec_b64 s[0:1], s[46:47]
	s_cbranch_execz .LBB0_672
	s_movk_i32 s4, 0x1200
	v_cvt_pk_bf16_f32 v39, v38, s0
	v_mad_u64_u32 v[40:41], s[6:7], v26, s4, v[0:1]
	ds_write_b16 v40, v39 offset:2160
	s_and_b64 exec, exec, vcc
	v_add_u32_e32 v40, s56, v11
	ds_write_b16 v40, v39 offset:30
; #define LAS __attribute__((address_space(3)))
; __device__ __forceinline__ unsigned f2bf(float f) { return (unsigned)__builtin_bit_cast(unsigned short, (__bf16)f); }
; __device__ __forceinline__ void rwkv_pre(LAS unsigned char* lds, const MixBufs& B, bf16_t* rq, int L, int u, int unext, RwRaw& R) {
;     ...
;     if (w < 2) {
;         const int ob = w * 32, j = lane & 31;
;         float T[32];
;         int zv = 0; asm volatile("" : "+v"(zv));
;         const LAS float* Lfz = Lf + zv + ob * 68 + ob;
; #pragma unroll
;         for (int t = 0; t < 32; ++t) {
;             float a0 = (t == j) ? 1.f : 0.f, a1 = 0.f;
; #pragma unroll
;             for (int s4 = 0; s4 < (t + 3) / 4; ++s4) {
;                 const f32x4 l = *(const LAS f32x4*)(Lfz + t * 68 + s4 * 4);
; #pragma unroll
;                 for (int e2 = 0; e2 < 4; ++e2) { const int s_ = s4 * 4 + e2; if (s_ < t) { if (e2 & 1) a1 += l[e2] * T[s_]; else a0 += l[e2] * T[s_]; } }
;             }
;             T[t] = a0 + a1;
;             if (lane < 32) {
;                 Tm[(ob + t) * RL + ob + j] = (bf16_t)f2bf(T[t]);
;                 if (w == 0) T11T[j * 40 + t] = (bf16_t)f2bf(T[t]);
;             }
;         }
.LBB0_672:
	s_or_b64 exec, exec, s[0:1]
	v_cmp_eq_u32_e64 s[0:1], 16, v9
	v_cndmask_b32_e64 v39, 0, 1.0, s[0:1]
	s_waitcnt lgkmcnt(1)
	ds_read_b128 v[174:177], v8 offset:4624
	ds_read_b128 v[178:181], v8 offset:4640
	ds_read_b128 v[182:185], v8 offset:4656
	ds_read_b128 v[186:189], v8 offset:4672
	ds_read_b128 v[190:193], v8 offset:4688
	v_fmac_f32_e32 v39, v10, v132
	v_fma_f32 v40, v7, v133, 0
	v_fmac_f32_e32 v39, v13, v134
	v_fmac_f32_e32 v40, v12, v135
	v_fmac_f32_e32 v39, v15, v136
	v_fmac_f32_e32 v40, v14, v137
	v_fmac_f32_e32 v39, v17, v138
	v_fmac_f32_e32 v40, v16, v139
	v_fmac_f32_e32 v39, v31, v140
	v_fmac_f32_e32 v40, v32, v141
	v_fmac_f32_e32 v39, v33, v142
	v_fmac_f32_e32 v40, v34, v143
	v_fmac_f32_e32 v39, v35, v144
	v_fmac_f32_e32 v40, v36, v145
	v_fmac_f32_e32 v39, v37, v146
	v_fmac_f32_e32 v40, v38, v147
	v_add_f32_e32 v39, v40, v39
	s_and_saveexec_b64 s[0:1], s[46:47]
	s_cbranch_execz .LBB0_675
	s_movk_i32 s4, 0x1200
	v_cvt_pk_bf16_f32 v40, v39, s0
	v_mad_u64_u32 v[50:51], s[6:7], v26, s4, v[0:1]
	ds_write_b16 v50, v40 offset:2304
	s_and_b64 exec, exec, vcc
	v_add_u32_e32 v41, s56, v11
	ds_write_b16 v41, v40 offset:32
.LBB0_675:
	s_or_b64 exec, exec, s[0:1]
	v_cmp_eq_u32_e64 s[0:1], 17, v9
	v_cndmask_b32_e64 v40, 0, 1.0, s[0:1]
	s_waitcnt lgkmcnt(1)
	ds_read_b128 v[132:135], v8 offset:4896
	ds_read_b128 v[136:139], v8 offset:4912
	ds_read_b128 v[140:143], v8 offset:4928
	ds_read_b128 v[144:147], v8 offset:4944
	ds_read_b128 v[148:151], v8 offset:4960
	v_fmac_f32_e32 v40, v10, v174
	v_fma_f32 v41, v7, v175, 0
	v_fmac_f32_e32 v40, v13, v176
	v_fmac_f32_e32 v41, v12, v177
	v_fmac_f32_e32 v40, v15, v178
	v_fmac_f32_e32 v41, v14, v179
	v_fmac_f32_e32 v40, v17, v180
	v_fmac_f32_e32 v41, v16, v181
	v_fmac_f32_e32 v40, v31, v182
	v_fmac_f32_e32 v41, v32, v183
	v_fmac_f32_e32 v40, v33, v184
	v_fmac_f32_e32 v41, v34, v185
	v_fmac_f32_e32 v40, v35, v186
	v_fmac_f32_e32 v41, v36, v187
	v_fmac_f32_e32 v40, v37, v188
	v_fmac_f32_e32 v41, v38, v189
	v_fmac_f32_e32 v40, v39, v190
	v_add_f32_e32 v40, v41, v40
	s_and_saveexec_b64 s[0:1], s[46:47]
	s_cbranch_execz .LBB0_678
	s_movk_i32 s4, 0x1200
	v_cvt_pk_bf16_f32 v41, v40, s0
	v_mad_u64_u32 v[50:51], s[6:7], v26, s4, v[0:1]
	ds_write_b16 v50, v41 offset:2448
	s_and_b64 exec, exec, vcc
	v_add_u32_e32 v50, s56, v11
	ds_write_b16 v50, v41 offset:34
.LBB0_678:
	s_or_b64 exec, exec, s[0:1]
	v_cmp_eq_u32_e64 s[0:1], 18, v9
	v_cndmask_b32_e64 v41, 0, 1.0, s[0:1]
	s_waitcnt lgkmcnt(1)
	ds_read_b128 v[174:177], v8 offset:5168
	ds_read_b128 v[178:181], v8 offset:5184
	ds_read_b128 v[182:185], v8 offset:5200
	ds_read_b128 v[186:189], v8 offset:5216
	ds_read_b128 v[190:193], v8 offset:5232
	v_fmac_f32_e32 v41, v10, v132
	v_fma_f32 v54, v7, v133, 0
	v_fmac_f32_e32 v41, v13, v134
	v_fmac_f32_e32 v54, v12, v135
	v_fmac_f32_e32 v41, v15, v136
	v_fmac_f32_e32 v54, v14, v137
	v_fmac_f32_e32 v41, v17, v138
	v_fmac_f32_e32 v54, v16, v139
	v_fmac_f32_e32 v41, v31, v140
	v_fmac_f32_e32 v54, v32, v141
	v_fmac_f32_e32 v41, v33, v142
	v_fmac_f32_e32 v54, v34, v143
	v_fmac_f32_e32 v41, v35, v144
	v_fmac_f32_e32 v54, v36, v145
	v_fmac_f32_e32 v41, v37, v146
	v_fmac_f32_e32 v54, v38, v147
	v_fmac_f32_e32 v41, v39, v148
	v_fmac_f32_e32 v54, v40, v149
	v_add_f32_e32 v41, v54, v41
	s_and_saveexec_b64 s[0:1], s[46:47]
	s_cbranch_execz .LBB0_681
	s_movk_i32 s4, 0x1200
	v_cvt_pk_bf16_f32 v50, v41, s0
	v_mad_u64_u32 v[52:53], s[6:7], v26, s4, v[0:1]
	ds_write_b16 v52, v50 offset:2592
	s_and_b64 exec, exec, vcc
	v_add_u32_e32 v51, s56, v11
	ds_write_b16 v51, v50 offset:36
.LBB0_681:
	s_or_b64 exec, exec, s[0:1]
	v_cmp_eq_u32_e64 s[0:1], 19, v9
	v_cndmask_b32_e64 v54, 0, 1.0, s[0:1]
	s_waitcnt lgkmcnt(1)
	ds_read_b128 v[132:135], v8 offset:5440
	ds_read_b128 v[136:139], v8 offset:5456
	ds_read_b128 v[140:143], v8 offset:5472
	ds_read_b128 v[144:147], v8 offset:5488
	ds_read_b128 v[148:151], v8 offset:5504
	v_fmac_f32_e32 v54, v10, v174
	v_fma_f32 v55, v7, v175, 0
	v_fmac_f32_e32 v54, v13, v176
	v_fmac_f32_e32 v55, v12, v177
	v_fmac_f32_e32 v54, v15, v178
	v_fmac_f32_e32 v55, v14, v179
	v_fmac_f32_e32 v54, v17, v180
	v_fmac_f32_e32 v55, v16, v181
	v_fmac_f32_e32 v54, v31, v182
	v_fmac_f32_e32 v55, v32, v183
	v_fmac_f32_e32 v54, v33, v184
	v_fmac_f32_e32 v55, v34, v185
	v_fmac_f32_e32 v54, v35, v186
	v_fmac_f32_e32 v55, v36, v187
	v_fmac_f32_e32 v54, v37, v188
	v_fmac_f32_e32 v55, v38, v189
	v_fmac_f32_e32 v54, v39, v190
	v_fmac_f32_e32 v55, v40, v191
	v_fmac_f32_e32 v54, v41, v192
	v_add_f32_e32 v50, v55, v54
	s_and_saveexec_b64 s[0:1], s[46:47]
	s_cbranch_execz .LBB0_684
	s_movk_i32 s4, 0x1200
	v_cvt_pk_bf16_f32 v51, v50, s0
	v_mad_u64_u32 v[52:53], s[6:7], v26, s4, v[0:1]
	ds_write_b16 v52, v51 offset:2736
	s_and_b64 exec, exec, vcc
	v_add_u32_e32 v52, s56, v11
	ds_write_b16 v52, v51 offset:38
.LBB0_684:
	s_or_b64 exec, exec, s[0:1]
	v_cmp_eq_u32_e64 s[0:1], 20, v9
	v_cndmask_b32_e64 v51, 0, 1.0, s[0:1]
	s_waitcnt lgkmcnt(1)
	ds_read_b128 v[174:177], v8 offset:5712
	ds_read_b128 v[178:181], v8 offset:5728
	ds_read_b128 v[182:185], v8 offset:5744
	ds_read_b128 v[186:189], v8 offset:5760
	ds_read_b128 v[190:193], v8 offset:5776
	ds_read_b128 v[194:197], v8 offset:5792
	v_fmac_f32_e32 v51, v10, v132
	v_fma_f32 v57, v7, v133, 0
	v_fmac_f32_e32 v51, v13, v134
	v_fmac_f32_e32 v57, v12, v135
	v_fmac_f32_e32 v51, v15, v136
	v_fmac_f32_e32 v57, v14, v137
	v_fmac_f32_e32 v51, v17, v138
	v_fmac_f32_e32 v57, v16, v139
	v_fmac_f32_e32 v51, v31, v140
	v_fmac_f32_e32 v57, v32, v141
	v_fmac_f32_e32 v51, v33, v142
	v_fmac_f32_e32 v57, v34, v143
	v_fmac_f32_e32 v51, v35, v144
	v_fmac_f32_e32 v57, v36, v145
	v_fmac_f32_e32 v51, v37, v146
	v_fmac_f32_e32 v57, v38, v147
	v_fmac_f32_e32 v51, v39, v148
	v_fmac_f32_e32 v57, v40, v149
	v_fmac_f32_e32 v51, v41, v150
	v_fmac_f32_e32 v57, v50, v151
	v_add_f32_e32 v51, v57, v51
	s_and_saveexec_b64 s[0:1], s[46:47]
	s_cbranch_execz .LBB0_687
	s_movk_i32 s4, 0x1200
	v_cvt_pk_bf16_f32 v52, v51, s0
	v_mad_u64_u32 v[54:55], s[6:7], v26, s4, v[0:1]
	ds_write_b16 v54, v52 offset:2880
	s_and_b64 exec, exec, vcc
	v_add_u32_e32 v53, s56, v11
	ds_write_b16 v53, v52 offset:40
; #define LAS __attribute__((address_space(3)))
; __device__ __forceinline__ unsigned f2bf(float f) { return (unsigned)__builtin_bit_cast(unsigned short, (__bf16)f); }
; __device__ __forceinline__ void rwkv_pre(LAS unsigned char* lds, const MixBufs& B, bf16_t* rq, int L, int u, int unext, RwRaw& R) {
;     ...
;     if (w < 2) {
;         const int ob = w * 32, j = lane & 31;
;         float T[32];
;         int zv = 0; asm volatile("" : "+v"(zv));
;         const LAS float* Lfz = Lf + zv + ob * 68 + ob;
; #pragma unroll
;         for (int t = 0; t < 32; ++t) {
;             float a0 = (t == j) ? 1.f : 0.f, a1 = 0.f;
; #pragma unroll
;             for (int s4 = 0; s4 < (t + 3) / 4; ++s4) {
;                 const f32x4 l = *(const LAS f32x4*)(Lfz + t * 68 + s4 * 4);
; #pragma unroll
;                 for (int e2 = 0; e2 < 4; ++e2) { const int s_ = s4 * 4 + e2; if (s_ < t) { if (e2 & 1) a1 += l[e2] * T[s_]; else a0 += l[e2] * T[s_]; } }
;             }
;             T[t] = a0 + a1;
;             if (lane < 32) {
;                 Tm[(ob + t) * RL + ob + j] = (bf16_t)f2bf(T[t]);
;                 if (w == 0) T11T[j * 40 + t] = (bf16_t)f2bf(T[t]);
;             }
;         }
.LBB0_687:
	s_or_b64 exec, exec, s[0:1]
	v_cmp_eq_u32_e64 s[0:1], 21, v9
	v_cndmask_b32_e64 v57, 0, 1.0, s[0:1]
	s_waitcnt lgkmcnt(1)
	ds_read_b128 v[132:135], v8 offset:5984
	ds_read_b128 v[136:139], v8 offset:6000
	ds_read_b128 v[140:143], v8 offset:6016
	ds_read_b128 v[144:147], v8 offset:6032
	ds_read_b128 v[148:151], v8 offset:6048
	ds_read_b128 v[166:169], v8 offset:6064
	v_fmac_f32_e32 v57, v10, v174
	v_fma_f32 v67, v7, v175, 0
	v_fmac_f32_e32 v57, v13, v176
	v_fmac_f32_e32 v67, v12, v177
	v_fmac_f32_e32 v57, v15, v178
	v_fmac_f32_e32 v67, v14, v179
	v_fmac_f32_e32 v57, v17, v180
	v_fmac_f32_e32 v67, v16, v181
	v_fmac_f32_e32 v57, v31, v182
	v_fmac_f32_e32 v67, v32, v183
	v_fmac_f32_e32 v57, v33, v184
	v_fmac_f32_e32 v67, v34, v185
	v_fmac_f32_e32 v57, v35, v186
	v_fmac_f32_e32 v67, v36, v187
	v_fmac_f32_e32 v57, v37, v188
	v_fmac_f32_e32 v67, v38, v189
	v_fmac_f32_e32 v57, v39, v190
	v_fmac_f32_e32 v67, v40, v191
	v_fmac_f32_e32 v57, v41, v192
	v_fmac_f32_e32 v67, v50, v193
	v_fmac_f32_e32 v57, v51, v194
	v_add_f32_e32 v52, v67, v57
	s_and_saveexec_b64 s[0:1], s[46:47]
	s_cbranch_execz .LBB0_690
	s_movk_i32 s4, 0x1200
	v_cvt_pk_bf16_f32 v53, v52, s0
	v_mad_u64_u32 v[54:55], s[6:7], v26, s4, v[0:1]
	ds_write_b16 v54, v53 offset:3024
	s_and_b64 exec, exec, vcc
	v_add_u32_e32 v54, s56, v11
	ds_write_b16 v54, v53 offset:42
.LBB0_690:
	s_or_b64 exec, exec, s[0:1]
	v_cmp_eq_u32_e64 s[0:1], 22, v9
	v_cndmask_b32_e64 v53, 0, 1.0, s[0:1]
	s_waitcnt lgkmcnt(1)
	ds_read_b128 v[174:177], v8 offset:6256
	ds_read_b128 v[178:181], v8 offset:6272
	ds_read_b128 v[182:185], v8 offset:6288
	ds_read_b128 v[186:189], v8 offset:6304
	ds_read_b128 v[190:193], v8 offset:6320
	ds_read_b128 v[194:197], v8 offset:6336
	v_fmac_f32_e32 v53, v10, v132
	v_fma_f32 v54, v7, v133, 0
	v_fmac_f32_e32 v53, v13, v134
	v_fmac_f32_e32 v54, v12, v135
	v_fmac_f32_e32 v53, v15, v136
	v_fmac_f32_e32 v54, v14, v137
	v_fmac_f32_e32 v53, v17, v138
	v_fmac_f32_e32 v54, v16, v139
	v_fmac_f32_e32 v53, v31, v140
	v_fmac_f32_e32 v54, v32, v141
	v_fmac_f32_e32 v53, v33, v142
	v_fmac_f32_e32 v54, v34, v143
	v_fmac_f32_e32 v53, v35, v144
	v_fmac_f32_e32 v54, v36, v145
	v_fmac_f32_e32 v53, v37, v146
	v_fmac_f32_e32 v54, v38, v147
	v_fmac_f32_e32 v53, v39, v148
	v_fmac_f32_e32 v54, v40, v149
	v_fmac_f32_e32 v53, v41, v150
	v_fmac_f32_e32 v54, v50, v151
	v_fmac_f32_e32 v53, v51, v166
	v_fmac_f32_e32 v54, v52, v167
	v_add_f32_e32 v53, v54, v53
	s_and_saveexec_b64 s[0:1], s[46:47]
	s_cbranch_execz .LBB0_693
	s_movk_i32 s4, 0x1200
	v_cvt_pk_bf16_f32 v54, v53, s0
	v_mad_u64_u32 v[68:69], s[6:7], v26, s4, v[0:1]
	ds_write_b16 v68, v54 offset:3168
	s_and_b64 exec, exec, vcc
	v_add_u32_e32 v55, s56, v11
	ds_write_b16 v55, v54 offset:44
.LBB0_693:
	s_or_b64 exec, exec, s[0:1]
	v_cmp_eq_u32_e64 s[0:1], 23, v9
	v_cndmask_b32_e64 v54, 0, 1.0, s[0:1]
	s_waitcnt lgkmcnt(1)
	ds_read_b128 v[132:135], v8 offset:6528
	ds_read_b128 v[136:139], v8 offset:6544
	ds_read_b128 v[140:143], v8 offset:6560
	ds_read_b128 v[144:147], v8 offset:6576
	ds_read_b128 v[148:151], v8 offset:6592
	ds_read_b128 v[166:169], v8 offset:6608
	v_fmac_f32_e32 v54, v10, v174
	v_fma_f32 v55, v7, v175, 0
	v_fmac_f32_e32 v54, v13, v176
	v_fmac_f32_e32 v55, v12, v177
	v_fmac_f32_e32 v54, v15, v178
	v_fmac_f32_e32 v55, v14, v179
	v_fmac_f32_e32 v54, v17, v180
	v_fmac_f32_e32 v55, v16, v181
	v_fmac_f32_e32 v54, v31, v182
	v_fmac_f32_e32 v55, v32, v183
	v_fmac_f32_e32 v54, v33, v184
	v_fmac_f32_e32 v55, v34, v185
	v_fmac_f32_e32 v54, v35, v186
	v_fmac_f32_e32 v55, v36, v187
	v_fmac_f32_e32 v54, v37, v188
	v_fmac_f32_e32 v55, v38, v189
	v_fmac_f32_e32 v54, v39, v190
	v_fmac_f32_e32 v55, v40, v191
	v_fmac_f32_e32 v54, v41, v192
	v_fmac_f32_e32 v55, v50, v193
	v_fmac_f32_e32 v54, v51, v194
	v_fmac_f32_e32 v55, v52, v195
	v_fmac_f32_e32 v54, v53, v196
	v_add_f32_e32 v54, v55, v54
	s_and_saveexec_b64 s[0:1], s[46:47]
	s_cbranch_execz .LBB0_696
	s_movk_i32 s4, 0x1200
	v_cvt_pk_bf16_f32 v55, v54, s0
	v_mad_u64_u32 v[68:69], s[6:7], v26, s4, v[0:1]
	ds_write_b16 v68, v55 offset:3312
	s_and_b64 exec, exec, vcc
	v_add_u32_e32 v57, s56, v11
	ds_write_b16 v57, v55 offset:46
.LBB0_696:
	s_or_b64 exec, exec, s[0:1]
	v_cmp_eq_u32_e64 s[0:1], 24, v9
	v_cndmask_b32_e64 v55, 0, 1.0, s[0:1]
	s_waitcnt lgkmcnt(1)
	ds_read_b128 v[174:177], v8 offset:6800
	ds_read_b128 v[178:181], v8 offset:6816
	ds_read_b128 v[182:185], v8 offset:6832
	ds_read_b128 v[186:189], v8 offset:6848
	ds_read_b128 v[190:193], v8 offset:6864
	ds_read_b128 v[194:197], v8 offset:6880
	ds_read_b128 v[198:201], v8 offset:6896
	v_fmac_f32_e32 v55, v10, v132
	v_fma_f32 v57, v7, v133, 0
	v_fmac_f32_e32 v55, v13, v134
	v_fmac_f32_e32 v57, v12, v135
	v_fmac_f32_e32 v55, v15, v136
	v_fmac_f32_e32 v57, v14, v137
	v_fmac_f32_e32 v55, v17, v138
	v_fmac_f32_e32 v57, v16, v139
	v_fmac_f32_e32 v55, v31, v140
	v_fmac_f32_e32 v57, v32, v141
	v_fmac_f32_e32 v55, v33, v142
	v_fmac_f32_e32 v57, v34, v143
	v_fmac_f32_e32 v55, v35, v144
	v_fmac_f32_e32 v57, v36, v145
	v_fmac_f32_e32 v55, v37, v146
	v_fmac_f32_e32 v57, v38, v147
	v_fmac_f32_e32 v55, v39, v148
	v_fmac_f32_e32 v57, v40, v149
	v_fmac_f32_e32 v55, v41, v150
	v_fmac_f32_e32 v57, v50, v151
	v_fmac_f32_e32 v55, v51, v166
	v_fmac_f32_e32 v57, v52, v167
	v_fmac_f32_e32 v55, v53, v168
	v_fmac_f32_e32 v57, v54, v169
	v_add_f32_e32 v55, v57, v55
	s_and_saveexec_b64 s[0:1], s[46:47]
	s_cbranch_execz .LBB0_699
	s_movk_i32 s4, 0x1200
	v_cvt_pk_bf16_f32 v57, v55, s0
	v_mad_u64_u32 v[68:69], s[6:7], v26, s4, v[0:1]
	ds_write_b16 v68, v57 offset:3456
	s_and_b64 exec, exec, vcc
	v_add_u32_e32 v67, s56, v11
	ds_write_b16 v67, v57 offset:48
; #define LAS __attribute__((address_space(3)))
; __device__ __forceinline__ unsigned f2bf(float f) { return (unsigned)__builtin_bit_cast(unsigned short, (__bf16)f); }
; __device__ __forceinline__ void rwkv_pre(LAS unsigned char* lds, const MixBufs& B, bf16_t* rq, int L, int u, int unext, RwRaw& R) {
;     ...
; #pragma unroll
;         for (int t = 0; t < 32; ++t) {
;             float a0 = (t == j) ? 1.f : 0.f, a1 = 0.f;
; #pragma unroll
;             for (int s4 = 0; s4 < (t + 3) / 4; ++s4) {
;                 const f32x4 l = *(const LAS f32x4*)(Lfz + t * 68 + s4 * 4);
; #pragma unroll
;                 for (int e2 = 0; e2 < 4; ++e2) { const int s_ = s4 * 4 + e2; if (s_ < t) { if (e2 & 1) a1 += l[e2] * T[s_]; else a0 += l[e2] * T[s_]; } }
;             }
;             T[t] = a0 + a1;
;             if (lane < 32) {
;                 Tm[(ob + t) * RL + ob + j] = (bf16_t)f2bf(T[t]);
;                 if (w == 0) T11T[j * 40 + t] = (bf16_t)f2bf(T[t]);
;             }
;         }
.LBB0_699:
	s_or_b64 exec, exec, s[0:1]
	v_cmp_eq_u32_e64 s[0:1], 25, v9
	v_cndmask_b32_e64 v57, 0, 1.0, s[0:1]
	s_waitcnt lgkmcnt(1)
	ds_read_b128 v[132:135], v8 offset:7072
	ds_read_b128 v[136:139], v8 offset:7088
	ds_read_b128 v[140:143], v8 offset:7104
	ds_read_b128 v[144:147], v8 offset:7120
	ds_read_b128 v[148:151], v8 offset:7136
	ds_read_b128 v[166:169], v8 offset:7152
	ds_read_b128 v[170:173], v8 offset:7168
	v_fmac_f32_e32 v57, v10, v174
	v_fma_f32 v67, v7, v175, 0
	v_fmac_f32_e32 v57, v13, v176
	v_fmac_f32_e32 v67, v12, v177
	v_fmac_f32_e32 v57, v15, v178
	v_fmac_f32_e32 v67, v14, v179
	v_fmac_f32_e32 v57, v17, v180
	v_fmac_f32_e32 v67, v16, v181
	v_fmac_f32_e32 v57, v31, v182
	v_fmac_f32_e32 v67, v32, v183
	v_fmac_f32_e32 v57, v33, v184
	v_fmac_f32_e32 v67, v34, v185
	v_fmac_f32_e32 v57, v35, v186
	v_fmac_f32_e32 v67, v36, v187
	v_fmac_f32_e32 v57, v37, v188
	v_fmac_f32_e32 v67, v38, v189
	v_fmac_f32_e32 v57, v39, v190
	v_fmac_f32_e32 v67, v40, v191
	v_fmac_f32_e32 v57, v41, v192
	v_fmac_f32_e32 v67, v50, v193
	v_fmac_f32_e32 v57, v51, v194
	v_fmac_f32_e32 v67, v52, v195
	v_fmac_f32_e32 v57, v53, v196
	v_fmac_f32_e32 v67, v54, v197
	v_fmac_f32_e32 v57, v55, v198
	v_add_f32_e32 v57, v67, v57
	s_and_saveexec_b64 s[0:1], s[46:47]
	s_cbranch_execz .LBB0_702
	s_movk_i32 s4, 0x1200
	v_cvt_pk_bf16_f32 v67, v57, s0
	v_mad_u64_u32 v[68:69], s[6:7], v26, s4, v[0:1]
	ds_write_b16 v68, v67 offset:3600
	s_and_b64 exec, exec, vcc
	v_add_u32_e32 v68, s56, v11
	ds_write_b16 v68, v67 offset:50
.LBB0_702:
	s_or_b64 exec, exec, s[0:1]
	v_cmp_eq_u32_e64 s[0:1], 26, v9
	v_cndmask_b32_e64 v67, 0, 1.0, s[0:1]
	s_waitcnt lgkmcnt(1)
	ds_read_b128 v[174:177], v8 offset:7344
	ds_read_b128 v[178:181], v8 offset:7360
	ds_read_b128 v[182:185], v8 offset:7376
	ds_read_b128 v[186:189], v8 offset:7392
	ds_read_b128 v[190:193], v8 offset:7408
	ds_read_b128 v[194:197], v8 offset:7424
	ds_read_b128 v[198:201], v8 offset:7440
	v_fmac_f32_e32 v67, v10, v132
	v_fma_f32 v84, v7, v133, 0
	v_fmac_f32_e32 v67, v13, v134
	v_fmac_f32_e32 v84, v12, v135
	v_fmac_f32_e32 v67, v15, v136
	v_fmac_f32_e32 v84, v14, v137
	v_fmac_f32_e32 v67, v17, v138
	v_fmac_f32_e32 v84, v16, v139
	v_fmac_f32_e32 v67, v31, v140
	v_fmac_f32_e32 v84, v32, v141
	v_fmac_f32_e32 v67, v33, v142
	v_fmac_f32_e32 v84, v34, v143
	v_fmac_f32_e32 v67, v35, v144
	v_fmac_f32_e32 v84, v36, v145
	v_fmac_f32_e32 v67, v37, v146
	v_fmac_f32_e32 v84, v38, v147
	v_fmac_f32_e32 v67, v39, v148
	v_fmac_f32_e32 v84, v40, v149
	v_fmac_f32_e32 v67, v41, v150
	v_fmac_f32_e32 v84, v50, v151
	v_fmac_f32_e32 v67, v51, v166
	v_fmac_f32_e32 v84, v52, v167
	v_fmac_f32_e32 v67, v53, v168
	v_fmac_f32_e32 v84, v54, v169
	v_fmac_f32_e32 v67, v55, v170
	v_fmac_f32_e32 v84, v57, v171
	v_add_f32_e32 v67, v84, v67
	s_and_saveexec_b64 s[0:1], s[46:47]
	s_cbranch_execz .LBB0_705
	s_movk_i32 s4, 0x1200
	v_cvt_pk_bf16_f32 v68, v67, s0
	v_mad_u64_u32 v[70:71], s[6:7], v26, s4, v[0:1]
	ds_write_b16 v70, v68 offset:3744
	s_and_b64 exec, exec, vcc
	v_add_u32_e32 v69, s56, v11
	ds_write_b16 v69, v68 offset:52
.LBB0_705:
	s_or_b64 exec, exec, s[0:1]
	v_cmp_eq_u32_e64 s[0:1], 27, v9
	v_cndmask_b32_e64 v84, 0, 1.0, s[0:1]
	s_waitcnt lgkmcnt(1)
	ds_read_b128 v[132:135], v8 offset:7616
	ds_read_b128 v[136:139], v8 offset:7632
	ds_read_b128 v[140:143], v8 offset:7648
	ds_read_b128 v[144:147], v8 offset:7664
	ds_read_b128 v[148:151], v8 offset:7680
	ds_read_b128 v[166:169], v8 offset:7696
	ds_read_b128 v[170:173], v8 offset:7712
	v_fmac_f32_e32 v84, v10, v174
	v_fma_f32 v85, v7, v175, 0
	v_fmac_f32_e32 v84, v13, v176
	v_fmac_f32_e32 v85, v12, v177
	v_fmac_f32_e32 v84, v15, v178
	v_fmac_f32_e32 v85, v14, v179
	v_fmac_f32_e32 v84, v17, v180
	v_fmac_f32_e32 v85, v16, v181
	v_fmac_f32_e32 v84, v31, v182
	v_fmac_f32_e32 v85, v32, v183
	v_fmac_f32_e32 v84, v33, v184
	v_fmac_f32_e32 v85, v34, v185
	v_fmac_f32_e32 v84, v35, v186
	v_fmac_f32_e32 v85, v36, v187
	v_fmac_f32_e32 v84, v37, v188
	v_fmac_f32_e32 v85, v38, v189
	v_fmac_f32_e32 v84, v39, v190
	v_fmac_f32_e32 v85, v40, v191
	v_fmac_f32_e32 v84, v41, v192
	v_fmac_f32_e32 v85, v50, v193
	v_fmac_f32_e32 v84, v51, v194
	v_fmac_f32_e32 v85, v52, v195
	v_fmac_f32_e32 v84, v53, v196
	v_fmac_f32_e32 v85, v54, v197
	v_fmac_f32_e32 v84, v55, v198
	v_fmac_f32_e32 v85, v57, v199
	v_fmac_f32_e32 v84, v67, v200
	v_add_f32_e32 v68, v85, v84
	s_and_saveexec_b64 s[0:1], s[46:47]
	s_cbranch_execz .LBB0_708
	s_movk_i32 s4, 0x1200
	v_cvt_pk_bf16_f32 v69, v68, s0
	v_mad_u64_u32 v[70:71], s[6:7], v26, s4, v[0:1]
	ds_write_b16 v70, v69 offset:3888
	s_and_b64 exec, exec, vcc
	v_add_u32_e32 v70, s56, v11
	ds_write_b16 v70, v69 offset:54
.LBB0_708:
	s_or_b64 exec, exec, s[0:1]
	v_cmp_eq_u32_e64 s[0:1], 28, v9
	v_cndmask_b32_e64 v69, 0, 1.0, s[0:1]
	s_waitcnt lgkmcnt(1)
	v_fmac_f32_e32 v69, v10, v132
	v_fma_f32 v86, v7, v133, 0
	v_fmac_f32_e32 v69, v13, v134
	v_fmac_f32_e32 v86, v12, v135
	v_fmac_f32_e32 v69, v15, v136
	v_fmac_f32_e32 v86, v14, v137
	v_fmac_f32_e32 v69, v17, v138
	v_fmac_f32_e32 v86, v16, v139
	v_fmac_f32_e32 v69, v31, v140
	v_fmac_f32_e32 v86, v32, v141
	v_fmac_f32_e32 v69, v33, v142
	v_fmac_f32_e32 v86, v34, v143
	v_fmac_f32_e32 v69, v35, v144
	v_fmac_f32_e32 v86, v36, v145
	v_fmac_f32_e32 v69, v37, v146
	v_fmac_f32_e32 v86, v38, v147
	v_fmac_f32_e32 v69, v39, v148
	v_fmac_f32_e32 v86, v40, v149
	v_fmac_f32_e32 v69, v41, v150
	v_fmac_f32_e32 v86, v50, v151
	v_fmac_f32_e32 v69, v51, v166
	v_fmac_f32_e32 v86, v52, v167
	v_fmac_f32_e32 v69, v53, v168
	v_fmac_f32_e32 v86, v54, v169
	v_fmac_f32_e32 v69, v55, v170
	v_fmac_f32_e32 v86, v57, v171
	v_fmac_f32_e32 v69, v67, v172
	v_fmac_f32_e32 v86, v68, v173
	v_add_f32_e32 v69, v86, v69
	s_and_saveexec_b64 s[0:1], s[46:47]
	s_cbranch_execz .LBB0_711
	s_movk_i32 s4, 0x1200
	v_cvt_pk_bf16_f32 v70, v69, s0
	v_mad_u64_u32 v[72:73], s[6:7], v26, s4, v[0:1]
	ds_write_b16 v72, v70 offset:4032
	s_and_b64 exec, exec, vcc
	v_add_u32_e32 v71, s56, v11
	ds_write_b16 v71, v70 offset:56

; #define LAS __attribute__((address_space(3)))
; __device__ __forceinline__ unsigned f2bf(float f) { return (unsigned)__builtin_bit_cast(unsigned short, (__bf16)f); }
; __device__ __forceinline__ void rwkv_pre(LAS unsigned char* lds, const MixBufs& B, bf16_t* rq, int L, int u, int unext, RwRaw& R) {
;     ...
; #pragma unroll
;         for (int t = 0; t < 32; ++t) {
;             float a0 = (t == j) ? 1.f : 0.f, a1 = 0.f;
; #pragma unroll
;             for (int s4 = 0; s4 < (t + 3) / 4; ++s4) {
;                 const f32x4 l = *(const LAS f32x4*)(Lfz + t * 68 + s4 * 4);
; #pragma unroll
;                 for (int e2 = 0; e2 < 4; ++e2) { const int s_ = s4 * 4 + e2; if (s_ < t) { if (e2 & 1) a1 += l[e2] * T[s_]; else a0 += l[e2] * T[s_]; } }
;             }
;             T[t] = a0 + a1;
;             if (lane < 32) {
;                 Tm[(ob + t) * RL + ob + j] = (bf16_t)f2bf(T[t]);
;                 if (w == 0) T11T[j * 40 + t] = (bf16_t)f2bf(T[t]);
;             }
;         }
.LBB0_771:
	s_or_b64 exec, exec, s[0:1]
	ds_read_b128 v[12:15], v9 offset:544
	v_cmp_eq_u32_e64 s[0:1], 2, v10
	s_waitcnt lgkmcnt(0)
	ds_read_b128 v[174:177], v9 offset:816
	s_nop 0
	v_cndmask_b32_e64 v14, 0, 1.0, s[0:1]
	v_fmac_f32_e32 v14, v11, v12
	v_fma_f32 v12, v8, v13, 0
	v_add_f32_e32 v13, v12, v14
	s_and_saveexec_b64 s[0:1], s[44:45]
	s_cbranch_execz .LBB0_774
	s_movk_i32 s4, 0x1200
	v_cvt_pk_bf16_f32 v12, v13, s0
	v_mad_u64_u32 v[14:15], s[6:7], v26, s4, v[0:1]
	ds_write_b16 v14, v12 offset:288
	s_and_b64 exec, exec, vcc
	s_add_i32 s5, 0, 0x18c00
	v_add_u32_e32 v14, s5, v7
	ds_write_b16 v14, v12 offset:4
.LBB0_774:
	s_or_b64 exec, exec, s[0:1]
	v_cmp_eq_u32_e64 s[0:1], 3, v10
	s_nop 1
	v_cndmask_b32_e64 v12, 0, 1.0, s[0:1]
	s_waitcnt lgkmcnt(1)
	ds_read_b128 v[132:135], v9 offset:1088
	v_fmac_f32_e32 v12, v11, v174
	v_fma_f32 v14, v8, v175, 0
	v_fmac_f32_e32 v12, v13, v176
	v_add_f32_e32 v12, v14, v12
	s_and_saveexec_b64 s[0:1], s[44:45]
	s_cbranch_execz .LBB0_777
	s_movk_i32 s4, 0x1200
	v_cvt_pk_bf16_f32 v14, v12, s0
	v_mad_u64_u32 v[16:17], s[6:7], v26, s4, v[0:1]
	ds_write_b16 v16, v14 offset:432
	s_and_b64 exec, exec, vcc
	s_add_i32 s5, 0, 0x18c00
	v_add_u32_e32 v15, s5, v7
	ds_write_b16 v15, v14 offset:6
.LBB0_777:
	s_or_b64 exec, exec, s[0:1]
	v_cmp_eq_u32_e64 s[0:1], 4, v10
	s_nop 1
	v_cndmask_b32_e64 v31, 0, 1.0, s[0:1]
	s_waitcnt lgkmcnt(1)
	ds_read_b128 v[174:177], v9 offset:1360
	ds_read_b128 v[178:181], v9 offset:1376
	v_fmac_f32_e32 v31, v11, v132
	v_fma_f32 v14, v8, v133, 0
	v_fmac_f32_e32 v31, v13, v134
	v_fmac_f32_e32 v14, v12, v135
	v_add_f32_e32 v15, v14, v31
	s_and_saveexec_b64 s[0:1], s[44:45]
	s_cbranch_execz .LBB0_780
	s_movk_i32 s4, 0x1200
	v_cvt_pk_bf16_f32 v14, v15, s0
	v_mad_u64_u32 v[16:17], s[6:7], v26, s4, v[0:1]
	ds_write_b16 v16, v14 offset:576
	s_and_b64 exec, exec, vcc
	s_add_i32 s5, 0, 0x18c00
	v_add_u32_e32 v16, s5, v7
	ds_write_b16 v16, v14 offset:8
.LBB0_780:
	s_or_b64 exec, exec, s[0:1]
	v_cmp_eq_u32_e64 s[0:1], 5, v10
	s_waitcnt lgkmcnt(1)
	ds_read_b128 v[132:135], v9 offset:1632
	ds_read_b128 v[136:139], v9 offset:1648
	v_fma_f32 v16, v8, v175, 0
	v_cndmask_b32_e64 v14, 0, 1.0, s[0:1]
	v_fmac_f32_e32 v14, v11, v174
	v_fmac_f32_e32 v14, v13, v176
	v_fmac_f32_e32 v16, v12, v177
	v_fmac_f32_e32 v14, v15, v178
	v_add_f32_e32 v14, v16, v14
	s_and_saveexec_b64 s[0:1], s[44:45]
	s_cbranch_execz .LBB0_783
	s_movk_i32 s4, 0x1200
	v_cvt_pk_bf16_f32 v16, v14, s0
	v_mad_u64_u32 v[32:33], s[6:7], v26, s4, v[0:1]
	ds_write_b16 v32, v16 offset:720
	s_and_b64 exec, exec, vcc
	s_add_i32 s5, 0, 0x18c00
	v_add_u32_e32 v17, s5, v7
	ds_write_b16 v17, v16 offset:10
.LBB0_783:
	s_or_b64 exec, exec, s[0:1]
	v_cmp_eq_u32_e64 s[0:1], 6, v10
	s_waitcnt lgkmcnt(1)
	ds_read_b128 v[174:177], v9 offset:1904
	ds_read_b128 v[178:181], v9 offset:1920
	v_fma_f32 v17, v8, v133, 0
	v_cndmask_b32_e64 v16, 0, 1.0, s[0:1]
	v_fmac_f32_e32 v16, v11, v132
	v_fmac_f32_e32 v16, v13, v134
	v_fmac_f32_e32 v17, v12, v135
	v_fmac_f32_e32 v16, v15, v136
	v_fmac_f32_e32 v17, v14, v137
	v_add_f32_e32 v16, v17, v16
	s_and_saveexec_b64 s[0:1], s[44:45]
	s_cbranch_execz .LBB0_786
	s_movk_i32 s4, 0x1200
	v_cvt_pk_bf16_f32 v17, v16, s0
	v_mad_u64_u32 v[32:33], s[6:7], v26, s4, v[0:1]
	ds_write_b16 v32, v17 offset:864
	s_and_b64 exec, exec, vcc
	s_add_i32 s5, 0, 0x18c00
	v_add_u32_e32 v31, s5, v7
	ds_write_b16 v31, v17 offset:12
.LBB0_786:
	s_or_b64 exec, exec, s[0:1]
	v_cmp_eq_u32_e64 s[0:1], 7, v10
	s_waitcnt lgkmcnt(1)
	ds_read_b128 v[132:135], v9 offset:2176
	ds_read_b128 v[136:139], v9 offset:2192
	v_fma_f32 v31, v8, v175, 0
	v_cndmask_b32_e64 v17, 0, 1.0, s[0:1]
	v_fmac_f32_e32 v17, v11, v174
	v_fmac_f32_e32 v17, v13, v176
	v_fmac_f32_e32 v31, v12, v177
	v_fmac_f32_e32 v17, v15, v178
	v_fmac_f32_e32 v31, v14, v179
	v_fmac_f32_e32 v17, v16, v180
	v_add_f32_e32 v17, v31, v17
	s_and_saveexec_b64 s[0:1], s[44:45]
	s_cbranch_execz .LBB0_789
	s_movk_i32 s4, 0x1200
	v_cvt_pk_bf16_f32 v31, v17, s0
	v_mad_u64_u32 v[32:33], s[6:7], v26, s4, v[0:1]
	ds_write_b16 v32, v31 offset:1008
	s_and_b64 exec, exec, vcc
	s_add_i32 s5, 0, 0x18c00
	v_add_u32_e32 v32, s5, v7
	ds_write_b16 v32, v31 offset:14
.LBB0_789:
	s_or_b64 exec, exec, s[0:1]
	v_cmp_eq_u32_e64 s[0:1], 8, v10
	s_nop 1
	v_cndmask_b32_e64 v31, 0, 1.0, s[0:1]
	s_waitcnt lgkmcnt(1)
	ds_read_b128 v[174:177], v9 offset:2448
	ds_read_b128 v[178:181], v9 offset:2464
	ds_read_b128 v[182:185], v9 offset:2480
	v_fmac_f32_e32 v31, v11, v132
	v_fma_f32 v32, v8, v133, 0
	v_fmac_f32_e32 v31, v13, v134
	v_fmac_f32_e32 v32, v12, v135
	v_fmac_f32_e32 v31, v15, v136
	v_fmac_f32_e32 v32, v14, v137
	v_fmac_f32_e32 v31, v16, v138
	v_fmac_f32_e32 v32, v17, v139
	v_add_f32_e32 v31, v32, v31
	s_and_saveexec_b64 s[0:1], s[44:45]
	s_cbranch_execz .LBB0_792
	s_movk_i32 s4, 0x1200
	v_cvt_pk_bf16_f32 v32, v31, s0
	v_mad_u64_u32 v[34:35], s[6:7], v26, s4, v[0:1]
	ds_write_b16 v34, v32 offset:1152
	s_and_b64 exec, exec, vcc
	s_add_i32 s5, 0, 0x18c00
	v_add_u32_e32 v33, s5, v7
	ds_write_b16 v33, v32 offset:16
.LBB0_792:
	s_or_b64 exec, exec, s[0:1]
	v_cmp_eq_u32_e64 s[0:1], 9, v10
	s_nop 1
	v_cndmask_b32_e64 v40, 0, 1.0, s[0:1]
	s_waitcnt lgkmcnt(1)
	ds_read_b128 v[132:135], v9 offset:2720
	ds_read_b128 v[136:139], v9 offset:2736
	ds_read_b128 v[140:143], v9 offset:2752
	v_fmac_f32_e32 v40, v11, v174
	v_fma_f32 v32, v8, v175, 0
	v_fmac_f32_e32 v40, v13, v176
	v_fmac_f32_e32 v32, v12, v177
	v_fmac_f32_e32 v40, v15, v178
	v_fmac_f32_e32 v32, v14, v179
	v_fmac_f32_e32 v40, v16, v180
	v_fmac_f32_e32 v32, v17, v181
	v_fmac_f32_e32 v40, v31, v182
	v_add_f32_e32 v32, v32, v40
	s_and_saveexec_b64 s[0:1], s[44:45]
	s_cbranch_execz .LBB0_795
	s_movk_i32 s4, 0x1200
	v_cvt_pk_bf16_f32 v33, v32, s0
	v_mad_u64_u32 v[34:35], s[6:7], v26, s4, v[0:1]
	ds_write_b16 v34, v33 offset:1296
	s_and_b64 exec, exec, vcc
	s_add_i32 s5, 0, 0x18c00
	v_add_u32_e32 v34, s5, v7
	ds_write_b16 v34, v33 offset:18
; #define LAS __attribute__((address_space(3)))
; __device__ __forceinline__ unsigned f2bf(float f) { return (unsigned)__builtin_bit_cast(unsigned short, (__bf16)f); }
; __device__ __forceinline__ void rwkv_pre(LAS unsigned char* lds, const MixBufs& B, bf16_t* rq, int L, int u, int unext, RwRaw& R) {
;     ...
; #pragma unroll
;         for (int t = 0; t < 32; ++t) {
;             float a0 = (t == j) ? 1.f : 0.f, a1 = 0.f;
; #pragma unroll
;             for (int s4 = 0; s4 < (t + 3) / 4; ++s4) {
;                 const f32x4 l = *(const LAS f32x4*)(Lfz + t * 68 + s4 * 4);
; #pragma unroll
;                 for (int e2 = 0; e2 < 4; ++e2) { const int s_ = s4 * 4 + e2; if (s_ < t) { if (e2 & 1) a1 += l[e2] * T[s_]; else a0 += l[e2] * T[s_]; } }
;             }
;             T[t] = a0 + a1;
;             if (lane < 32) {
;                 Tm[(ob + t) * RL + ob + j] = (bf16_t)f2bf(T[t]);
;                 if (w == 0) T11T[j * 40 + t] = (bf16_t)f2bf(T[t]);
;             }
;         }
.LBB0_795:
	s_or_b64 exec, exec, s[0:1]
	v_cmp_eq_u32_e64 s[0:1], 10, v10
	s_nop 1
	v_cndmask_b32_e64 v33, 0, 1.0, s[0:1]
	s_waitcnt lgkmcnt(1)
	ds_read_b128 v[174:177], v9 offset:2992
	ds_read_b128 v[178:181], v9 offset:3008
	ds_read_b128 v[182:185], v9 offset:3024
	v_fmac_f32_e32 v33, v11, v132
	v_fma_f32 v34, v8, v133, 0
	v_fmac_f32_e32 v33, v13, v134
	v_fmac_f32_e32 v34, v12, v135
	v_fmac_f32_e32 v33, v15, v136
	v_fmac_f32_e32 v34, v14, v137
	v_fmac_f32_e32 v33, v16, v138
	v_fmac_f32_e32 v34, v17, v139
	v_fmac_f32_e32 v33, v31, v140
	v_fmac_f32_e32 v34, v32, v141
	v_add_f32_e32 v33, v34, v33
	s_and_saveexec_b64 s[0:1], s[44:45]
	s_cbranch_execz .LBB0_798
	s_movk_i32 s4, 0x1200
	v_cvt_pk_bf16_f32 v34, v33, s0
	v_mad_u64_u32 v[36:37], s[6:7], v26, s4, v[0:1]
	ds_write_b16 v36, v34 offset:1440
	s_and_b64 exec, exec, vcc
	s_add_i32 s5, 0, 0x18c00
	v_add_u32_e32 v35, s5, v7
	ds_write_b16 v35, v34 offset:20
.LBB0_798:
	s_or_b64 exec, exec, s[0:1]
	v_cmp_eq_u32_e64 s[0:1], 11, v10
	s_waitcnt lgkmcnt(1)
	ds_read_b128 v[132:135], v9 offset:3264
	ds_read_b128 v[136:139], v9 offset:3280
	ds_read_b128 v[140:143], v9 offset:3296
	s_nop 0
	v_cndmask_b32_e64 v53, 0, 1.0, s[0:1]
	v_fmac_f32_e32 v53, v11, v174
	v_fma_f32 v34, v8, v175, 0
	v_fmac_f32_e32 v53, v13, v176
	v_fmac_f32_e32 v34, v12, v177
	v_fmac_f32_e32 v53, v15, v178
	v_fmac_f32_e32 v34, v14, v179
	v_fmac_f32_e32 v53, v16, v180
	v_fmac_f32_e32 v34, v17, v181
	v_fmac_f32_e32 v53, v31, v182
	v_fmac_f32_e32 v34, v32, v183
	v_fmac_f32_e32 v53, v33, v184
	v_add_f32_e32 v34, v34, v53
	s_and_saveexec_b64 s[0:1], s[44:45]
	s_cbranch_execz .LBB0_801
	s_movk_i32 s4, 0x1200
	v_cvt_pk_bf16_f32 v35, v34, s0
	v_mad_u64_u32 v[36:37], s[6:7], v26, s4, v[0:1]
	ds_write_b16 v36, v35 offset:1584
	s_and_b64 exec, exec, vcc
	s_add_i32 s5, 0, 0x18c00
	v_add_u32_e32 v36, s5, v7
	ds_write_b16 v36, v35 offset:22
.LBB0_801:
	s_or_b64 exec, exec, s[0:1]
	v_cmp_eq_u32_e64 s[0:1], 12, v10
	v_cndmask_b32_e64 v35, 0, 1.0, s[0:1]
	s_waitcnt lgkmcnt(1)
	ds_read_b128 v[174:177], v9 offset:3536
	ds_read_b128 v[178:181], v9 offset:3552
	ds_read_b128 v[182:185], v9 offset:3568
	ds_read_b128 v[186:189], v9 offset:3584
	v_fmac_f32_e32 v35, v11, v132
	v_fma_f32 v36, v8, v133, 0
	v_fmac_f32_e32 v35, v13, v134
	v_fmac_f32_e32 v36, v12, v135
	v_fmac_f32_e32 v35, v15, v136
	v_fmac_f32_e32 v36, v14, v137
	v_fmac_f32_e32 v35, v16, v138
	v_fmac_f32_e32 v36, v17, v139
	v_fmac_f32_e32 v35, v31, v140
	v_fmac_f32_e32 v36, v32, v141
	v_fmac_f32_e32 v35, v33, v142
	v_fmac_f32_e32 v36, v34, v143
	v_add_f32_e32 v35, v36, v35
	s_and_saveexec_b64 s[0:1], s[44:45]
	s_cbranch_execz .LBB0_804
	s_movk_i32 s4, 0x1200
	v_cvt_pk_bf16_f32 v36, v35, s0
	v_mad_u64_u32 v[38:39], s[6:7], v26, s4, v[0:1]
	ds_write_b16 v38, v36 offset:1728
	s_and_b64 exec, exec, vcc
	s_add_i32 s5, 0, 0x18c00
	v_add_u32_e32 v37, s5, v7
	ds_write_b16 v37, v36 offset:24
.LBB0_804:
	s_or_b64 exec, exec, s[0:1]
	v_cmp_eq_u32_e64 s[0:1], 13, v10
	v_cndmask_b32_e64 v40, 0, 1.0, s[0:1]
	s_waitcnt lgkmcnt(1)
	ds_read_b128 v[132:135], v9 offset:3808
	ds_read_b128 v[136:139], v9 offset:3824
	ds_read_b128 v[140:143], v9 offset:3840
	ds_read_b128 v[144:147], v9 offset:3856
	v_fmac_f32_e32 v40, v11, v174
	v_fma_f32 v36, v8, v175, 0
	v_fmac_f32_e32 v40, v13, v176
	v_fmac_f32_e32 v36, v12, v177
	v_fmac_f32_e32 v40, v15, v178
	v_fmac_f32_e32 v36, v14, v179
	v_fmac_f32_e32 v40, v16, v180
	v_fmac_f32_e32 v36, v17, v181
	v_fmac_f32_e32 v40, v31, v182
	v_fmac_f32_e32 v36, v32, v183
	v_fmac_f32_e32 v40, v33, v184
	v_fmac_f32_e32 v36, v34, v185
	v_fmac_f32_e32 v40, v35, v186
	v_add_f32_e32 v36, v36, v40
	s_and_saveexec_b64 s[0:1], s[44:45]
	s_cbranch_execz .LBB0_807
	s_movk_i32 s4, 0x1200
	v_cvt_pk_bf16_f32 v37, v36, s0
	v_mad_u64_u32 v[38:39], s[6:7], v26, s4, v[0:1]
	ds_write_b16 v38, v37 offset:1872
	s_and_b64 exec, exec, vcc
	s_add_i32 s5, 0, 0x18c00
	v_add_u32_e32 v38, s5, v7
	ds_write_b16 v38, v37 offset:26
.LBB0_807:
	s_or_b64 exec, exec, s[0:1]
	v_cmp_eq_u32_e64 s[0:1], 14, v10
	v_cndmask_b32_e64 v37, 0, 1.0, s[0:1]
	s_waitcnt lgkmcnt(1)
	ds_read_b128 v[174:177], v9 offset:4080
	ds_read_b128 v[178:181], v9 offset:4096
	ds_read_b128 v[182:185], v9 offset:4112
	ds_read_b128 v[186:189], v9 offset:4128
	v_fmac_f32_e32 v37, v11, v132
	v_fma_f32 v38, v8, v133, 0
	v_fmac_f32_e32 v37, v13, v134
	v_fmac_f32_e32 v38, v12, v135
	v_fmac_f32_e32 v37, v15, v136
	v_fmac_f32_e32 v38, v14, v137
	v_fmac_f32_e32 v37, v16, v138
	v_fmac_f32_e32 v38, v17, v139
	v_fmac_f32_e32 v37, v31, v140
	v_fmac_f32_e32 v38, v32, v141
	v_fmac_f32_e32 v37, v33, v142
	v_fmac_f32_e32 v38, v34, v143
	v_fmac_f32_e32 v37, v35, v144
	v_fmac_f32_e32 v38, v36, v145
	v_add_f32_e32 v37, v38, v37
	s_and_saveexec_b64 s[0:1], s[44:45]
	s_cbranch_execz .LBB0_810
	s_movk_i32 s4, 0x1200
	v_cvt_pk_bf16_f32 v38, v37, s0
	v_mad_u64_u32 v[40:41], s[6:7], v26, s4, v[0:1]
	ds_write_b16 v40, v38 offset:2016
	s_and_b64 exec, exec, vcc
	s_add_i32 s5, 0, 0x18c00
	v_add_u32_e32 v39, s5, v7
	ds_write_b16 v39, v38 offset:28
.LBB0_810:
	s_or_b64 exec, exec, s[0:1]
	v_cmp_eq_u32_e64 s[0:1], 15, v10
	v_cndmask_b32_e64 v54, 0, 1.0, s[0:1]
	s_waitcnt lgkmcnt(1)
	ds_read_b128 v[132:135], v9 offset:4352
	ds_read_b128 v[136:139], v9 offset:4368
	ds_read_b128 v[140:143], v9 offset:4384
	ds_read_b128 v[144:147], v9 offset:4400
	v_fmac_f32_e32 v54, v11, v174
	v_fma_f32 v38, v8, v175, 0
	v_fmac_f32_e32 v54, v13, v176
	v_fmac_f32_e32 v38, v12, v177
	v_fmac_f32_e32 v54, v15, v178
	v_fmac_f32_e32 v38, v14, v179
	v_fmac_f32_e32 v54, v16, v180
	v_fmac_f32_e32 v38, v17, v181
	v_fmac_f32_e32 v54, v31, v182
	v_fmac_f32_e32 v38, v32, v183
	v_fmac_f32_e32 v54, v33, v184
	v_fmac_f32_e32 v38, v34, v185
	v_fmac_f32_e32 v54, v35, v186
	v_fmac_f32_e32 v38, v36, v187
	v_fmac_f32_e32 v54, v37, v188
	v_add_f32_e32 v38, v38, v54
	s_and_saveexec_b64 s[0:1], s[44:45]
	s_cbranch_execz .LBB0_813
	s_movk_i32 s4, 0x1200
	v_cvt_pk_bf16_f32 v39, v38, s0
	v_mad_u64_u32 v[40:41], s[6:7], v26, s4, v[0:1]
	ds_write_b16 v40, v39 offset:2160
	s_and_b64 exec, exec, vcc
	s_add_i32 s5, 0, 0x18c00
	v_add_u32_e32 v40, s5, v7
	ds_write_b16 v40, v39 offset:30
; #define LAS __attribute__((address_space(3)))
; __device__ __forceinline__ unsigned f2bf(float f) { return (unsigned)__builtin_bit_cast(unsigned short, (__bf16)f); }
; __device__ __forceinline__ void rwkv_pre(LAS unsigned char* lds, const MixBufs& B, bf16_t* rq, int L, int u, int unext, RwRaw& R) {
;     ...
; #pragma unroll
;         for (int t = 0; t < 32; ++t) {
;             float a0 = (t == j) ? 1.f : 0.f, a1 = 0.f;
; #pragma unroll
;             for (int s4 = 0; s4 < (t + 3) / 4; ++s4) {
;                 const f32x4 l = *(const LAS f32x4*)(Lfz + t * 68 + s4 * 4);
; #pragma unroll
;                 for (int e2 = 0; e2 < 4; ++e2) { const int s_ = s4 * 4 + e2; if (s_ < t) { if (e2 & 1) a1 += l[e2] * T[s_]; else a0 += l[e2] * T[s_]; } }
;             }
;             T[t] = a0 + a1;
;             if (lane < 32) {
;                 Tm[(ob + t) * RL + ob + j] = (bf16_t)f2bf(T[t]);
;                 if (w == 0) T11T[j * 40 + t] = (bf16_t)f2bf(T[t]);
;             }
;         }
.LBB0_813:
	s_or_b64 exec, exec, s[0:1]
	v_cmp_eq_u32_e64 s[0:1], 16, v10
	v_cndmask_b32_e64 v39, 0, 1.0, s[0:1]
	s_waitcnt lgkmcnt(1)
	ds_read_b128 v[174:177], v9 offset:4624
	ds_read_b128 v[178:181], v9 offset:4640
	ds_read_b128 v[182:185], v9 offset:4656
	ds_read_b128 v[186:189], v9 offset:4672
	ds_read_b128 v[190:193], v9 offset:4688
	v_fmac_f32_e32 v39, v11, v132
	v_fma_f32 v40, v8, v133, 0
	v_fmac_f32_e32 v39, v13, v134
	v_fmac_f32_e32 v40, v12, v135
	v_fmac_f32_e32 v39, v15, v136
	v_fmac_f32_e32 v40, v14, v137
	v_fmac_f32_e32 v39, v16, v138
	v_fmac_f32_e32 v40, v17, v139
	v_fmac_f32_e32 v39, v31, v140
	v_fmac_f32_e32 v40, v32, v141
	v_fmac_f32_e32 v39, v33, v142
	v_fmac_f32_e32 v40, v34, v143
	v_fmac_f32_e32 v39, v35, v144
	v_fmac_f32_e32 v40, v36, v145
	v_fmac_f32_e32 v39, v37, v146
	v_fmac_f32_e32 v40, v38, v147
	v_add_f32_e32 v39, v40, v39
	s_and_saveexec_b64 s[0:1], s[44:45]
	s_cbranch_execz .LBB0_816
	s_movk_i32 s4, 0x1200
	v_cvt_pk_bf16_f32 v40, v39, s0
	v_mad_u64_u32 v[50:51], s[6:7], v26, s4, v[0:1]
	ds_write_b16 v50, v40 offset:2304
	s_and_b64 exec, exec, vcc
	s_add_i32 s5, 0, 0x18c00
	v_add_u32_e32 v41, s5, v7
	ds_write_b16 v41, v40 offset:32
.LBB0_816:
	s_or_b64 exec, exec, s[0:1]
	v_cmp_eq_u32_e64 s[0:1], 17, v10
	v_cndmask_b32_e64 v40, 0, 1.0, s[0:1]
	s_waitcnt lgkmcnt(1)
	ds_read_b128 v[132:135], v9 offset:4896
	ds_read_b128 v[136:139], v9 offset:4912
	ds_read_b128 v[140:143], v9 offset:4928
	ds_read_b128 v[144:147], v9 offset:4944
	ds_read_b128 v[148:151], v9 offset:4960
	v_fmac_f32_e32 v40, v11, v174
	v_fma_f32 v41, v8, v175, 0
	v_fmac_f32_e32 v40, v13, v176
	v_fmac_f32_e32 v41, v12, v177
	v_fmac_f32_e32 v40, v15, v178
	v_fmac_f32_e32 v41, v14, v179
	v_fmac_f32_e32 v40, v16, v180
	v_fmac_f32_e32 v41, v17, v181
	v_fmac_f32_e32 v40, v31, v182
	v_fmac_f32_e32 v41, v32, v183
	v_fmac_f32_e32 v40, v33, v184
	v_fmac_f32_e32 v41, v34, v185
	v_fmac_f32_e32 v40, v35, v186
	v_fmac_f32_e32 v41, v36, v187
	v_fmac_f32_e32 v40, v37, v188
	v_fmac_f32_e32 v41, v38, v189
	v_fmac_f32_e32 v40, v39, v190
	v_add_f32_e32 v40, v41, v40
	s_and_saveexec_b64 s[0:1], s[44:45]
	s_cbranch_execz .LBB0_819
	s_movk_i32 s4, 0x1200
	v_cvt_pk_bf16_f32 v41, v40, s0
	v_mad_u64_u32 v[50:51], s[6:7], v26, s4, v[0:1]
	ds_write_b16 v50, v41 offset:2448
	s_and_b64 exec, exec, vcc
	s_add_i32 s5, 0, 0x18c00
	v_add_u32_e32 v50, s5, v7
	ds_write_b16 v50, v41 offset:34
.LBB0_819:
	s_or_b64 exec, exec, s[0:1]
	v_cmp_eq_u32_e64 s[0:1], 18, v10
	v_cndmask_b32_e64 v41, 0, 1.0, s[0:1]
	s_waitcnt lgkmcnt(1)
	ds_read_b128 v[174:177], v9 offset:5168
	ds_read_b128 v[178:181], v9 offset:5184
	ds_read_b128 v[182:185], v9 offset:5200
	ds_read_b128 v[186:189], v9 offset:5216
	ds_read_b128 v[190:193], v9 offset:5232
	v_fmac_f32_e32 v41, v11, v132
	v_fma_f32 v54, v8, v133, 0
	v_fmac_f32_e32 v41, v13, v134
	v_fmac_f32_e32 v54, v12, v135
	v_fmac_f32_e32 v41, v15, v136
	v_fmac_f32_e32 v54, v14, v137
	v_fmac_f32_e32 v41, v16, v138
	v_fmac_f32_e32 v54, v17, v139
	v_fmac_f32_e32 v41, v31, v140
	v_fmac_f32_e32 v54, v32, v141
	v_fmac_f32_e32 v41, v33, v142
	v_fmac_f32_e32 v54, v34, v143
	v_fmac_f32_e32 v41, v35, v144
	v_fmac_f32_e32 v54, v36, v145
	v_fmac_f32_e32 v41, v37, v146
	v_fmac_f32_e32 v54, v38, v147
	v_fmac_f32_e32 v41, v39, v148
	v_fmac_f32_e32 v54, v40, v149
	v_add_f32_e32 v41, v54, v41
	s_and_saveexec_b64 s[0:1], s[44:45]
	s_cbranch_execz .LBB0_822
	s_movk_i32 s4, 0x1200
	v_cvt_pk_bf16_f32 v50, v41, s0
	v_mad_u64_u32 v[52:53], s[6:7], v26, s4, v[0:1]
	ds_write_b16 v52, v50 offset:2592
	s_and_b64 exec, exec, vcc
	s_add_i32 s5, 0, 0x18c00
	v_add_u32_e32 v51, s5, v7
	ds_write_b16 v51, v50 offset:36
.LBB0_822:
	s_or_b64 exec, exec, s[0:1]
	v_cmp_eq_u32_e64 s[0:1], 19, v10
	v_cndmask_b32_e64 v54, 0, 1.0, s[0:1]
	s_waitcnt lgkmcnt(1)
	ds_read_b128 v[132:135], v9 offset:5440
	ds_read_b128 v[136:139], v9 offset:5456
	ds_read_b128 v[140:143], v9 offset:5472
	ds_read_b128 v[144:147], v9 offset:5488
	ds_read_b128 v[148:151], v9 offset:5504
	v_fmac_f32_e32 v54, v11, v174
	v_fma_f32 v55, v8, v175, 0
	v_fmac_f32_e32 v54, v13, v176
	v_fmac_f32_e32 v55, v12, v177
	v_fmac_f32_e32 v54, v15, v178
	v_fmac_f32_e32 v55, v14, v179
	v_fmac_f32_e32 v54, v16, v180
	v_fmac_f32_e32 v55, v17, v181
	v_fmac_f32_e32 v54, v31, v182
	v_fmac_f32_e32 v55, v32, v183
	v_fmac_f32_e32 v54, v33, v184
	v_fmac_f32_e32 v55, v34, v185
	v_fmac_f32_e32 v54, v35, v186
	v_fmac_f32_e32 v55, v36, v187
	v_fmac_f32_e32 v54, v37, v188
	v_fmac_f32_e32 v55, v38, v189
	v_fmac_f32_e32 v54, v39, v190
	v_fmac_f32_e32 v55, v40, v191
	v_fmac_f32_e32 v54, v41, v192
	v_add_f32_e32 v50, v55, v54
	s_and_saveexec_b64 s[0:1], s[44:45]
	s_cbranch_execz .LBB0_825
	s_movk_i32 s4, 0x1200
	v_cvt_pk_bf16_f32 v51, v50, s0
	v_mad_u64_u32 v[52:53], s[6:7], v26, s4, v[0:1]
	ds_write_b16 v52, v51 offset:2736
	s_and_b64 exec, exec, vcc
	s_add_i32 s5, 0, 0x18c00
	v_add_u32_e32 v52, s5, v7
	ds_write_b16 v52, v51 offset:38
.LBB0_825:
	s_or_b64 exec, exec, s[0:1]
	v_cmp_eq_u32_e64 s[0:1], 20, v10
	v_cndmask_b32_e64 v51, 0, 1.0, s[0:1]
	s_waitcnt lgkmcnt(1)
	ds_read_b128 v[174:177], v9 offset:5712
	ds_read_b128 v[178:181], v9 offset:5728
	ds_read_b128 v[182:185], v9 offset:5744
	ds_read_b128 v[186:189], v9 offset:5760
	ds_read_b128 v[190:193], v9 offset:5776
	ds_read_b128 v[194:197], v9 offset:5792
	v_fmac_f32_e32 v51, v11, v132
	v_fma_f32 v57, v8, v133, 0
	v_fmac_f32_e32 v51, v13, v134
	v_fmac_f32_e32 v57, v12, v135
	v_fmac_f32_e32 v51, v15, v136
	v_fmac_f32_e32 v57, v14, v137
	v_fmac_f32_e32 v51, v16, v138
	v_fmac_f32_e32 v57, v17, v139
	v_fmac_f32_e32 v51, v31, v140
	v_fmac_f32_e32 v57, v32, v141
	v_fmac_f32_e32 v51, v33, v142
	v_fmac_f32_e32 v57, v34, v143
	v_fmac_f32_e32 v51, v35, v144
	v_fmac_f32_e32 v57, v36, v145
	v_fmac_f32_e32 v51, v37, v146
	v_fmac_f32_e32 v57, v38, v147
	v_fmac_f32_e32 v51, v39, v148
	v_fmac_f32_e32 v57, v40, v149
	v_fmac_f32_e32 v51, v41, v150
	v_fmac_f32_e32 v57, v50, v151
	v_add_f32_e32 v51, v57, v51
	s_and_saveexec_b64 s[0:1], s[44:45]
	s_cbranch_execz .LBB0_828
	s_movk_i32 s4, 0x1200
	v_cvt_pk_bf16_f32 v52, v51, s0
	v_mad_u64_u32 v[54:55], s[6:7], v26, s4, v[0:1]
	ds_write_b16 v54, v52 offset:2880
	s_and_b64 exec, exec, vcc
	s_add_i32 s5, 0, 0x18c00
	v_add_u32_e32 v53, s5, v7
	ds_write_b16 v53, v52 offset:40
; #define LAS __attribute__((address_space(3)))
; __device__ __forceinline__ unsigned f2bf(float f) { return (unsigned)__builtin_bit_cast(unsigned short, (__bf16)f); }
; __device__ __forceinline__ void rwkv_pre(LAS unsigned char* lds, const MixBufs& B, bf16_t* rq, int L, int u, int unext, RwRaw& R) {
;     ...
; #pragma unroll
;         for (int t = 0; t < 32; ++t) {
;             float a0 = (t == j) ? 1.f : 0.f, a1 = 0.f;
; #pragma unroll
;             for (int s4 = 0; s4 < (t + 3) / 4; ++s4) {
;                 const f32x4 l = *(const LAS f32x4*)(Lfz + t * 68 + s4 * 4);
; #pragma unroll
;                 for (int e2 = 0; e2 < 4; ++e2) { const int s_ = s4 * 4 + e2; if (s_ < t) { if (e2 & 1) a1 += l[e2] * T[s_]; else a0 += l[e2] * T[s_]; } }
;             }
;             T[t] = a0 + a1;
;             if (lane < 32) {
;                 Tm[(ob + t) * RL + ob + j] = (bf16_t)f2bf(T[t]);
;                 if (w == 0) T11T[j * 40 + t] = (bf16_t)f2bf(T[t]);
;             }
;         }
.LBB0_828:
	s_or_b64 exec, exec, s[0:1]
	v_cmp_eq_u32_e64 s[0:1], 21, v10
	v_cndmask_b32_e64 v57, 0, 1.0, s[0:1]
	s_waitcnt lgkmcnt(1)
	ds_read_b128 v[132:135], v9 offset:5984
	ds_read_b128 v[136:139], v9 offset:6000
	ds_read_b128 v[140:143], v9 offset:6016
	ds_read_b128 v[144:147], v9 offset:6032
	ds_read_b128 v[148:151], v9 offset:6048
	ds_read_b128 v[166:169], v9 offset:6064
	v_fmac_f32_e32 v57, v11, v174
	v_fma_f32 v78, v8, v175, 0
	v_fmac_f32_e32 v57, v13, v176
	v_fmac_f32_e32 v78, v12, v177
	v_fmac_f32_e32 v57, v15, v178
	v_fmac_f32_e32 v78, v14, v179
	v_fmac_f32_e32 v57, v16, v180
	v_fmac_f32_e32 v78, v17, v181
	v_fmac_f32_e32 v57, v31, v182
	v_fmac_f32_e32 v78, v32, v183
	v_fmac_f32_e32 v57, v33, v184
	v_fmac_f32_e32 v78, v34, v185
	v_fmac_f32_e32 v57, v35, v186
	v_fmac_f32_e32 v78, v36, v187
	v_fmac_f32_e32 v57, v37, v188
	v_fmac_f32_e32 v78, v38, v189
	v_fmac_f32_e32 v57, v39, v190
	v_fmac_f32_e32 v78, v40, v191
	v_fmac_f32_e32 v57, v41, v192
	v_fmac_f32_e32 v78, v50, v193
	v_fmac_f32_e32 v57, v51, v194
	v_add_f32_e32 v52, v78, v57
	s_and_saveexec_b64 s[0:1], s[44:45]
	s_cbranch_execz .LBB0_831
	s_movk_i32 s4, 0x1200
	v_cvt_pk_bf16_f32 v53, v52, s0
	v_mad_u64_u32 v[54:55], s[6:7], v26, s4, v[0:1]
	ds_write_b16 v54, v53 offset:3024
	s_and_b64 exec, exec, vcc
	s_add_i32 s5, 0, 0x18c00
	v_add_u32_e32 v54, s5, v7
	ds_write_b16 v54, v53 offset:42
.LBB0_831:
	s_or_b64 exec, exec, s[0:1]
	v_cmp_eq_u32_e64 s[0:1], 22, v10
	v_cndmask_b32_e64 v53, 0, 1.0, s[0:1]
	s_waitcnt lgkmcnt(1)
	ds_read_b128 v[174:177], v9 offset:6256
	ds_read_b128 v[178:181], v9 offset:6272
	ds_read_b128 v[182:185], v9 offset:6288
	ds_read_b128 v[186:189], v9 offset:6304
	ds_read_b128 v[190:193], v9 offset:6320
	ds_read_b128 v[194:197], v9 offset:6336
	v_fmac_f32_e32 v53, v11, v132
	v_fma_f32 v54, v8, v133, 0
	v_fmac_f32_e32 v53, v13, v134
	v_fmac_f32_e32 v54, v12, v135
	v_fmac_f32_e32 v53, v15, v136
	v_fmac_f32_e32 v54, v14, v137
	v_fmac_f32_e32 v53, v16, v138
	v_fmac_f32_e32 v54, v17, v139
	v_fmac_f32_e32 v53, v31, v140
	v_fmac_f32_e32 v54, v32, v141
	v_fmac_f32_e32 v53, v33, v142
	v_fmac_f32_e32 v54, v34, v143
	v_fmac_f32_e32 v53, v35, v144
	v_fmac_f32_e32 v54, v36, v145
	v_fmac_f32_e32 v53, v37, v146
	v_fmac_f32_e32 v54, v38, v147
	v_fmac_f32_e32 v53, v39, v148
	v_fmac_f32_e32 v54, v40, v149
	v_fmac_f32_e32 v53, v41, v150
	v_fmac_f32_e32 v54, v50, v151
	v_fmac_f32_e32 v53, v51, v166
	v_fmac_f32_e32 v54, v52, v167
	v_add_f32_e32 v53, v54, v53
	s_and_saveexec_b64 s[0:1], s[44:45]
	s_cbranch_execz .LBB0_834
	s_movk_i32 s4, 0x1200
	v_cvt_pk_bf16_f32 v54, v53, s0
	v_mad_u64_u32 v[66:67], s[6:7], v26, s4, v[0:1]
	ds_write_b16 v66, v54 offset:3168
	s_and_b64 exec, exec, vcc
	s_add_i32 s5, 0, 0x18c00
	v_add_u32_e32 v55, s5, v7
	ds_write_b16 v55, v54 offset:44
.LBB0_834:
	s_or_b64 exec, exec, s[0:1]
	v_cmp_eq_u32_e64 s[0:1], 23, v10
	v_cndmask_b32_e64 v54, 0, 1.0, s[0:1]
	s_waitcnt lgkmcnt(1)
	ds_read_b128 v[132:135], v9 offset:6528
	ds_read_b128 v[136:139], v9 offset:6544
	ds_read_b128 v[140:143], v9 offset:6560
	ds_read_b128 v[144:147], v9 offset:6576
	ds_read_b128 v[148:151], v9 offset:6592
	ds_read_b128 v[166:169], v9 offset:6608
	v_fmac_f32_e32 v54, v11, v174
	v_fma_f32 v55, v8, v175, 0
	v_fmac_f32_e32 v54, v13, v176
	v_fmac_f32_e32 v55, v12, v177
	v_fmac_f32_e32 v54, v15, v178
	v_fmac_f32_e32 v55, v14, v179
	v_fmac_f32_e32 v54, v16, v180
	v_fmac_f32_e32 v55, v17, v181
	v_fmac_f32_e32 v54, v31, v182
	v_fmac_f32_e32 v55, v32, v183
	v_fmac_f32_e32 v54, v33, v184
	v_fmac_f32_e32 v55, v34, v185
	v_fmac_f32_e32 v54, v35, v186
	v_fmac_f32_e32 v55, v36, v187
	v_fmac_f32_e32 v54, v37, v188
	v_fmac_f32_e32 v55, v38, v189
	v_fmac_f32_e32 v54, v39, v190
	v_fmac_f32_e32 v55, v40, v191
	v_fmac_f32_e32 v54, v41, v192
	v_fmac_f32_e32 v55, v50, v193
	v_fmac_f32_e32 v54, v51, v194
	v_fmac_f32_e32 v55, v52, v195
	v_fmac_f32_e32 v54, v53, v196
	v_add_f32_e32 v54, v55, v54
	s_and_saveexec_b64 s[0:1], s[44:45]
	s_cbranch_execz .LBB0_837
	s_movk_i32 s4, 0x1200
	v_cvt_pk_bf16_f32 v55, v54, s0
	v_mad_u64_u32 v[66:67], s[6:7], v26, s4, v[0:1]
	ds_write_b16 v66, v55 offset:3312
	s_and_b64 exec, exec, vcc
	s_add_i32 s5, 0, 0x18c00
	v_add_u32_e32 v57, s5, v7
	ds_write_b16 v57, v55 offset:46
.LBB0_837:
	s_or_b64 exec, exec, s[0:1]
	v_cmp_eq_u32_e64 s[0:1], 24, v10
	v_cndmask_b32_e64 v55, 0, 1.0, s[0:1]
	s_waitcnt lgkmcnt(1)
	ds_read_b128 v[174:177], v9 offset:6800
	ds_read_b128 v[178:181], v9 offset:6816
	ds_read_b128 v[182:185], v9 offset:6832
	ds_read_b128 v[186:189], v9 offset:6848
	ds_read_b128 v[190:193], v9 offset:6864
	ds_read_b128 v[194:197], v9 offset:6880
	ds_read_b128 v[198:201], v9 offset:6896
	v_fmac_f32_e32 v55, v11, v132
	v_fma_f32 v57, v8, v133, 0
	v_fmac_f32_e32 v55, v13, v134
	v_fmac_f32_e32 v57, v12, v135
	v_fmac_f32_e32 v55, v15, v136
	v_fmac_f32_e32 v57, v14, v137
	v_fmac_f32_e32 v55, v16, v138
	v_fmac_f32_e32 v57, v17, v139
	v_fmac_f32_e32 v55, v31, v140
	v_fmac_f32_e32 v57, v32, v141
	v_fmac_f32_e32 v55, v33, v142
	v_fmac_f32_e32 v57, v34, v143
	v_fmac_f32_e32 v55, v35, v144
	v_fmac_f32_e32 v57, v36, v145
	v_fmac_f32_e32 v55, v37, v146
	v_fmac_f32_e32 v57, v38, v147
	v_fmac_f32_e32 v55, v39, v148
	v_fmac_f32_e32 v57, v40, v149
	v_fmac_f32_e32 v55, v41, v150
	v_fmac_f32_e32 v57, v50, v151
	v_fmac_f32_e32 v55, v51, v166
	v_fmac_f32_e32 v57, v52, v167
	v_fmac_f32_e32 v55, v53, v168
	v_fmac_f32_e32 v57, v54, v169
	v_add_f32_e32 v55, v57, v55
	s_and_saveexec_b64 s[0:1], s[44:45]
	s_cbranch_execz .LBB0_840
	s_movk_i32 s4, 0x1200
	v_cvt_pk_bf16_f32 v57, v55, s0
	v_mad_u64_u32 v[66:67], s[6:7], v26, s4, v[0:1]
	ds_write_b16 v66, v57 offset:3456
	s_and_b64 exec, exec, vcc
	s_add_i32 s5, 0, 0x18c00
	v_add_u32_e32 v66, s5, v7
	ds_write_b16 v66, v57 offset:48
; #define LAS __attribute__((address_space(3)))
; __device__ __forceinline__ unsigned f2bf(float f) { return (unsigned)__builtin_bit_cast(unsigned short, (__bf16)f); }
; __device__ __forceinline__ void rwkv_pre(LAS unsigned char* lds, const MixBufs& B, bf16_t* rq, int L, int u, int unext, RwRaw& R) {
;     ...
; #pragma unroll
;         for (int t = 0; t < 32; ++t) {
;             float a0 = (t == j) ? 1.f : 0.f, a1 = 0.f;
; #pragma unroll
;             for (int s4 = 0; s4 < (t + 3) / 4; ++s4) {
;                 const f32x4 l = *(const LAS f32x4*)(Lfz + t * 68 + s4 * 4);
; #pragma unroll
;                 for (int e2 = 0; e2 < 4; ++e2) { const int s_ = s4 * 4 + e2; if (s_ < t) { if (e2 & 1) a1 += l[e2] * T[s_]; else a0 += l[e2] * T[s_]; } }
;             }
;             T[t] = a0 + a1;
;             if (lane < 32) {
;                 Tm[(ob + t) * RL + ob + j] = (bf16_t)f2bf(T[t]);
;                 if (w == 0) T11T[j * 40 + t] = (bf16_t)f2bf(T[t]);
;             }
;         }
.LBB0_840:
	s_or_b64 exec, exec, s[0:1]
	v_cmp_eq_u32_e64 s[0:1], 25, v10
	v_cndmask_b32_e64 v57, 0, 1.0, s[0:1]
	s_waitcnt lgkmcnt(1)
	ds_read_b128 v[132:135], v9 offset:7072
	ds_read_b128 v[136:139], v9 offset:7088
	ds_read_b128 v[140:143], v9 offset:7104
	ds_read_b128 v[144:147], v9 offset:7120
	ds_read_b128 v[148:151], v9 offset:7136
	ds_read_b128 v[166:169], v9 offset:7152
	ds_read_b128 v[170:173], v9 offset:7168
	v_fmac_f32_e32 v57, v11, v174
	v_fma_f32 v82, v8, v175, 0
	v_fmac_f32_e32 v57, v13, v176
	v_fmac_f32_e32 v82, v12, v177
	v_fmac_f32_e32 v57, v15, v178
	v_fmac_f32_e32 v82, v14, v179
	v_fmac_f32_e32 v57, v16, v180
	v_fmac_f32_e32 v82, v17, v181
	v_fmac_f32_e32 v57, v31, v182
	v_fmac_f32_e32 v82, v32, v183
	v_fmac_f32_e32 v57, v33, v184
	v_fmac_f32_e32 v82, v34, v185
	v_fmac_f32_e32 v57, v35, v186
	v_fmac_f32_e32 v82, v36, v187
	v_fmac_f32_e32 v57, v37, v188
	v_fmac_f32_e32 v82, v38, v189
	v_fmac_f32_e32 v57, v39, v190
	v_fmac_f32_e32 v82, v40, v191
	v_fmac_f32_e32 v57, v41, v192
	v_fmac_f32_e32 v82, v50, v193
	v_fmac_f32_e32 v57, v51, v194
	v_fmac_f32_e32 v82, v52, v195
	v_fmac_f32_e32 v57, v53, v196
	v_fmac_f32_e32 v82, v54, v197
	v_fmac_f32_e32 v57, v55, v198
	v_add_f32_e32 v57, v82, v57
	s_and_saveexec_b64 s[0:1], s[44:45]
	s_cbranch_execz .LBB0_843
	s_movk_i32 s4, 0x1200
	v_cvt_pk_bf16_f32 v66, v57, s0
	v_mad_u64_u32 v[68:69], s[6:7], v26, s4, v[0:1]
	ds_write_b16 v68, v66 offset:3600
	s_and_b64 exec, exec, vcc
	s_add_i32 s5, 0, 0x18c00
	v_add_u32_e32 v67, s5, v7
	ds_write_b16 v67, v66 offset:50
.LBB0_843:
	s_or_b64 exec, exec, s[0:1]
	v_cmp_eq_u32_e64 s[0:1], 26, v10
	v_cndmask_b32_e64 v82, 0, 1.0, s[0:1]
	s_waitcnt lgkmcnt(1)
	ds_read_b128 v[174:177], v9 offset:7344
	ds_read_b128 v[178:181], v9 offset:7360
	ds_read_b128 v[182:185], v9 offset:7376
	ds_read_b128 v[186:189], v9 offset:7392
	ds_read_b128 v[190:193], v9 offset:7408
	ds_read_b128 v[194:197], v9 offset:7424
	ds_read_b128 v[198:201], v9 offset:7440
	v_fmac_f32_e32 v82, v11, v132
	v_fma_f32 v83, v8, v133, 0
	v_fmac_f32_e32 v82, v13, v134
	v_fmac_f32_e32 v83, v12, v135
	v_fmac_f32_e32 v82, v15, v136
	v_fmac_f32_e32 v83, v14, v137
	v_fmac_f32_e32 v82, v16, v138
	v_fmac_f32_e32 v83, v17, v139
	v_fmac_f32_e32 v82, v31, v140
	v_fmac_f32_e32 v83, v32, v141
	v_fmac_f32_e32 v82, v33, v142
	v_fmac_f32_e32 v83, v34, v143
	v_fmac_f32_e32 v82, v35, v144
	v_fmac_f32_e32 v83, v36, v145
	v_fmac_f32_e32 v82, v37, v146
	v_fmac_f32_e32 v83, v38, v147
	v_fmac_f32_e32 v82, v39, v148
	v_fmac_f32_e32 v83, v40, v149
	v_fmac_f32_e32 v82, v41, v150
	v_fmac_f32_e32 v83, v50, v151
	v_fmac_f32_e32 v82, v51, v166
	v_fmac_f32_e32 v83, v52, v167
	v_fmac_f32_e32 v82, v53, v168
	v_fmac_f32_e32 v83, v54, v169
	v_fmac_f32_e32 v82, v55, v170
	v_fmac_f32_e32 v83, v57, v171
	v_add_f32_e32 v66, v83, v82
	s_and_saveexec_b64 s[0:1], s[44:45]
	s_cbranch_execz .LBB0_846
	s_movk_i32 s4, 0x1200
	v_cvt_pk_bf16_f32 v67, v66, s0
	v_mad_u64_u32 v[68:69], s[6:7], v26, s4, v[0:1]
	ds_write_b16 v68, v67 offset:3744
	s_and_b64 exec, exec, vcc
	s_add_i32 s5, 0, 0x18c00
	v_add_u32_e32 v68, s5, v7
	ds_write_b16 v68, v67 offset:52
.LBB0_846:
	s_or_b64 exec, exec, s[0:1]
	v_cmp_eq_u32_e64 s[0:1], 27, v10
	v_cndmask_b32_e64 v67, 0, 1.0, s[0:1]
	s_waitcnt lgkmcnt(1)
	ds_read_b128 v[132:135], v9 offset:7616
	ds_read_b128 v[136:139], v9 offset:7632
	ds_read_b128 v[140:143], v9 offset:7648
	ds_read_b128 v[144:147], v9 offset:7664
	ds_read_b128 v[148:151], v9 offset:7680
	ds_read_b128 v[166:169], v9 offset:7696
	ds_read_b128 v[170:173], v9 offset:7712
	v_fmac_f32_e32 v67, v11, v174
	v_fma_f32 v84, v8, v175, 0
	v_fmac_f32_e32 v67, v13, v176
	v_fmac_f32_e32 v84, v12, v177
	v_fmac_f32_e32 v67, v15, v178
	v_fmac_f32_e32 v84, v14, v179
	v_fmac_f32_e32 v67, v16, v180
	v_fmac_f32_e32 v84, v17, v181
	v_fmac_f32_e32 v67, v31, v182
	v_fmac_f32_e32 v84, v32, v183
	v_fmac_f32_e32 v67, v33, v184
	v_fmac_f32_e32 v84, v34, v185
	v_fmac_f32_e32 v67, v35, v186
	v_fmac_f32_e32 v84, v36, v187
	v_fmac_f32_e32 v67, v37, v188
	v_fmac_f32_e32 v84, v38, v189
	v_fmac_f32_e32 v67, v39, v190
	v_fmac_f32_e32 v84, v40, v191
	v_fmac_f32_e32 v67, v41, v192
	v_fmac_f32_e32 v84, v50, v193
	v_fmac_f32_e32 v67, v51, v194
	v_fmac_f32_e32 v84, v52, v195
	v_fmac_f32_e32 v67, v53, v196
	v_fmac_f32_e32 v84, v54, v197
	v_fmac_f32_e32 v67, v55, v198
	v_fmac_f32_e32 v84, v57, v199
	v_fmac_f32_e32 v67, v66, v200
	v_add_f32_e32 v67, v84, v67
	s_and_saveexec_b64 s[0:1], s[44:45]
	s_cbranch_execz .LBB0_849
	s_movk_i32 s4, 0x1200
	v_cvt_pk_bf16_f32 v68, v67, s0
	v_mad_u64_u32 v[70:71], s[6:7], v26, s4, v[0:1]
	ds_write_b16 v70, v68 offset:3888
	s_and_b64 exec, exec, vcc
	s_add_i32 s5, 0, 0x18c00
	v_add_u32_e32 v69, s5, v7
	ds_write_b16 v69, v68 offset:54
.LBB0_849:
	s_or_b64 exec, exec, s[0:1]
	v_cmp_eq_u32_e64 s[0:1], 28, v10
	v_cndmask_b32_e64 v84, 0, 1.0, s[0:1]
	s_waitcnt lgkmcnt(1)
	v_fmac_f32_e32 v84, v11, v132
	v_fma_f32 v85, v8, v133, 0
	v_fmac_f32_e32 v84, v13, v134
	v_fmac_f32_e32 v85, v12, v135
	v_fmac_f32_e32 v84, v15, v136
	v_fmac_f32_e32 v85, v14, v137
	v_fmac_f32_e32 v84, v16, v138
	v_fmac_f32_e32 v85, v17, v139
	v_fmac_f32_e32 v84, v31, v140
	v_fmac_f32_e32 v85, v32, v141
	v_fmac_f32_e32 v84, v33, v142
	v_fmac_f32_e32 v85, v34, v143
	v_fmac_f32_e32 v84, v35, v144
	v_fmac_f32_e32 v85, v36, v145
	v_fmac_f32_e32 v84, v37, v146
	v_fmac_f32_e32 v85, v38, v147
	v_fmac_f32_e32 v84, v39, v148
	v_fmac_f32_e32 v85, v40, v149
	v_fmac_f32_e32 v84, v41, v150
	v_fmac_f32_e32 v85, v50, v151
	v_fmac_f32_e32 v84, v51, v166
	v_fmac_f32_e32 v85, v52, v167
	v_fmac_f32_e32 v84, v53, v168
	v_fmac_f32_e32 v85, v54, v169
	v_fmac_f32_e32 v84, v55, v170
	v_fmac_f32_e32 v85, v57, v171
	v_fmac_f32_e32 v84, v66, v172
	v_fmac_f32_e32 v85, v67, v173
	v_add_f32_e32 v68, v85, v84
	s_and_saveexec_b64 s[0:1], s[44:45]
	s_cbranch_execz .LBB0_852
	s_movk_i32 s4, 0x1200
	v_cvt_pk_bf16_f32 v69, v68, s0
	v_mad_u64_u32 v[70:71], s[6:7], v26, s4, v[0:1]
	ds_write_b16 v70, v69 offset:4032
	s_and_b64 exec, exec, vcc
	s_add_i32 s5, 0, 0x18c00
	v_add_u32_e32 v70, s5, v7
	ds_write_b16 v70, v69 offset:56

; #define LAS __attribute__((address_space(3)))
; __device__ __forceinline__ unsigned f2bf(float f) { return (unsigned)__builtin_bit_cast(unsigned short, (__bf16)f); }
; __device__ __forceinline__ void rwkv_pre(LAS unsigned char* lds, const MixBufs& B, bf16_t* rq, int L, int u, int unext, RwRaw& R) {
;     ...
; #pragma unroll
;         for (int t = 0; t < 32; ++t) {
;             float a0 = (t == j) ? 1.f : 0.f, a1 = 0.f;
; #pragma unroll
;             for (int s4 = 0; s4 < (t + 3) / 4; ++s4) {
;                 const f32x4 l = *(const LAS f32x4*)(Lfz + t * 68 + s4 * 4);
; #pragma unroll
;                 for (int e2 = 0; e2 < 4; ++e2) { const int s_ = s4 * 4 + e2; if (s_ < t) { if (e2 & 1) a1 += l[e2] * T[s_]; else a0 += l[e2] * T[s_]; } }
;             }
;             T[t] = a0 + a1;
;             if (lane < 32) {
;                 Tm[(ob + t) * RL + ob + j] = (bf16_t)f2bf(T[t]);
;                 if (w == 0) T11T[j * 40 + t] = (bf16_t)f2bf(T[t]);
;             }
;         }
.LBB0_1144:
	s_or_b64 exec, exec, s[0:1]
	ds_read_b128 v[12:15], v8 offset:544
	v_cmp_eq_u32_e64 s[0:1], 2, v9
	s_waitcnt lgkmcnt(0)
	ds_read_b128 v[174:177], v8 offset:816
	s_nop 0
	v_cndmask_b32_e64 v14, 0, 1.0, s[0:1]
	v_fmac_f32_e32 v14, v10, v12
	v_fma_f32 v12, v7, v13, 0
	v_add_f32_e32 v13, v12, v14
	s_and_saveexec_b64 s[0:1], s[46:47]
	s_cbranch_execz .LBB0_1147
	s_movk_i32 s4, 0x1200
	v_cvt_pk_bf16_f32 v12, v13, s0
	v_mad_u64_u32 v[14:15], s[6:7], v26, s4, v[0:1]
	ds_write_b16 v14, v12 offset:288
	s_and_b64 exec, exec, vcc
	v_add_u32_e32 v14, s54, v11
	ds_write_b16 v14, v12 offset:4
.LBB0_1147:
	s_or_b64 exec, exec, s[0:1]
	v_cmp_eq_u32_e64 s[0:1], 3, v9
	s_nop 1
	v_cndmask_b32_e64 v12, 0, 1.0, s[0:1]
	s_waitcnt lgkmcnt(1)
	ds_read_b128 v[132:135], v8 offset:1088
	v_fmac_f32_e32 v12, v10, v174
	v_fma_f32 v14, v7, v175, 0
	v_fmac_f32_e32 v12, v13, v176
	v_add_f32_e32 v12, v14, v12
	s_and_saveexec_b64 s[0:1], s[46:47]
	s_cbranch_execz .LBB0_1150
	s_movk_i32 s4, 0x1200
	v_cvt_pk_bf16_f32 v14, v12, s0
	v_mad_u64_u32 v[16:17], s[6:7], v26, s4, v[0:1]
	ds_write_b16 v16, v14 offset:432
	s_and_b64 exec, exec, vcc
	v_add_u32_e32 v15, s54, v11
	ds_write_b16 v15, v14 offset:6
.LBB0_1150:
	s_or_b64 exec, exec, s[0:1]
	v_cmp_eq_u32_e64 s[0:1], 4, v9
	s_nop 1
	v_cndmask_b32_e64 v31, 0, 1.0, s[0:1]
	s_waitcnt lgkmcnt(1)
	ds_read_b128 v[174:177], v8 offset:1360
	ds_read_b128 v[178:181], v8 offset:1376
	v_fmac_f32_e32 v31, v10, v132
	v_fma_f32 v14, v7, v133, 0
	v_fmac_f32_e32 v31, v13, v134
	v_fmac_f32_e32 v14, v12, v135
	v_add_f32_e32 v15, v14, v31
	s_and_saveexec_b64 s[0:1], s[46:47]
	s_cbranch_execz .LBB0_1153
	s_movk_i32 s4, 0x1200
	v_cvt_pk_bf16_f32 v14, v15, s0
	v_mad_u64_u32 v[16:17], s[6:7], v26, s4, v[0:1]
	ds_write_b16 v16, v14 offset:576
	s_and_b64 exec, exec, vcc
	v_add_u32_e32 v16, s54, v11
	ds_write_b16 v16, v14 offset:8
.LBB0_1153:
	s_or_b64 exec, exec, s[0:1]
	v_cmp_eq_u32_e64 s[0:1], 5, v9
	s_waitcnt lgkmcnt(1)
	ds_read_b128 v[132:135], v8 offset:1632
	ds_read_b128 v[136:139], v8 offset:1648
	v_fma_f32 v16, v7, v175, 0
	v_cndmask_b32_e64 v14, 0, 1.0, s[0:1]
	v_fmac_f32_e32 v14, v10, v174
	v_fmac_f32_e32 v14, v13, v176
	v_fmac_f32_e32 v16, v12, v177
	v_fmac_f32_e32 v14, v15, v178
	v_add_f32_e32 v14, v16, v14
	s_and_saveexec_b64 s[0:1], s[46:47]
	s_cbranch_execz .LBB0_1156
	s_movk_i32 s4, 0x1200
	v_cvt_pk_bf16_f32 v16, v14, s0
	v_mad_u64_u32 v[32:33], s[6:7], v26, s4, v[0:1]
	ds_write_b16 v32, v16 offset:720
	s_and_b64 exec, exec, vcc
	v_add_u32_e32 v17, s54, v11
	ds_write_b16 v17, v16 offset:10
.LBB0_1156:
	s_or_b64 exec, exec, s[0:1]
	v_cmp_eq_u32_e64 s[0:1], 6, v9
	s_waitcnt lgkmcnt(1)
	ds_read_b128 v[174:177], v8 offset:1904
	ds_read_b128 v[178:181], v8 offset:1920
	v_fma_f32 v17, v7, v133, 0
	v_cndmask_b32_e64 v16, 0, 1.0, s[0:1]
	v_fmac_f32_e32 v16, v10, v132
	v_fmac_f32_e32 v16, v13, v134
	v_fmac_f32_e32 v17, v12, v135
	v_fmac_f32_e32 v16, v15, v136
	v_fmac_f32_e32 v17, v14, v137
	v_add_f32_e32 v17, v17, v16
	s_and_saveexec_b64 s[0:1], s[46:47]
	s_cbranch_execz .LBB0_1159
	s_movk_i32 s4, 0x1200
	v_cvt_pk_bf16_f32 v16, v17, s0
	v_mad_u64_u32 v[32:33], s[6:7], v26, s4, v[0:1]
	ds_write_b16 v32, v16 offset:864
	s_and_b64 exec, exec, vcc
	v_add_u32_e32 v31, s54, v11
	ds_write_b16 v31, v16 offset:12
.LBB0_1159:
	s_or_b64 exec, exec, s[0:1]
	v_cmp_eq_u32_e64 s[0:1], 7, v9
	s_waitcnt lgkmcnt(1)
	ds_read_b128 v[132:135], v8 offset:2176
	ds_read_b128 v[136:139], v8 offset:2192
	v_fma_f32 v31, v7, v175, 0
	v_cndmask_b32_e64 v16, 0, 1.0, s[0:1]
	v_fmac_f32_e32 v16, v10, v174
	v_fmac_f32_e32 v16, v13, v176
	v_fmac_f32_e32 v31, v12, v177
	v_fmac_f32_e32 v16, v15, v178
	v_fmac_f32_e32 v31, v14, v179
	v_fmac_f32_e32 v16, v17, v180
	v_add_f32_e32 v16, v31, v16
	s_and_saveexec_b64 s[0:1], s[46:47]
	s_cbranch_execz .LBB0_1162
	s_movk_i32 s4, 0x1200
	v_cvt_pk_bf16_f32 v31, v16, s0
	v_mad_u64_u32 v[32:33], s[6:7], v26, s4, v[0:1]
	ds_write_b16 v32, v31 offset:1008
	s_and_b64 exec, exec, vcc
	v_add_u32_e32 v32, s54, v11
	ds_write_b16 v32, v31 offset:14
.LBB0_1162:
	s_or_b64 exec, exec, s[0:1]
	v_cmp_eq_u32_e64 s[0:1], 8, v9
	s_nop 1
	v_cndmask_b32_e64 v31, 0, 1.0, s[0:1]
	s_waitcnt lgkmcnt(1)
	ds_read_b128 v[174:177], v8 offset:2448
	ds_read_b128 v[178:181], v8 offset:2464
	ds_read_b128 v[182:185], v8 offset:2480
	v_fmac_f32_e32 v31, v10, v132
	v_fma_f32 v32, v7, v133, 0
	v_fmac_f32_e32 v31, v13, v134
	v_fmac_f32_e32 v32, v12, v135
	v_fmac_f32_e32 v31, v15, v136
	v_fmac_f32_e32 v32, v14, v137
	v_fmac_f32_e32 v31, v17, v138
	v_fmac_f32_e32 v32, v16, v139
	v_add_f32_e32 v31, v32, v31
	s_and_saveexec_b64 s[0:1], s[46:47]
	s_cbranch_execz .LBB0_1165
	s_movk_i32 s4, 0x1200
	v_cvt_pk_bf16_f32 v32, v31, s0
	v_mad_u64_u32 v[34:35], s[6:7], v26, s4, v[0:1]
	ds_write_b16 v34, v32 offset:1152
	s_and_b64 exec, exec, vcc
	v_add_u32_e32 v33, s54, v11
	ds_write_b16 v33, v32 offset:16
.LBB0_1165:
	s_or_b64 exec, exec, s[0:1]
	v_cmp_eq_u32_e64 s[0:1], 9, v9
	s_nop 1
	v_cndmask_b32_e64 v40, 0, 1.0, s[0:1]
	s_waitcnt lgkmcnt(1)
	ds_read_b128 v[132:135], v8 offset:2720
	ds_read_b128 v[136:139], v8 offset:2736
	ds_read_b128 v[140:143], v8 offset:2752
	v_fmac_f32_e32 v40, v10, v174
	v_fma_f32 v32, v7, v175, 0
	v_fmac_f32_e32 v40, v13, v176
	v_fmac_f32_e32 v32, v12, v177
	v_fmac_f32_e32 v40, v15, v178
	v_fmac_f32_e32 v32, v14, v179
	v_fmac_f32_e32 v40, v17, v180
	v_fmac_f32_e32 v32, v16, v181
	v_fmac_f32_e32 v40, v31, v182
	v_add_f32_e32 v32, v32, v40
	s_and_saveexec_b64 s[0:1], s[46:47]
	s_cbranch_execz .LBB0_1168
	s_movk_i32 s4, 0x1200
	v_cvt_pk_bf16_f32 v33, v32, s0
	v_mad_u64_u32 v[34:35], s[6:7], v26, s4, v[0:1]
	ds_write_b16 v34, v33 offset:1296
	s_and_b64 exec, exec, vcc
	v_add_u32_e32 v34, s54, v11
	ds_write_b16 v34, v33 offset:18
; #define LAS __attribute__((address_space(3)))
; __device__ __forceinline__ unsigned f2bf(float f) { return (unsigned)__builtin_bit_cast(unsigned short, (__bf16)f); }
; __device__ __forceinline__ void rwkv_pre(LAS unsigned char* lds, const MixBufs& B, bf16_t* rq, int L, int u, int unext, RwRaw& R) {
;     ...
; #pragma unroll
;         for (int t = 0; t < 32; ++t) {
;             float a0 = (t == j) ? 1.f : 0.f, a1 = 0.f;
; #pragma unroll
;             for (int s4 = 0; s4 < (t + 3) / 4; ++s4) {
;                 const f32x4 l = *(const LAS f32x4*)(Lfz + t * 68 + s4 * 4);
; #pragma unroll
;                 for (int e2 = 0; e2 < 4; ++e2) { const int s_ = s4 * 4 + e2; if (s_ < t) { if (e2 & 1) a1 += l[e2] * T[s_]; else a0 += l[e2] * T[s_]; } }
;             }
;             T[t] = a0 + a1;
;             if (lane < 32) {
;                 Tm[(ob + t) * RL + ob + j] = (bf16_t)f2bf(T[t]);
;                 if (w == 0) T11T[j * 40 + t] = (bf16_t)f2bf(T[t]);
;             }
;         }
.LBB0_1168:
	s_or_b64 exec, exec, s[0:1]
	v_cmp_eq_u32_e64 s[0:1], 10, v9
	s_nop 1
	v_cndmask_b32_e64 v33, 0, 1.0, s[0:1]
	s_waitcnt lgkmcnt(1)
	ds_read_b128 v[174:177], v8 offset:2992
	ds_read_b128 v[178:181], v8 offset:3008
	ds_read_b128 v[182:185], v8 offset:3024
	v_fmac_f32_e32 v33, v10, v132
	v_fma_f32 v34, v7, v133, 0
	v_fmac_f32_e32 v33, v13, v134
	v_fmac_f32_e32 v34, v12, v135
	v_fmac_f32_e32 v33, v15, v136
	v_fmac_f32_e32 v34, v14, v137
	v_fmac_f32_e32 v33, v17, v138
	v_fmac_f32_e32 v34, v16, v139
	v_fmac_f32_e32 v33, v31, v140
	v_fmac_f32_e32 v34, v32, v141
	v_add_f32_e32 v33, v34, v33
	s_and_saveexec_b64 s[0:1], s[46:47]
	s_cbranch_execz .LBB0_1171
	s_movk_i32 s4, 0x1200
	v_cvt_pk_bf16_f32 v34, v33, s0
	v_mad_u64_u32 v[36:37], s[6:7], v26, s4, v[0:1]
	ds_write_b16 v36, v34 offset:1440
	s_and_b64 exec, exec, vcc
	v_add_u32_e32 v35, s54, v11
	ds_write_b16 v35, v34 offset:20
.LBB0_1171:
	s_or_b64 exec, exec, s[0:1]
	v_cmp_eq_u32_e64 s[0:1], 11, v9
	s_waitcnt lgkmcnt(1)
	ds_read_b128 v[132:135], v8 offset:3264
	ds_read_b128 v[136:139], v8 offset:3280
	ds_read_b128 v[140:143], v8 offset:3296
	s_nop 0
	v_cndmask_b32_e64 v53, 0, 1.0, s[0:1]
	v_fmac_f32_e32 v53, v10, v174
	v_fma_f32 v34, v7, v175, 0
	v_fmac_f32_e32 v53, v13, v176
	v_fmac_f32_e32 v34, v12, v177
	v_fmac_f32_e32 v53, v15, v178
	v_fmac_f32_e32 v34, v14, v179
	v_fmac_f32_e32 v53, v17, v180
	v_fmac_f32_e32 v34, v16, v181
	v_fmac_f32_e32 v53, v31, v182
	v_fmac_f32_e32 v34, v32, v183
	v_fmac_f32_e32 v53, v33, v184
	v_add_f32_e32 v34, v34, v53
	s_and_saveexec_b64 s[0:1], s[46:47]
	s_cbranch_execz .LBB0_1174
	s_movk_i32 s4, 0x1200
	v_cvt_pk_bf16_f32 v35, v34, s0
	v_mad_u64_u32 v[36:37], s[6:7], v26, s4, v[0:1]
	ds_write_b16 v36, v35 offset:1584
	s_and_b64 exec, exec, vcc
	v_add_u32_e32 v36, s54, v11
	ds_write_b16 v36, v35 offset:22
.LBB0_1174:
	s_or_b64 exec, exec, s[0:1]
	v_cmp_eq_u32_e64 s[0:1], 12, v9
	v_cndmask_b32_e64 v35, 0, 1.0, s[0:1]
	s_waitcnt lgkmcnt(1)
	ds_read_b128 v[174:177], v8 offset:3536
	ds_read_b128 v[178:181], v8 offset:3552
	ds_read_b128 v[182:185], v8 offset:3568
	ds_read_b128 v[186:189], v8 offset:3584
	v_fmac_f32_e32 v35, v10, v132
	v_fma_f32 v36, v7, v133, 0
	v_fmac_f32_e32 v35, v13, v134
	v_fmac_f32_e32 v36, v12, v135
	v_fmac_f32_e32 v35, v15, v136
	v_fmac_f32_e32 v36, v14, v137
	v_fmac_f32_e32 v35, v17, v138
	v_fmac_f32_e32 v36, v16, v139
	v_fmac_f32_e32 v35, v31, v140
	v_fmac_f32_e32 v36, v32, v141
	v_fmac_f32_e32 v35, v33, v142
	v_fmac_f32_e32 v36, v34, v143
	v_add_f32_e32 v35, v36, v35
	s_and_saveexec_b64 s[0:1], s[46:47]
	s_cbranch_execz .LBB0_1177
	s_movk_i32 s4, 0x1200
	v_cvt_pk_bf16_f32 v36, v35, s0
	v_mad_u64_u32 v[38:39], s[6:7], v26, s4, v[0:1]
	ds_write_b16 v38, v36 offset:1728
	s_and_b64 exec, exec, vcc
	v_add_u32_e32 v37, s54, v11
	ds_write_b16 v37, v36 offset:24
.LBB0_1177:
	s_or_b64 exec, exec, s[0:1]
	v_cmp_eq_u32_e64 s[0:1], 13, v9
	v_cndmask_b32_e64 v40, 0, 1.0, s[0:1]
	s_waitcnt lgkmcnt(1)
	ds_read_b128 v[132:135], v8 offset:3808
	ds_read_b128 v[136:139], v8 offset:3824
	ds_read_b128 v[140:143], v8 offset:3840
	ds_read_b128 v[144:147], v8 offset:3856
	v_fmac_f32_e32 v40, v10, v174
	v_fma_f32 v36, v7, v175, 0
	v_fmac_f32_e32 v40, v13, v176
	v_fmac_f32_e32 v36, v12, v177
	v_fmac_f32_e32 v40, v15, v178
	v_fmac_f32_e32 v36, v14, v179
	v_fmac_f32_e32 v40, v17, v180
	v_fmac_f32_e32 v36, v16, v181
	v_fmac_f32_e32 v40, v31, v182
	v_fmac_f32_e32 v36, v32, v183
	v_fmac_f32_e32 v40, v33, v184
	v_fmac_f32_e32 v36, v34, v185
	v_fmac_f32_e32 v40, v35, v186
	v_add_f32_e32 v36, v36, v40
	s_and_saveexec_b64 s[0:1], s[46:47]
	s_cbranch_execz .LBB0_1180
	s_movk_i32 s4, 0x1200
	v_cvt_pk_bf16_f32 v37, v36, s0
	v_mad_u64_u32 v[38:39], s[6:7], v26, s4, v[0:1]
	ds_write_b16 v38, v37 offset:1872
	s_and_b64 exec, exec, vcc
	v_add_u32_e32 v38, s54, v11
	ds_write_b16 v38, v37 offset:26
.LBB0_1180:
	s_or_b64 exec, exec, s[0:1]
	v_cmp_eq_u32_e64 s[0:1], 14, v9
	v_cndmask_b32_e64 v37, 0, 1.0, s[0:1]
	s_waitcnt lgkmcnt(1)
	ds_read_b128 v[174:177], v8 offset:4080
	ds_read_b128 v[178:181], v8 offset:4096
	ds_read_b128 v[182:185], v8 offset:4112
	ds_read_b128 v[186:189], v8 offset:4128
	v_fmac_f32_e32 v37, v10, v132
	v_fma_f32 v38, v7, v133, 0
	v_fmac_f32_e32 v37, v13, v134
	v_fmac_f32_e32 v38, v12, v135
	v_fmac_f32_e32 v37, v15, v136
	v_fmac_f32_e32 v38, v14, v137
	v_fmac_f32_e32 v37, v17, v138
	v_fmac_f32_e32 v38, v16, v139
	v_fmac_f32_e32 v37, v31, v140
	v_fmac_f32_e32 v38, v32, v141
	v_fmac_f32_e32 v37, v33, v142
	v_fmac_f32_e32 v38, v34, v143
	v_fmac_f32_e32 v37, v35, v144
	v_fmac_f32_e32 v38, v36, v145
	v_add_f32_e32 v37, v38, v37
	s_and_saveexec_b64 s[0:1], s[46:47]
	s_cbranch_execz .LBB0_1183
	s_movk_i32 s4, 0x1200
	v_cvt_pk_bf16_f32 v38, v37, s0
	v_mad_u64_u32 v[40:41], s[6:7], v26, s4, v[0:1]
	ds_write_b16 v40, v38 offset:2016
	s_and_b64 exec, exec, vcc
	v_add_u32_e32 v39, s54, v11
	ds_write_b16 v39, v38 offset:28
.LBB0_1183:
	s_or_b64 exec, exec, s[0:1]
	v_cmp_eq_u32_e64 s[0:1], 15, v9
	v_cndmask_b32_e64 v54, 0, 1.0, s[0:1]
	s_waitcnt lgkmcnt(1)
	ds_read_b128 v[132:135], v8 offset:4352
	ds_read_b128 v[136:139], v8 offset:4368
	ds_read_b128 v[140:143], v8 offset:4384
	ds_read_b128 v[144:147], v8 offset:4400
	v_fmac_f32_e32 v54, v10, v174
	v_fma_f32 v38, v7, v175, 0
	v_fmac_f32_e32 v54, v13, v176
	v_fmac_f32_e32 v38, v12, v177
	v_fmac_f32_e32 v54, v15, v178
	v_fmac_f32_e32 v38, v14, v179
	v_fmac_f32_e32 v54, v17, v180
	v_fmac_f32_e32 v38, v16, v181
	v_fmac_f32_e32 v54, v31, v182
	v_fmac_f32_e32 v38, v32, v183
	v_fmac_f32_e32 v54, v33, v184
	v_fmac_f32_e32 v38, v34, v185
	v_fmac_f32_e32 v54, v35, v186
	v_fmac_f32_e32 v38, v36, v187
	v_fmac_f32_e32 v54, v37, v188
	v_add_f32_e32 v38, v38, v54
	s_and_saveexec_b64 s[0:1], s[46:47]
	s_cbranch_execz .LBB0_1186
	s_movk_i32 s4, 0x1200
	v_cvt_pk_bf16_f32 v39, v38, s0
	v_mad_u64_u32 v[40:41], s[6:7], v26, s4, v[0:1]
	ds_write_b16 v40, v39 offset:2160
	s_and_b64 exec, exec, vcc
	v_add_u32_e32 v40, s54, v11
	ds_write_b16 v40, v39 offset:30
; #define LAS __attribute__((address_space(3)))
; __device__ __forceinline__ unsigned f2bf(float f) { return (unsigned)__builtin_bit_cast(unsigned short, (__bf16)f); }
; __device__ __forceinline__ void rwkv_pre(LAS unsigned char* lds, const MixBufs& B, bf16_t* rq, int L, int u, int unext, RwRaw& R) {
;     ...
; #pragma unroll
;         for (int t = 0; t < 32; ++t) {
;             float a0 = (t == j) ? 1.f : 0.f, a1 = 0.f;
; #pragma unroll
;             for (int s4 = 0; s4 < (t + 3) / 4; ++s4) {
;                 const f32x4 l = *(const LAS f32x4*)(Lfz + t * 68 + s4 * 4);
; #pragma unroll
;                 for (int e2 = 0; e2 < 4; ++e2) { const int s_ = s4 * 4 + e2; if (s_ < t) { if (e2 & 1) a1 += l[e2] * T[s_]; else a0 += l[e2] * T[s_]; } }
;             }
;             T[t] = a0 + a1;
;             if (lane < 32) {
;                 Tm[(ob + t) * RL + ob + j] = (bf16_t)f2bf(T[t]);
;                 if (w == 0) T11T[j * 40 + t] = (bf16_t)f2bf(T[t]);
;             }
;         }
.LBB0_1186:
	s_or_b64 exec, exec, s[0:1]
	v_cmp_eq_u32_e64 s[0:1], 16, v9
	v_cndmask_b32_e64 v39, 0, 1.0, s[0:1]
	s_waitcnt lgkmcnt(1)
	ds_read_b128 v[174:177], v8 offset:4624
	ds_read_b128 v[178:181], v8 offset:4640
	ds_read_b128 v[182:185], v8 offset:4656
	ds_read_b128 v[186:189], v8 offset:4672
	ds_read_b128 v[190:193], v8 offset:4688
	v_fmac_f32_e32 v39, v10, v132
	v_fma_f32 v40, v7, v133, 0
	v_fmac_f32_e32 v39, v13, v134
	v_fmac_f32_e32 v40, v12, v135
	v_fmac_f32_e32 v39, v15, v136
	v_fmac_f32_e32 v40, v14, v137
	v_fmac_f32_e32 v39, v17, v138
	v_fmac_f32_e32 v40, v16, v139
	v_fmac_f32_e32 v39, v31, v140
	v_fmac_f32_e32 v40, v32, v141
	v_fmac_f32_e32 v39, v33, v142
	v_fmac_f32_e32 v40, v34, v143
	v_fmac_f32_e32 v39, v35, v144
	v_fmac_f32_e32 v40, v36, v145
	v_fmac_f32_e32 v39, v37, v146
	v_fmac_f32_e32 v40, v38, v147
	v_add_f32_e32 v39, v40, v39
	s_and_saveexec_b64 s[0:1], s[46:47]
	s_cbranch_execz .LBB0_1189
	s_movk_i32 s4, 0x1200
	v_cvt_pk_bf16_f32 v40, v39, s0
	v_mad_u64_u32 v[50:51], s[6:7], v26, s4, v[0:1]
	ds_write_b16 v50, v40 offset:2304
	s_and_b64 exec, exec, vcc
	v_add_u32_e32 v41, s54, v11
	ds_write_b16 v41, v40 offset:32
.LBB0_1189:
	s_or_b64 exec, exec, s[0:1]
	v_cmp_eq_u32_e64 s[0:1], 17, v9
	v_cndmask_b32_e64 v40, 0, 1.0, s[0:1]
	s_waitcnt lgkmcnt(1)
	ds_read_b128 v[132:135], v8 offset:4896
	ds_read_b128 v[136:139], v8 offset:4912
	ds_read_b128 v[140:143], v8 offset:4928
	ds_read_b128 v[144:147], v8 offset:4944
	ds_read_b128 v[148:151], v8 offset:4960
	v_fmac_f32_e32 v40, v10, v174
	v_fma_f32 v41, v7, v175, 0
	v_fmac_f32_e32 v40, v13, v176
	v_fmac_f32_e32 v41, v12, v177
	v_fmac_f32_e32 v40, v15, v178
	v_fmac_f32_e32 v41, v14, v179
	v_fmac_f32_e32 v40, v17, v180
	v_fmac_f32_e32 v41, v16, v181
	v_fmac_f32_e32 v40, v31, v182
	v_fmac_f32_e32 v41, v32, v183
	v_fmac_f32_e32 v40, v33, v184
	v_fmac_f32_e32 v41, v34, v185
	v_fmac_f32_e32 v40, v35, v186
	v_fmac_f32_e32 v41, v36, v187
	v_fmac_f32_e32 v40, v37, v188
	v_fmac_f32_e32 v41, v38, v189
	v_fmac_f32_e32 v40, v39, v190
	v_add_f32_e32 v40, v41, v40
	s_and_saveexec_b64 s[0:1], s[46:47]
	s_cbranch_execz .LBB0_1192
	s_movk_i32 s4, 0x1200
	v_cvt_pk_bf16_f32 v41, v40, s0
	v_mad_u64_u32 v[50:51], s[6:7], v26, s4, v[0:1]
	ds_write_b16 v50, v41 offset:2448
	s_and_b64 exec, exec, vcc
	v_add_u32_e32 v50, s54, v11
	ds_write_b16 v50, v41 offset:34
.LBB0_1192:
	s_or_b64 exec, exec, s[0:1]
	v_cmp_eq_u32_e64 s[0:1], 18, v9
	v_cndmask_b32_e64 v41, 0, 1.0, s[0:1]
	s_waitcnt lgkmcnt(1)
	ds_read_b128 v[174:177], v8 offset:5168
	ds_read_b128 v[178:181], v8 offset:5184
	ds_read_b128 v[182:185], v8 offset:5200
	ds_read_b128 v[186:189], v8 offset:5216
	ds_read_b128 v[190:193], v8 offset:5232
	v_fmac_f32_e32 v41, v10, v132
	v_fma_f32 v54, v7, v133, 0
	v_fmac_f32_e32 v41, v13, v134
	v_fmac_f32_e32 v54, v12, v135
	v_fmac_f32_e32 v41, v15, v136
	v_fmac_f32_e32 v54, v14, v137
	v_fmac_f32_e32 v41, v17, v138
	v_fmac_f32_e32 v54, v16, v139
	v_fmac_f32_e32 v41, v31, v140
	v_fmac_f32_e32 v54, v32, v141
	v_fmac_f32_e32 v41, v33, v142
	v_fmac_f32_e32 v54, v34, v143
	v_fmac_f32_e32 v41, v35, v144
	v_fmac_f32_e32 v54, v36, v145
	v_fmac_f32_e32 v41, v37, v146
	v_fmac_f32_e32 v54, v38, v147
	v_fmac_f32_e32 v41, v39, v148
	v_fmac_f32_e32 v54, v40, v149
	v_add_f32_e32 v41, v54, v41
	s_and_saveexec_b64 s[0:1], s[46:47]
	s_cbranch_execz .LBB0_1195
	s_movk_i32 s4, 0x1200
	v_cvt_pk_bf16_f32 v50, v41, s0
	v_mad_u64_u32 v[52:53], s[6:7], v26, s4, v[0:1]
	ds_write_b16 v52, v50 offset:2592
	s_and_b64 exec, exec, vcc
	v_add_u32_e32 v51, s54, v11
	ds_write_b16 v51, v50 offset:36
.LBB0_1195:
	s_or_b64 exec, exec, s[0:1]
	v_cmp_eq_u32_e64 s[0:1], 19, v9
	v_cndmask_b32_e64 v54, 0, 1.0, s[0:1]
	s_waitcnt lgkmcnt(1)
	ds_read_b128 v[132:135], v8 offset:5440
	ds_read_b128 v[136:139], v8 offset:5456
	ds_read_b128 v[140:143], v8 offset:5472
	ds_read_b128 v[144:147], v8 offset:5488
	ds_read_b128 v[148:151], v8 offset:5504
	v_fmac_f32_e32 v54, v10, v174
	v_fma_f32 v55, v7, v175, 0
	v_fmac_f32_e32 v54, v13, v176
	v_fmac_f32_e32 v55, v12, v177
	v_fmac_f32_e32 v54, v15, v178
	v_fmac_f32_e32 v55, v14, v179
	v_fmac_f32_e32 v54, v17, v180
	v_fmac_f32_e32 v55, v16, v181
	v_fmac_f32_e32 v54, v31, v182
	v_fmac_f32_e32 v55, v32, v183
	v_fmac_f32_e32 v54, v33, v184
	v_fmac_f32_e32 v55, v34, v185
	v_fmac_f32_e32 v54, v35, v186
	v_fmac_f32_e32 v55, v36, v187
	v_fmac_f32_e32 v54, v37, v188
	v_fmac_f32_e32 v55, v38, v189
	v_fmac_f32_e32 v54, v39, v190
	v_fmac_f32_e32 v55, v40, v191
	v_fmac_f32_e32 v54, v41, v192
	v_add_f32_e32 v50, v55, v54
	s_and_saveexec_b64 s[0:1], s[46:47]
	s_cbranch_execz .LBB0_1198
	s_movk_i32 s4, 0x1200
	v_cvt_pk_bf16_f32 v51, v50, s0
	v_mad_u64_u32 v[52:53], s[6:7], v26, s4, v[0:1]
	ds_write_b16 v52, v51 offset:2736
	s_and_b64 exec, exec, vcc
	v_add_u32_e32 v52, s54, v11
	ds_write_b16 v52, v51 offset:38
.LBB0_1198:
	s_or_b64 exec, exec, s[0:1]
	v_cmp_eq_u32_e64 s[0:1], 20, v9
	v_cndmask_b32_e64 v51, 0, 1.0, s[0:1]
	s_waitcnt lgkmcnt(1)
	ds_read_b128 v[174:177], v8 offset:5712
	ds_read_b128 v[178:181], v8 offset:5728
	ds_read_b128 v[182:185], v8 offset:5744
	ds_read_b128 v[186:189], v8 offset:5760
	ds_read_b128 v[190:193], v8 offset:5776
	ds_read_b128 v[194:197], v8 offset:5792
	v_fmac_f32_e32 v51, v10, v132
	v_fma_f32 v57, v7, v133, 0
	v_fmac_f32_e32 v51, v13, v134
	v_fmac_f32_e32 v57, v12, v135
	v_fmac_f32_e32 v51, v15, v136
	v_fmac_f32_e32 v57, v14, v137
	v_fmac_f32_e32 v51, v17, v138
	v_fmac_f32_e32 v57, v16, v139
	v_fmac_f32_e32 v51, v31, v140
	v_fmac_f32_e32 v57, v32, v141
	v_fmac_f32_e32 v51, v33, v142
	v_fmac_f32_e32 v57, v34, v143
	v_fmac_f32_e32 v51, v35, v144
	v_fmac_f32_e32 v57, v36, v145
	v_fmac_f32_e32 v51, v37, v146
	v_fmac_f32_e32 v57, v38, v147
	v_fmac_f32_e32 v51, v39, v148
	v_fmac_f32_e32 v57, v40, v149
	v_fmac_f32_e32 v51, v41, v150
	v_fmac_f32_e32 v57, v50, v151
	v_add_f32_e32 v51, v57, v51
	s_and_saveexec_b64 s[0:1], s[46:47]
	s_cbranch_execz .LBB0_1201
	s_movk_i32 s4, 0x1200
	v_cvt_pk_bf16_f32 v52, v51, s0
	v_mad_u64_u32 v[54:55], s[6:7], v26, s4, v[0:1]
	ds_write_b16 v54, v52 offset:2880
	s_and_b64 exec, exec, vcc
	v_add_u32_e32 v53, s54, v11
	ds_write_b16 v53, v52 offset:40
; #define LAS __attribute__((address_space(3)))
; __device__ __forceinline__ unsigned f2bf(float f) { return (unsigned)__builtin_bit_cast(unsigned short, (__bf16)f); }
; __device__ __forceinline__ void rwkv_pre(LAS unsigned char* lds, const MixBufs& B, bf16_t* rq, int L, int u, int unext, RwRaw& R) {
;     ...
; #pragma unroll
;         for (int t = 0; t < 32; ++t) {
;             float a0 = (t == j) ? 1.f : 0.f, a1 = 0.f;
; #pragma unroll
;             for (int s4 = 0; s4 < (t + 3) / 4; ++s4) {
;                 const f32x4 l = *(const LAS f32x4*)(Lfz + t * 68 + s4 * 4);
; #pragma unroll
;                 for (int e2 = 0; e2 < 4; ++e2) { const int s_ = s4 * 4 + e2; if (s_ < t) { if (e2 & 1) a1 += l[e2] * T[s_]; else a0 += l[e2] * T[s_]; } }
;             }
;             T[t] = a0 + a1;
;             if (lane < 32) {
;                 Tm[(ob + t) * RL + ob + j] = (bf16_t)f2bf(T[t]);
;                 if (w == 0) T11T[j * 40 + t] = (bf16_t)f2bf(T[t]);
;             }
;         }
.LBB0_1201:
	s_or_b64 exec, exec, s[0:1]
	v_cmp_eq_u32_e64 s[0:1], 21, v9
	v_cndmask_b32_e64 v57, 0, 1.0, s[0:1]
	s_waitcnt lgkmcnt(1)
	ds_read_b128 v[132:135], v8 offset:5984
	ds_read_b128 v[136:139], v8 offset:6000
	ds_read_b128 v[140:143], v8 offset:6016
	ds_read_b128 v[144:147], v8 offset:6032
	ds_read_b128 v[148:151], v8 offset:6048
	ds_read_b128 v[166:169], v8 offset:6064
	v_fmac_f32_e32 v57, v10, v174
	v_fma_f32 v67, v7, v175, 0
	v_fmac_f32_e32 v57, v13, v176
	v_fmac_f32_e32 v67, v12, v177
	v_fmac_f32_e32 v57, v15, v178
	v_fmac_f32_e32 v67, v14, v179
	v_fmac_f32_e32 v57, v17, v180
	v_fmac_f32_e32 v67, v16, v181
	v_fmac_f32_e32 v57, v31, v182
	v_fmac_f32_e32 v67, v32, v183
	v_fmac_f32_e32 v57, v33, v184
	v_fmac_f32_e32 v67, v34, v185
	v_fmac_f32_e32 v57, v35, v186
	v_fmac_f32_e32 v67, v36, v187
	v_fmac_f32_e32 v57, v37, v188
	v_fmac_f32_e32 v67, v38, v189
	v_fmac_f32_e32 v57, v39, v190
	v_fmac_f32_e32 v67, v40, v191
	v_fmac_f32_e32 v57, v41, v192
	v_fmac_f32_e32 v67, v50, v193
	v_fmac_f32_e32 v57, v51, v194
	v_add_f32_e32 v52, v67, v57
	s_and_saveexec_b64 s[0:1], s[46:47]
	s_cbranch_execz .LBB0_1204
	s_movk_i32 s4, 0x1200
	v_cvt_pk_bf16_f32 v53, v52, s0
	v_mad_u64_u32 v[54:55], s[6:7], v26, s4, v[0:1]
	ds_write_b16 v54, v53 offset:3024
	s_and_b64 exec, exec, vcc
	v_add_u32_e32 v54, s54, v11
	ds_write_b16 v54, v53 offset:42
.LBB0_1204:
	s_or_b64 exec, exec, s[0:1]
	v_cmp_eq_u32_e64 s[0:1], 22, v9
	v_cndmask_b32_e64 v53, 0, 1.0, s[0:1]
	s_waitcnt lgkmcnt(1)
	ds_read_b128 v[174:177], v8 offset:6256
	ds_read_b128 v[178:181], v8 offset:6272
	ds_read_b128 v[182:185], v8 offset:6288
	ds_read_b128 v[186:189], v8 offset:6304
	ds_read_b128 v[190:193], v8 offset:6320
	ds_read_b128 v[194:197], v8 offset:6336
	v_fmac_f32_e32 v53, v10, v132
	v_fma_f32 v54, v7, v133, 0
	v_fmac_f32_e32 v53, v13, v134
	v_fmac_f32_e32 v54, v12, v135
	v_fmac_f32_e32 v53, v15, v136
	v_fmac_f32_e32 v54, v14, v137
	v_fmac_f32_e32 v53, v17, v138
	v_fmac_f32_e32 v54, v16, v139
	v_fmac_f32_e32 v53, v31, v140
	v_fmac_f32_e32 v54, v32, v141
	v_fmac_f32_e32 v53, v33, v142
	v_fmac_f32_e32 v54, v34, v143
	v_fmac_f32_e32 v53, v35, v144
	v_fmac_f32_e32 v54, v36, v145
	v_fmac_f32_e32 v53, v37, v146
	v_fmac_f32_e32 v54, v38, v147
	v_fmac_f32_e32 v53, v39, v148
	v_fmac_f32_e32 v54, v40, v149
	v_fmac_f32_e32 v53, v41, v150
	v_fmac_f32_e32 v54, v50, v151
	v_fmac_f32_e32 v53, v51, v166
	v_fmac_f32_e32 v54, v52, v167
	v_add_f32_e32 v53, v54, v53
	s_and_saveexec_b64 s[0:1], s[46:47]
	s_cbranch_execz .LBB0_1207
	s_movk_i32 s4, 0x1200
	v_cvt_pk_bf16_f32 v54, v53, s0
	v_mad_u64_u32 v[68:69], s[6:7], v26, s4, v[0:1]
	ds_write_b16 v68, v54 offset:3168
	s_and_b64 exec, exec, vcc
	v_add_u32_e32 v55, s54, v11
	ds_write_b16 v55, v54 offset:44
.LBB0_1207:
	s_or_b64 exec, exec, s[0:1]
	v_cmp_eq_u32_e64 s[0:1], 23, v9
	v_cndmask_b32_e64 v54, 0, 1.0, s[0:1]
	s_waitcnt lgkmcnt(1)
	ds_read_b128 v[132:135], v8 offset:6528
	ds_read_b128 v[136:139], v8 offset:6544
	ds_read_b128 v[140:143], v8 offset:6560
	ds_read_b128 v[144:147], v8 offset:6576
	ds_read_b128 v[148:151], v8 offset:6592
	ds_read_b128 v[166:169], v8 offset:6608
	v_fmac_f32_e32 v54, v10, v174
	v_fma_f32 v55, v7, v175, 0
	v_fmac_f32_e32 v54, v13, v176
	v_fmac_f32_e32 v55, v12, v177
	v_fmac_f32_e32 v54, v15, v178
	v_fmac_f32_e32 v55, v14, v179
	v_fmac_f32_e32 v54, v17, v180
	v_fmac_f32_e32 v55, v16, v181
	v_fmac_f32_e32 v54, v31, v182
	v_fmac_f32_e32 v55, v32, v183
	v_fmac_f32_e32 v54, v33, v184
	v_fmac_f32_e32 v55, v34, v185
	v_fmac_f32_e32 v54, v35, v186
	v_fmac_f32_e32 v55, v36, v187
	v_fmac_f32_e32 v54, v37, v188
	v_fmac_f32_e32 v55, v38, v189
	v_fmac_f32_e32 v54, v39, v190
	v_fmac_f32_e32 v55, v40, v191
	v_fmac_f32_e32 v54, v41, v192
	v_fmac_f32_e32 v55, v50, v193
	v_fmac_f32_e32 v54, v51, v194
	v_fmac_f32_e32 v55, v52, v195
	v_fmac_f32_e32 v54, v53, v196
	v_add_f32_e32 v54, v55, v54
	s_and_saveexec_b64 s[0:1], s[46:47]
	s_cbranch_execz .LBB0_1210
	s_movk_i32 s4, 0x1200
	v_cvt_pk_bf16_f32 v55, v54, s0
	v_mad_u64_u32 v[68:69], s[6:7], v26, s4, v[0:1]
	ds_write_b16 v68, v55 offset:3312
	s_and_b64 exec, exec, vcc
	v_add_u32_e32 v57, s54, v11
	ds_write_b16 v57, v55 offset:46
.LBB0_1210:
	s_or_b64 exec, exec, s[0:1]
	v_cmp_eq_u32_e64 s[0:1], 24, v9
	v_cndmask_b32_e64 v55, 0, 1.0, s[0:1]
	s_waitcnt lgkmcnt(1)
	ds_read_b128 v[174:177], v8 offset:6800
	ds_read_b128 v[178:181], v8 offset:6816
	ds_read_b128 v[182:185], v8 offset:6832
	ds_read_b128 v[186:189], v8 offset:6848
	ds_read_b128 v[190:193], v8 offset:6864
	ds_read_b128 v[194:197], v8 offset:6880
	ds_read_b128 v[198:201], v8 offset:6896
	v_fmac_f32_e32 v55, v10, v132
	v_fma_f32 v57, v7, v133, 0
	v_fmac_f32_e32 v55, v13, v134
	v_fmac_f32_e32 v57, v12, v135
	v_fmac_f32_e32 v55, v15, v136
	v_fmac_f32_e32 v57, v14, v137
	v_fmac_f32_e32 v55, v17, v138
	v_fmac_f32_e32 v57, v16, v139
	v_fmac_f32_e32 v55, v31, v140
	v_fmac_f32_e32 v57, v32, v141
	v_fmac_f32_e32 v55, v33, v142
	v_fmac_f32_e32 v57, v34, v143
	v_fmac_f32_e32 v55, v35, v144
	v_fmac_f32_e32 v57, v36, v145
	v_fmac_f32_e32 v55, v37, v146
	v_fmac_f32_e32 v57, v38, v147
	v_fmac_f32_e32 v55, v39, v148
	v_fmac_f32_e32 v57, v40, v149
	v_fmac_f32_e32 v55, v41, v150
	v_fmac_f32_e32 v57, v50, v151
	v_fmac_f32_e32 v55, v51, v166
	v_fmac_f32_e32 v57, v52, v167
	v_fmac_f32_e32 v55, v53, v168
	v_fmac_f32_e32 v57, v54, v169
	v_add_f32_e32 v55, v57, v55
	s_and_saveexec_b64 s[0:1], s[46:47]
	s_cbranch_execz .LBB0_1213
	s_movk_i32 s4, 0x1200
	v_cvt_pk_bf16_f32 v57, v55, s0
	v_mad_u64_u32 v[68:69], s[6:7], v26, s4, v[0:1]
	ds_write_b16 v68, v57 offset:3456
	s_and_b64 exec, exec, vcc
	v_add_u32_e32 v67, s54, v11
	ds_write_b16 v67, v57 offset:48
; #define LAS __attribute__((address_space(3)))
; __device__ __forceinline__ unsigned f2bf(float f) { return (unsigned)__builtin_bit_cast(unsigned short, (__bf16)f); }
; __device__ __forceinline__ void rwkv_pre(LAS unsigned char* lds, const MixBufs& B, bf16_t* rq, int L, int u, int unext, RwRaw& R) {
;     ...
; #pragma unroll
;         for (int t = 0; t < 32; ++t) {
;             float a0 = (t == j) ? 1.f : 0.f, a1 = 0.f;
; #pragma unroll
;             for (int s4 = 0; s4 < (t + 3) / 4; ++s4) {
;                 const f32x4 l = *(const LAS f32x4*)(Lfz + t * 68 + s4 * 4);
; #pragma unroll
;                 for (int e2 = 0; e2 < 4; ++e2) { const int s_ = s4 * 4 + e2; if (s_ < t) { if (e2 & 1) a1 += l[e2] * T[s_]; else a0 += l[e2] * T[s_]; } }
;             }
;             T[t] = a0 + a1;
;             if (lane < 32) {
;                 Tm[(ob + t) * RL + ob + j] = (bf16_t)f2bf(T[t]);
;                 if (w == 0) T11T[j * 40 + t] = (bf16_t)f2bf(T[t]);
;             }
;         }
.LBB0_1213:
	s_or_b64 exec, exec, s[0:1]
	v_cmp_eq_u32_e64 s[0:1], 25, v9
	v_cndmask_b32_e64 v57, 0, 1.0, s[0:1]
	s_waitcnt lgkmcnt(1)
	ds_read_b128 v[132:135], v8 offset:7072
	ds_read_b128 v[136:139], v8 offset:7088
	ds_read_b128 v[140:143], v8 offset:7104
	ds_read_b128 v[144:147], v8 offset:7120
	ds_read_b128 v[148:151], v8 offset:7136
	ds_read_b128 v[166:169], v8 offset:7152
	ds_read_b128 v[170:173], v8 offset:7168
	v_fmac_f32_e32 v57, v10, v174
	v_fma_f32 v67, v7, v175, 0
	v_fmac_f32_e32 v57, v13, v176
	v_fmac_f32_e32 v67, v12, v177
	v_fmac_f32_e32 v57, v15, v178
	v_fmac_f32_e32 v67, v14, v179
	v_fmac_f32_e32 v57, v17, v180
	v_fmac_f32_e32 v67, v16, v181
	v_fmac_f32_e32 v57, v31, v182
	v_fmac_f32_e32 v67, v32, v183
	v_fmac_f32_e32 v57, v33, v184
	v_fmac_f32_e32 v67, v34, v185
	v_fmac_f32_e32 v57, v35, v186
	v_fmac_f32_e32 v67, v36, v187
	v_fmac_f32_e32 v57, v37, v188
	v_fmac_f32_e32 v67, v38, v189
	v_fmac_f32_e32 v57, v39, v190
	v_fmac_f32_e32 v67, v40, v191
	v_fmac_f32_e32 v57, v41, v192
	v_fmac_f32_e32 v67, v50, v193
	v_fmac_f32_e32 v57, v51, v194
	v_fmac_f32_e32 v67, v52, v195
	v_fmac_f32_e32 v57, v53, v196
	v_fmac_f32_e32 v67, v54, v197
	v_fmac_f32_e32 v57, v55, v198
	v_add_f32_e32 v57, v67, v57
	s_and_saveexec_b64 s[0:1], s[46:47]
	s_cbranch_execz .LBB0_1216
	s_movk_i32 s4, 0x1200
	v_cvt_pk_bf16_f32 v67, v57, s0
	v_mad_u64_u32 v[68:69], s[6:7], v26, s4, v[0:1]
	ds_write_b16 v68, v67 offset:3600
	s_and_b64 exec, exec, vcc
	v_add_u32_e32 v68, s54, v11
	ds_write_b16 v68, v67 offset:50
.LBB0_1216:
	s_or_b64 exec, exec, s[0:1]
	v_cmp_eq_u32_e64 s[0:1], 26, v9
	v_cndmask_b32_e64 v67, 0, 1.0, s[0:1]
	s_waitcnt lgkmcnt(1)
	ds_read_b128 v[174:177], v8 offset:7344
	ds_read_b128 v[178:181], v8 offset:7360
	ds_read_b128 v[182:185], v8 offset:7376
	ds_read_b128 v[186:189], v8 offset:7392
	ds_read_b128 v[190:193], v8 offset:7408
	ds_read_b128 v[194:197], v8 offset:7424
	ds_read_b128 v[198:201], v8 offset:7440
	v_fmac_f32_e32 v67, v10, v132
	v_fma_f32 v84, v7, v133, 0
	v_fmac_f32_e32 v67, v13, v134
	v_fmac_f32_e32 v84, v12, v135
	v_fmac_f32_e32 v67, v15, v136
	v_fmac_f32_e32 v84, v14, v137
	v_fmac_f32_e32 v67, v17, v138
	v_fmac_f32_e32 v84, v16, v139
	v_fmac_f32_e32 v67, v31, v140
	v_fmac_f32_e32 v84, v32, v141
	v_fmac_f32_e32 v67, v33, v142
	v_fmac_f32_e32 v84, v34, v143
	v_fmac_f32_e32 v67, v35, v144
	v_fmac_f32_e32 v84, v36, v145
	v_fmac_f32_e32 v67, v37, v146
	v_fmac_f32_e32 v84, v38, v147
	v_fmac_f32_e32 v67, v39, v148
	v_fmac_f32_e32 v84, v40, v149
	v_fmac_f32_e32 v67, v41, v150
	v_fmac_f32_e32 v84, v50, v151
	v_fmac_f32_e32 v67, v51, v166
	v_fmac_f32_e32 v84, v52, v167
	v_fmac_f32_e32 v67, v53, v168
	v_fmac_f32_e32 v84, v54, v169
	v_fmac_f32_e32 v67, v55, v170
	v_fmac_f32_e32 v84, v57, v171
	v_add_f32_e32 v67, v84, v67
	s_and_saveexec_b64 s[0:1], s[46:47]
	s_cbranch_execz .LBB0_1219
	s_movk_i32 s4, 0x1200
	v_cvt_pk_bf16_f32 v68, v67, s0
	v_mad_u64_u32 v[70:71], s[6:7], v26, s4, v[0:1]
	ds_write_b16 v70, v68 offset:3744
	s_and_b64 exec, exec, vcc
	v_add_u32_e32 v69, s54, v11
	ds_write_b16 v69, v68 offset:52
.LBB0_1219:
	s_or_b64 exec, exec, s[0:1]
	v_cmp_eq_u32_e64 s[0:1], 27, v9
	v_cndmask_b32_e64 v84, 0, 1.0, s[0:1]
	s_waitcnt lgkmcnt(1)
	ds_read_b128 v[132:135], v8 offset:7616
	ds_read_b128 v[136:139], v8 offset:7632
	ds_read_b128 v[140:143], v8 offset:7648
	ds_read_b128 v[144:147], v8 offset:7664
	ds_read_b128 v[148:151], v8 offset:7680
	ds_read_b128 v[166:169], v8 offset:7696
	ds_read_b128 v[170:173], v8 offset:7712
	v_fmac_f32_e32 v84, v10, v174
	v_fma_f32 v85, v7, v175, 0
	v_fmac_f32_e32 v84, v13, v176
	v_fmac_f32_e32 v85, v12, v177
	v_fmac_f32_e32 v84, v15, v178
	v_fmac_f32_e32 v85, v14, v179
	v_fmac_f32_e32 v84, v17, v180
	v_fmac_f32_e32 v85, v16, v181
	v_fmac_f32_e32 v84, v31, v182
	v_fmac_f32_e32 v85, v32, v183
	v_fmac_f32_e32 v84, v33, v184
	v_fmac_f32_e32 v85, v34, v185
	v_fmac_f32_e32 v84, v35, v186
	v_fmac_f32_e32 v85, v36, v187
	v_fmac_f32_e32 v84, v37, v188
	v_fmac_f32_e32 v85, v38, v189
	v_fmac_f32_e32 v84, v39, v190
	v_fmac_f32_e32 v85, v40, v191
	v_fmac_f32_e32 v84, v41, v192
	v_fmac_f32_e32 v85, v50, v193
	v_fmac_f32_e32 v84, v51, v194
	v_fmac_f32_e32 v85, v52, v195
	v_fmac_f32_e32 v84, v53, v196
	v_fmac_f32_e32 v85, v54, v197
	v_fmac_f32_e32 v84, v55, v198
	v_fmac_f32_e32 v85, v57, v199
	v_fmac_f32_e32 v84, v67, v200
	v_add_f32_e32 v68, v85, v84
	s_and_saveexec_b64 s[0:1], s[46:47]
	s_cbranch_execz .LBB0_1222
	s_movk_i32 s4, 0x1200
	v_cvt_pk_bf16_f32 v69, v68, s0
	v_mad_u64_u32 v[70:71], s[6:7], v26, s4, v[0:1]
	ds_write_b16 v70, v69 offset:3888
	s_and_b64 exec, exec, vcc
	v_add_u32_e32 v70, s54, v11
	ds_write_b16 v70, v69 offset:54
.LBB0_1222:
	s_or_b64 exec, exec, s[0:1]
	v_cmp_eq_u32_e64 s[0:1], 28, v9
	v_cndmask_b32_e64 v69, 0, 1.0, s[0:1]
	s_waitcnt lgkmcnt(1)
	v_fmac_f32_e32 v69, v10, v132
	v_fma_f32 v86, v7, v133, 0
	v_fmac_f32_e32 v69, v13, v134
	v_fmac_f32_e32 v86, v12, v135
	v_fmac_f32_e32 v69, v15, v136
	v_fmac_f32_e32 v86, v14, v137
	v_fmac_f32_e32 v69, v17, v138
	v_fmac_f32_e32 v86, v16, v139
	v_fmac_f32_e32 v69, v31, v140
	v_fmac_f32_e32 v86, v32, v141
	v_fmac_f32_e32 v69, v33, v142
	v_fmac_f32_e32 v86, v34, v143
	v_fmac_f32_e32 v69, v35, v144
	v_fmac_f32_e32 v86, v36, v145
	v_fmac_f32_e32 v69, v37, v146
	v_fmac_f32_e32 v86, v38, v147
	v_fmac_f32_e32 v69, v39, v148
	v_fmac_f32_e32 v86, v40, v149
	v_fmac_f32_e32 v69, v41, v150
	v_fmac_f32_e32 v86, v50, v151
	v_fmac_f32_e32 v69, v51, v166
	v_fmac_f32_e32 v86, v52, v167
	v_fmac_f32_e32 v69, v53, v168
	v_fmac_f32_e32 v86, v54, v169
	v_fmac_f32_e32 v69, v55, v170
	v_fmac_f32_e32 v86, v57, v171
	v_fmac_f32_e32 v69, v67, v172
	v_fmac_f32_e32 v86, v68, v173
	v_add_f32_e32 v69, v86, v69
	s_and_saveexec_b64 s[0:1], s[46:47]
	s_cbranch_execz .LBB0_1225
	s_movk_i32 s4, 0x1200
	v_cvt_pk_bf16_f32 v70, v69, s0
	v_mad_u64_u32 v[72:73], s[6:7], v26, s4, v[0:1]
	ds_write_b16 v72, v70 offset:4032
	s_and_b64 exec, exec, vcc
	v_add_u32_e32 v71, s54, v11
	ds_write_b16 v71, v70 offset:56
